# ConvFFN middle phase (3x3 depthwise conv + exact-erf gelu * u) rewritten by hand: rotating 3-column window, packed f32 FMAs (no operand shuffling moves), next column loads prefetched, saddr-mode addre
# speedup vs baseline: 1.0475x; 1.0273x over previous
; __device__ __forceinline__ void phase_conv(KP p, int l, int tid) {
;     ...
;   const float* cw = p->in[29] + (size_t)l * 9 * DFF; const float* cbias = p->in[30] + (size_t)l * DFF;
;   constexpr int RB = 2, CB = 2;
;   const int total = (256 / RB) * 4 * 1408;
; #pragma unroll 1
;   for (int it = blockIdx.x * NTH + tid; it < total; it += gridDim.x * NTH) {
;     const int cc = it % 1408; const int rs = it / 1408; const int sgm = rs & 3, r0 = (rs >> 2) * RB; const int c0 = cc * 4;
;     f32x4 w[9];
; #pragma unroll
;     for (int k = 0; k < 9; ++k) w[k] = *(const f32x4*)(cw + k * DFF + c0);
;     const f32x4 bsv = *(const f32x4*)(cbias + c0);
;     const bf16_t* rowp[RB + 2]; bool rv[RB + 2];
; #pragma unroll
;     for (int di = 0; di < RB + 2; ++di) { const int rr = r0 + di - 1; rv[di] = (rr >= 0) && (rr < 256); const int rc = rr < 0 ? 0 : (rr > 255 ? 255 : rr); rowp[di] = A + (size_t)(rc * 64) * DFF + c0; }
;     float win[3][RB + 2][4];
;     const int j0 = sgm * 16;
;     {
;       u32x2 ra[2][RB + 2];
; #pragma unroll
;       for (int s = 0; s < 2; ++s) { const int col = j0 - 1 + s; const int cl = col < 0 ? 0 : col;
; #pragma unroll
;         for (int di = 0; di < RB + 2; ++di) ra[s][di] = *(const u32x2*)(rowp[di] + (size_t)cl * DFF); }
; #pragma unroll
;       for (int s = 0; s < 2; ++s) { const int col = j0 - 1 + s;
; #pragma unroll
;         for (int di = 0; di < RB + 2; ++di) { const bool ok = rv[di] && (col >= 0); unpack4(ra[s][di], win[s][di]);
; #pragma unroll
;           for (int k = 0; k < 4; ++k) win[s][di][k] = ok ? win[s][di][k] : 0.f; } }
.LBB0_45:
	s_mov_b64 s[0:1], 0
	v_writelane_b32 v254, s0, 11
	s_mov_b64 s[2:3], 0
	s_and_b64 vcc, exec, s[8:9]
	v_writelane_b32 v254, s1, 12
	s_cbranch_vccz .LBB0_56
	v_readlane_b32 s0, v254, 9
	v_readlane_b32 s1, v254, 10
	s_waitcnt lgkmcnt(0)
	s_load_dwordx2 s[18:19], s[0:1], 0x110
	v_readlane_b32 s0, v253, 4
	s_nop 1
	v_add_u32_e32 v142, s0, v146
	s_mov_b32 s0, 0xb0000
	v_cmp_gt_i32_e32 vcc, s0, v142
	s_and_saveexec_b64 s[4:5], vcc
	s_cbranch_execz .LBB0_51
	v_readlane_b32 s0, v254, 9
	v_readlane_b32 s1, v254, 10
	s_load_dwordx4 s[8:11], s[0:1], 0xe8
	s_cmp_eq_u32 s84, 16
	s_cselect_b32 s0, 0x31800, 0
	s_cselect_b32 s1, 0x5800, 0
	s_mov_b64 s[28:29], 0
	s_waitcnt lgkmcnt(0)
	s_add_u32 s20, s8, s0
	s_addc_u32 s21, s9, 0
	s_add_u32 s22, s10, s1
	s_addc_u32 s23, s11, 0
	s_add_u32 s24, s18, 0xac73c00
	s_addc_u32 s25, s19, 0
	s_add_u32 s6, s18, 0xad21000
	s_addc_u32 s7, s19, 0
	s_add_u32 s8, s18, 0x15d21000
	s_addc_u32 s9, s19, 0
	s_add_u32 s10, s18, 0x20d21000
	s_addc_u32 s11, s19, 0
	v_mov_b32_e32 v184, 0x3e6d3388
	v_mov_b32_e32 v185, 0x3e6d3388
	v_mov_b32_e32 v186, 0x3f800000
	v_mov_b32_e32 v187, 0x3f800000
	v_mov_b32_e32 v188, 0x3f07dc22
	v_mov_b32_e32 v189, 0x3f07dc22
	v_mov_b32_e32 v190, 0xbf3a00e3
	v_mov_b32_e32 v191, 0xbf3a00e3
	v_mov_b32_e32 v192, 0x3f35f0e3
	v_mov_b32_e32 v193, 0x3f35f0e3
	v_mov_b32_e32 v194, 0xbe11a98e
	v_mov_b32_e32 v195, 0xbe11a98e
	v_mov_b32_e32 v196, 0x3e027906
	v_mov_b32_e32 v197, 0x3e027906
	v_mov_b32_e32 v198, 0xbf38aa3b
	v_mov_b32_e32 v199, 0xbf38aa3b
.Lcv_item:
	s_mov_b32 s0, 0x2e8ba2e9
	v_mul_hi_i32 v220, v142, s0
	v_lshrrev_b32_e32 v221, 31, v220
	v_ashrrev_i32_e32 v220, 8, v220
	v_add_u32_e32 v220, v220, v221
	v_mul_u32_u24_e32 v221, 0x580, v220
	v_sub_u32_e32 v221, v142, v221
	v_lshlrev_b32_e32 v222, 4, v221
	v_lshlrev_b32_e32 v221, 3, v221
	global_load_dwordx4 v[0:3], v222, s[20:21]
	v_add_u32_e32 v223, 0x5800, v222
	global_load_dwordx4 v[4:7], v223, s[20:21]
	v_add_u32_e32 v223, 0xb000, v222
	global_load_dwordx4 v[8:11], v223, s[20:21]
	v_add_u32_e32 v223, 0x10800, v222
	global_load_dwordx4 v[12:15], v223, s[20:21]
	v_add_u32_e32 v223, 0x16000, v222
	global_load_dwordx4 v[16:19], v223, s[20:21]
	v_add_u32_e32 v223, 0x1b800, v222
	global_load_dwordx4 v[20:23], v223, s[20:21]
	v_add_u32_e32 v223, 0x21000, v222
	global_load_dwordx4 v[24:27], v223, s[20:21]
	v_add_u32_e32 v223, 0x26800, v222
	global_load_dwordx4 v[28:31], v223, s[20:21]
	v_add_u32_e32 v223, 0x2c000, v222
	global_load_dwordx4 v[32:35], v223, s[20:21]
	global_load_dwordx4 v[36:39], v222, s[22:23]
	v_and_b32_e32 v222, 3, v220
	v_lshrrev_b32_e32 v220, 1, v220
	v_and_b32_e32 v220, -2, v220
	v_cmp_lt_u32_e32 vcc, 0, v220
	s_nop 1
	v_cndmask_b32_e32 v200, 0, v186, vcc
	v_mov_b32_e32 v201, v200
	v_cmp_gt_u32_e32 vcc, 0xfe, v220
	s_nop 1
	v_cndmask_b32_e32 v202, 0, v186, vcc
	v_mov_b32_e32 v203, v202
	v_sub_u32_e64 v223, v220, 1 clamp
	v_mul_u32_u24_e32 v206, 0xb0000, v223
	v_mul_u32_u24_e32 v207, 0xb0000, v220
	v_add_u32_e32 v208, 0xb0000, v207
	v_add_u32_e32 v223, 2, v220
	v_min_u32_e32 v223, 0xff, v223
	v_mul_u32_u24_e32 v209, 0xb0000, v223
	v_add_u32_e32 v206, v206, v221
	v_add_u32_e32 v207, v207, v221
	v_add_u32_e32 v208, v208, v221
	v_add_u32_e32 v209, v209, v221
	v_lshlrev_b32_e32 v222, 4, v222
	v_mul_u32_u24_e32 v210, 0x2c00, v222
	v_cmp_lt_u32_e32 vcc, 0, v222
	s_nop 1
	v_cndmask_b32_e32 v204, 0, v186, vcc
	v_mov_b32_e32 v205, v204
	v_sub_u32_e64 v223, v222, 1 clamp
	v_mul_u32_u24_e32 v223, 0x2c00, v223
	v_add_u32_e32 v212, v206, v223
	global_load_dwordx2 v[96:97], v212, s[6:7]
	v_add_u32_e32 v213, v207, v223
	global_load_dwordx2 v[98:99], v213, s[6:7]
	v_add_u32_e32 v214, v208, v223
	global_load_dwordx2 v[100:101], v214, s[6:7]
	v_add_u32_e32 v215, v209, v223
	global_load_dwordx2 v[102:103], v215, s[6:7]
	v_add_u32_e32 v212, v206, v210
	global_load_dwordx2 v[88:89], v212, s[6:7]
	v_add_u32_e32 v213, v207, v210
	global_load_dwordx2 v[90:91], v213, s[6:7]
	v_add_u32_e32 v214, v208, v210
	global_load_dwordx2 v[92:93], v214, s[6:7]
	v_add_u32_e32 v215, v209, v210
	global_load_dwordx2 v[94:95], v215, s[6:7]
	s_waitcnt vmcnt(0)
	v_lshlrev_b32_e32 v40, 16, v96
	v_and_b32_e32 v41, 0xffff0000, v96
	v_lshlrev_b32_e32 v42, 16, v97
	v_and_b32_e32 v43, 0xffff0000, v97
	v_lshlrev_b32_e32 v44, 16, v98
	v_and_b32_e32 v45, 0xffff0000, v98
	v_lshlrev_b32_e32 v46, 16, v99
	v_and_b32_e32 v47, 0xffff0000, v99
	v_lshlrev_b32_e32 v48, 16, v100
	v_and_b32_e32 v49, 0xffff0000, v100
	v_lshlrev_b32_e32 v50, 16, v101
	v_and_b32_e32 v51, 0xffff0000, v101
	v_lshlrev_b32_e32 v52, 16, v102
	v_and_b32_e32 v53, 0xffff0000, v102
	v_lshlrev_b32_e32 v54, 16, v103
	v_and_b32_e32 v55, 0xffff0000, v103
	v_pk_mul_f32 v[40:41], v[40:41], v[200:201]
	v_pk_mul_f32 v[42:43], v[42:43], v[200:201]
	v_pk_mul_f32 v[52:53], v[52:53], v[202:203]
	v_pk_mul_f32 v[54:55], v[54:55], v[202:203]
	v_pk_mul_f32 v[40:41], v[40:41], v[204:205]
	v_pk_mul_f32 v[42:43], v[42:43], v[204:205]
	v_pk_mul_f32 v[44:45], v[44:45], v[204:205]
	v_pk_mul_f32 v[46:47], v[46:47], v[204:205]
	v_pk_mul_f32 v[48:49], v[48:49], v[204:205]
	v_pk_mul_f32 v[50:51], v[50:51], v[204:205]
	v_pk_mul_f32 v[52:53], v[52:53], v[204:205]
	v_pk_mul_f32 v[54:55], v[54:55], v[204:205]
	v_lshlrev_b32_e32 v56, 16, v88
	v_and_b32_e32 v57, 0xffff0000, v88
	v_lshlrev_b32_e32 v58, 16, v89
	v_and_b32_e32 v59, 0xffff0000, v89
	v_lshlrev_b32_e32 v60, 16, v90
	v_and_b32_e32 v61, 0xffff0000, v90
	v_lshlrev_b32_e32 v62, 16, v91
	v_and_b32_e32 v63, 0xffff0000, v91
	v_lshlrev_b32_e32 v64, 16, v92
	v_and_b32_e32 v65, 0xffff0000, v92
	v_lshlrev_b32_e32 v66, 16, v93
	v_and_b32_e32 v67, 0xffff0000, v93
	v_lshlrev_b32_e32 v68, 16, v94
; __device__ __forceinline__ unsigned cvt_pk_bf16(float lo, float hi) { unsigned r; asm volatile("v_cvt_pk_bf16_f32 %0, %1, %2" : "=v"(r) : "v"(lo), "v"(hi)); return r; }
; __device__ __forceinline__ void phase_conv(KP p, int l, int tid) {
;     ...
;     for (int jb = j0; jb < j0 + 16; jb += CB) {
;       u32x2 an[CB][RB + 2], ur[CB][RB];
; #pragma unroll
;       for (int q = 0; q < CB; ++q) { const int col = jb + q + 1; const int cl = col > 63 ? 63 : col;
; #pragma unroll
;         for (int di = 0; di < RB + 2; ++di) an[q][di] = *(const u32x2*)(rowp[di] + (size_t)cl * DFF);
; #pragma unroll
;         for (int rr = 0; rr < RB; ++rr) ur[q][rr] = *(const u32x2*)(U + (size_t)((r0 + rr) * 64 + jb + q) * DFF + c0); }
;       __builtin_amdgcn_sched_barrier(0);
; #pragma unroll
;       for (int q = 0; q < CB; ++q) {
;         const int col = jb + q + 1;
; #pragma unroll
;         for (int di = 0; di < RB + 2; ++di) { const bool ok = rv[di] && (col < 64); unpack4(an[q][di], win[2][di]);
; #pragma unroll
;           for (int k = 0; k < 4; ++k) win[2][di][k] = ok ? win[2][di][k] : 0.f; }
; #pragma unroll
;         for (int rr = 0; rr < RB; ++rr) {
;           float uv[4]; unpack4(ur[q][rr], uv);
;           float o[4];
; #pragma unroll
;           for (int k = 0; k < 4; ++k) {
;             float a = bsv[k];
; #pragma unroll
;             for (int di = 0; di < 3; ++di)
; #pragma unroll
;               for (int dj = 0; dj < 3; ++dj) a += win[dj][rr + di][k] * w[di * 3 + dj][k];
;             o[k] = gelu_as(a) * uv[k];
;           }
;           u32x2 ow; ow.x = cvt_pk_bf16(o[0], o[1]); ow.y = cvt_pk_bf16(o[2], o[3]);
;           *(u32x2*)(G + (size_t)((r0 + rr) * 64 + jb + q) * DFF + c0) = ow;
	v_and_b32_e32 v69, 0xffff0000, v94
	v_lshlrev_b32_e32 v70, 16, v95
	v_and_b32_e32 v71, 0xffff0000, v95
	v_pk_mul_f32 v[56:57], v[56:57], v[200:201]
	v_pk_mul_f32 v[58:59], v[58:59], v[200:201]
	v_pk_mul_f32 v[68:69], v[68:69], v[202:203]
	v_pk_mul_f32 v[70:71], v[70:71], v[202:203]
	v_add_u32_e32 v211, 0x2c00, v210
	v_add_u32_e32 v212, v206, v211
	global_load_dwordx2 v[88:89], v212, s[6:7]
	v_add_u32_e32 v213, v207, v211
	global_load_dwordx2 v[90:91], v213, s[6:7]
	v_add_u32_e32 v214, v208, v211
	global_load_dwordx2 v[92:93], v214, s[6:7]
	v_add_u32_e32 v215, v209, v211
	global_load_dwordx2 v[94:95], v215, s[6:7]
	v_add_u32_e32 v216, v207, v210
	global_load_dwordx2 v[104:105], v216, s[8:9]
	v_add_u32_e32 v217, v208, v210
	global_load_dwordx2 v[106:107], v217, s[8:9]
	v_cmp_gt_u32_e32 vcc, 48, v222
	s_nop 1
	v_cndmask_b32_e32 v204, 0, v186, vcc
	v_mov_b32_e32 v205, v204
	v_add_u32_e32 v210, 0x2c00, v210
	v_add_u32_e32 v211, 0x2c00, v210
	v_add_u32_e32 v212, v206, v211
	global_load_dwordx2 v[96:97], v212, s[6:7]
	v_add_u32_e32 v213, v207, v211
	global_load_dwordx2 v[98:99], v213, s[6:7]
	v_add_u32_e32 v214, v208, v211
	global_load_dwordx2 v[100:101], v214, s[6:7]
	v_add_u32_e32 v215, v209, v211
	global_load_dwordx2 v[102:103], v215, s[6:7]
	v_add_u32_e32 v218, v207, v210
	global_load_dwordx2 v[108:109], v218, s[8:9]
	v_add_u32_e32 v219, v208, v210
	global_load_dwordx2 v[110:111], v219, s[8:9]
	s_waitcnt vmcnt(6)
	v_lshlrev_b32_e32 v72, 16, v88
	v_and_b32_e32 v73, 0xffff0000, v88
	v_lshlrev_b32_e32 v74, 16, v89
	v_and_b32_e32 v75, 0xffff0000, v89
	v_lshlrev_b32_e32 v76, 16, v90
	v_and_b32_e32 v77, 0xffff0000, v90
	v_lshlrev_b32_e32 v78, 16, v91
	v_and_b32_e32 v79, 0xffff0000, v91
	v_lshlrev_b32_e32 v80, 16, v92
	v_and_b32_e32 v81, 0xffff0000, v92
	v_lshlrev_b32_e32 v82, 16, v93
	v_and_b32_e32 v83, 0xffff0000, v93
	v_lshlrev_b32_e32 v84, 16, v94
	v_and_b32_e32 v85, 0xffff0000, v94
	v_lshlrev_b32_e32 v86, 16, v95
	v_and_b32_e32 v87, 0xffff0000, v95
	v_pk_mul_f32 v[72:73], v[72:73], v[200:201]
	v_pk_mul_f32 v[74:75], v[74:75], v[200:201]
	v_pk_mul_f32 v[84:85], v[84:85], v[202:203]
	v_pk_mul_f32 v[86:87], v[86:87], v[202:203]
	v_lshlrev_b32_e32 v112, 16, v104
	v_and_b32_e32 v113, 0xffff0000, v104
	v_lshlrev_b32_e32 v114, 16, v105
	v_and_b32_e32 v115, 0xffff0000, v105
	v_lshlrev_b32_e32 v116, 16, v106
	v_and_b32_e32 v117, 0xffff0000, v106
	v_lshlrev_b32_e32 v118, 16, v107
	v_and_b32_e32 v119, 0xffff0000, v107
	v_pk_fma_f32 v[120:121], v[40:41], v[0:1], v[36:37]
	v_pk_fma_f32 v[122:123], v[42:43], v[2:3], v[38:39]
	v_pk_fma_f32 v[124:125], v[44:45], v[0:1], v[36:37]
	v_pk_fma_f32 v[126:127], v[46:47], v[2:3], v[38:39]
	v_pk_fma_f32 v[120:121], v[56:57], v[4:5], v[120:121]
	v_pk_fma_f32 v[122:123], v[58:59], v[6:7], v[122:123]
	v_pk_fma_f32 v[124:125], v[60:61], v[4:5], v[124:125]
	v_pk_fma_f32 v[126:127], v[62:63], v[6:7], v[126:127]
	v_pk_fma_f32 v[120:121], v[72:73], v[8:9], v[120:121]
	v_pk_fma_f32 v[122:123], v[74:75], v[10:11], v[122:123]
	v_pk_fma_f32 v[124:125], v[76:77], v[8:9], v[124:125]
	v_pk_fma_f32 v[126:127], v[78:79], v[10:11], v[126:127]
	v_pk_fma_f32 v[120:121], v[44:45], v[12:13], v[120:121]
	v_pk_fma_f32 v[122:123], v[46:47], v[14:15], v[122:123]
	v_pk_fma_f32 v[124:125], v[48:49], v[12:13], v[124:125]
	v_pk_fma_f32 v[126:127], v[50:51], v[14:15], v[126:127]
	v_pk_fma_f32 v[120:121], v[60:61], v[16:17], v[120:121]
	v_pk_fma_f32 v[122:123], v[62:63], v[18:19], v[122:123]
	v_pk_fma_f32 v[124:125], v[64:65], v[16:17], v[124:125]
	v_pk_fma_f32 v[126:127], v[66:67], v[18:19], v[126:127]
	v_pk_fma_f32 v[120:121], v[76:77], v[20:21], v[120:121]
	v_pk_fma_f32 v[122:123], v[78:79], v[22:23], v[122:123]
	v_pk_fma_f32 v[124:125], v[80:81], v[20:21], v[124:125]
	v_pk_fma_f32 v[126:127], v[82:83], v[22:23], v[126:127]
	v_pk_fma_f32 v[120:121], v[48:49], v[24:25], v[120:121]
	v_pk_fma_f32 v[122:123], v[50:51], v[26:27], v[122:123]
	v_pk_fma_f32 v[124:125], v[52:53], v[24:25], v[124:125]
	v_pk_fma_f32 v[126:127], v[54:55], v[26:27], v[126:127]
	v_pk_fma_f32 v[120:121], v[64:65], v[28:29], v[120:121]
	v_pk_fma_f32 v[122:123], v[66:67], v[30:31], v[122:123]
	v_pk_fma_f32 v[124:125], v[68:69], v[28:29], v[124:125]
	v_pk_fma_f32 v[126:127], v[70:71], v[30:31], v[126:127]
	v_pk_fma_f32 v[120:121], v[80:81], v[32:33], v[120:121]
	v_pk_fma_f32 v[122:123], v[82:83], v[34:35], v[122:123]
	v_pk_fma_f32 v[124:125], v[84:85], v[32:33], v[124:125]
	v_pk_fma_f32 v[126:127], v[86:87], v[34:35], v[126:127]
	v_and_b32_e32 v128, 0x7fffffff, v120
	v_and_b32_e32 v129, 0x7fffffff, v121
	v_and_b32_e32 v130, 0x7fffffff, v122
	v_and_b32_e32 v131, 0x7fffffff, v123
	v_and_b32_e32 v132, 0x7fffffff, v124
	v_and_b32_e32 v133, 0x7fffffff, v125
	v_and_b32_e32 v134, 0x7fffffff, v126
	v_and_b32_e32 v135, 0x7fffffff, v127
	v_pk_fma_f32 v[148:149], v[128:129], v[184:185], v[186:187]
	v_pk_fma_f32 v[150:151], v[130:131], v[184:185], v[186:187]
	v_pk_fma_f32 v[152:153], v[132:133], v[184:185], v[186:187]
	v_pk_fma_f32 v[154:155], v[134:135], v[184:185], v[186:187]
	v_rcp_f32_e32 v148, v148
	v_rcp_f32_e32 v149, v149
	v_rcp_f32_e32 v150, v150
	v_rcp_f32_e32 v151, v151
	v_rcp_f32_e32 v152, v152
	v_rcp_f32_e32 v153, v153
	v_rcp_f32_e32 v154, v154
	v_rcp_f32_e32 v155, v155
	v_pk_fma_f32 v[156:157], v[148:149], v[188:189], v[190:191]
	v_pk_fma_f32 v[158:159], v[150:151], v[188:189], v[190:191]
	v_pk_fma_f32 v[160:161], v[152:153], v[188:189], v[190:191]
	v_pk_fma_f32 v[162:163], v[154:155], v[188:189], v[190:191]
	v_pk_fma_f32 v[156:157], v[156:157], v[148:149], v[192:193]
	v_pk_fma_f32 v[158:159], v[158:159], v[150:151], v[192:193]
	v_pk_fma_f32 v[160:161], v[160:161], v[152:153], v[192:193]
; __device__ __forceinline__ unsigned cvt_pk_bf16(float lo, float hi) { unsigned r; asm volatile("v_cvt_pk_bf16_f32 %0, %1, %2" : "=v"(r) : "v"(lo), "v"(hi)); return r; }
; __device__ __forceinline__ float gelu_as(float v) {
;   const float av = fabsf(v); const float t = __builtin_amdgcn_rcpf(av * 0.2316418882f + 1.0f);
;   float q = t * 0.5307027145f + (-0.7265760135f); q = q * t + 0.7107068705f; q = q * t + (-0.142248368f); q = q * t + 0.127414796f; q = q * t;
;   const float e = __builtin_amdgcn_exp2f((v * v) * (-0.72134752044f));
;   const float m = v * (q * e);
;   return v < 0.f ? m : v - m;
; }
; __device__ __forceinline__ void phase_conv(KP p, int l, int tid) {
;     ...
;     for (int jb = j0; jb < j0 + 16; jb += CB) {
;       u32x2 an[CB][RB + 2], ur[CB][RB];
; #pragma unroll
;       for (int q = 0; q < CB; ++q) { const int col = jb + q + 1; const int cl = col > 63 ? 63 : col;
; #pragma unroll
;         for (int di = 0; di < RB + 2; ++di) an[q][di] = *(const u32x2*)(rowp[di] + (size_t)cl * DFF);
; #pragma unroll
;         for (int rr = 0; rr < RB; ++rr) ur[q][rr] = *(const u32x2*)(U + (size_t)((r0 + rr) * 64 + jb + q) * DFF + c0); }
;       __builtin_amdgcn_sched_barrier(0);
; #pragma unroll
;       for (int q = 0; q < CB; ++q) {
;         const int col = jb + q + 1;
; #pragma unroll
;         for (int di = 0; di < RB + 2; ++di) { const bool ok = rv[di] && (col < 64); unpack4(an[q][di], win[2][di]);
; #pragma unroll
;           for (int k = 0; k < 4; ++k) win[2][di][k] = ok ? win[2][di][k] : 0.f; }
; #pragma unroll
;         for (int rr = 0; rr < RB; ++rr) {
;           float uv[4]; unpack4(ur[q][rr], uv);
;           float o[4];
; #pragma unroll
;           for (int k = 0; k < 4; ++k) {
;             float a = bsv[k];
; #pragma unroll
;             for (int di = 0; di < 3; ++di)
; #pragma unroll
;               for (int dj = 0; dj < 3; ++dj) a += win[dj][rr + di][k] * w[di * 3 + dj][k];
;             o[k] = gelu_as(a) * uv[k];
;           }
;           u32x2 ow; ow.x = cvt_pk_bf16(o[0], o[1]); ow.y = cvt_pk_bf16(o[2], o[3]);
;           *(u32x2*)(G + (size_t)((r0 + rr) * 64 + jb + q) * DFF + c0) = ow;
	v_pk_fma_f32 v[162:163], v[162:163], v[154:155], v[192:193]
	v_pk_fma_f32 v[156:157], v[156:157], v[148:149], v[194:195]
	v_pk_fma_f32 v[158:159], v[158:159], v[150:151], v[194:195]
	v_pk_fma_f32 v[160:161], v[160:161], v[152:153], v[194:195]
	v_pk_fma_f32 v[162:163], v[162:163], v[154:155], v[194:195]
	v_pk_fma_f32 v[156:157], v[156:157], v[148:149], v[196:197]
	v_pk_fma_f32 v[158:159], v[158:159], v[150:151], v[196:197]
	v_pk_fma_f32 v[160:161], v[160:161], v[152:153], v[196:197]
	v_pk_fma_f32 v[162:163], v[162:163], v[154:155], v[196:197]
	v_pk_mul_f32 v[156:157], v[156:157], v[148:149]
	v_pk_mul_f32 v[158:159], v[158:159], v[150:151]
	v_pk_mul_f32 v[160:161], v[160:161], v[152:153]
	v_pk_mul_f32 v[162:163], v[162:163], v[154:155]
	v_pk_mul_f32 v[164:165], v[120:121], v[120:121]
	v_pk_mul_f32 v[166:167], v[122:123], v[122:123]
	v_pk_mul_f32 v[168:169], v[124:125], v[124:125]
	v_pk_mul_f32 v[170:171], v[126:127], v[126:127]
	v_pk_mul_f32 v[164:165], v[164:165], v[198:199]
	v_pk_mul_f32 v[166:167], v[166:167], v[198:199]
	v_pk_mul_f32 v[168:169], v[168:169], v[198:199]
	v_pk_mul_f32 v[170:171], v[170:171], v[198:199]
	v_exp_f32_e32 v164, v164
	v_exp_f32_e32 v165, v165
	v_exp_f32_e32 v166, v166
	v_exp_f32_e32 v167, v167
	v_exp_f32_e32 v168, v168
	v_exp_f32_e32 v169, v169
	v_exp_f32_e32 v170, v170
	v_exp_f32_e32 v171, v171
	v_pk_mul_f32 v[156:157], v[156:157], v[164:165]
	v_pk_mul_f32 v[158:159], v[158:159], v[166:167]
	v_pk_mul_f32 v[160:161], v[160:161], v[168:169]
	v_pk_mul_f32 v[162:163], v[162:163], v[170:171]
	v_pk_mul_f32 v[156:157], v[128:129], v[156:157]
	v_pk_mul_f32 v[158:159], v[130:131], v[158:159]
	v_pk_mul_f32 v[160:161], v[132:133], v[160:161]
	v_pk_mul_f32 v[162:163], v[134:135], v[162:163]
	v_max_f32_e32 v172, 0, v120
	v_max_f32_e32 v173, 0, v121
	v_max_f32_e32 v174, 0, v122
	v_max_f32_e32 v175, 0, v123
	v_max_f32_e32 v176, 0, v124
	v_max_f32_e32 v177, 0, v125
	v_max_f32_e32 v178, 0, v126
	v_max_f32_e32 v179, 0, v127
	v_pk_add_f32 v[172:173], v[172:173], v[156:157] neg_lo:[0,1] neg_hi:[0,1]
	v_pk_add_f32 v[174:175], v[174:175], v[158:159] neg_lo:[0,1] neg_hi:[0,1]
	v_pk_add_f32 v[176:177], v[176:177], v[160:161] neg_lo:[0,1] neg_hi:[0,1]
	v_pk_add_f32 v[178:179], v[178:179], v[162:163] neg_lo:[0,1] neg_hi:[0,1]
	v_pk_mul_f32 v[172:173], v[172:173], v[112:113]
	v_pk_mul_f32 v[174:175], v[174:175], v[114:115]
	v_pk_mul_f32 v[176:177], v[176:177], v[116:117]
	v_pk_mul_f32 v[178:179], v[178:179], v[118:119]
	v_cvt_pk_bf16_f32 v180, v172, v173
	v_cvt_pk_bf16_f32 v181, v174, v175
	v_cvt_pk_bf16_f32 v182, v176, v177
	v_cvt_pk_bf16_f32 v183, v178, v179
	global_store_dwordx2 v216, v[180:181], s[10:11]
	global_store_dwordx2 v217, v[182:183], s[10:11]
	v_add_u32_e32 v210, 0x2c00, v210
	v_add_u32_e32 v211, 0x2c00, v210
	v_add_u32_e32 v212, v206, v211
	global_load_dwordx2 v[88:89], v212, s[6:7]
	v_add_u32_e32 v213, v207, v211
	global_load_dwordx2 v[90:91], v213, s[6:7]
	v_add_u32_e32 v214, v208, v211
	global_load_dwordx2 v[92:93], v214, s[6:7]
	v_add_u32_e32 v215, v209, v211
	global_load_dwordx2 v[94:95], v215, s[6:7]
	v_add_u32_e32 v216, v207, v210
	global_load_dwordx2 v[104:105], v216, s[8:9]
	v_add_u32_e32 v217, v208, v210
	global_load_dwordx2 v[106:107], v217, s[8:9]
	s_waitcnt vmcnt(8)
	v_lshlrev_b32_e32 v40, 16, v96
	v_and_b32_e32 v41, 0xffff0000, v96
	v_lshlrev_b32_e32 v42, 16, v97
	v_and_b32_e32 v43, 0xffff0000, v97
	v_lshlrev_b32_e32 v44, 16, v98
	v_and_b32_e32 v45, 0xffff0000, v98
	v_lshlrev_b32_e32 v46, 16, v99
	v_and_b32_e32 v47, 0xffff0000, v99
	v_lshlrev_b32_e32 v48, 16, v100
	v_and_b32_e32 v49, 0xffff0000, v100
	v_lshlrev_b32_e32 v50, 16, v101
	v_and_b32_e32 v51, 0xffff0000, v101
	v_lshlrev_b32_e32 v52, 16, v102
	v_and_b32_e32 v53, 0xffff0000, v102
	v_lshlrev_b32_e32 v54, 16, v103
	v_and_b32_e32 v55, 0xffff0000, v103
	v_pk_mul_f32 v[40:41], v[40:41], v[200:201]
	v_pk_mul_f32 v[42:43], v[42:43], v[200:201]
	v_pk_mul_f32 v[52:53], v[52:53], v[202:203]
	v_pk_mul_f32 v[54:55], v[54:55], v[202:203]
	v_lshlrev_b32_e32 v112, 16, v108
	v_and_b32_e32 v113, 0xffff0000, v108
	v_lshlrev_b32_e32 v114, 16, v109
	v_and_b32_e32 v115, 0xffff0000, v109
	v_lshlrev_b32_e32 v116, 16, v110
	v_and_b32_e32 v117, 0xffff0000, v110
	v_lshlrev_b32_e32 v118, 16, v111
	v_and_b32_e32 v119, 0xffff0000, v111
	v_pk_fma_f32 v[120:121], v[56:57], v[0:1], v[36:37]
	v_pk_fma_f32 v[122:123], v[58:59], v[2:3], v[38:39]
	v_pk_fma_f32 v[124:125], v[60:61], v[0:1], v[36:37]
	v_pk_fma_f32 v[126:127], v[62:63], v[2:3], v[38:39]
	v_pk_fma_f32 v[120:121], v[72:73], v[4:5], v[120:121]
	v_pk_fma_f32 v[122:123], v[74:75], v[6:7], v[122:123]
	v_pk_fma_f32 v[124:125], v[76:77], v[4:5], v[124:125]
	v_pk_fma_f32 v[126:127], v[78:79], v[6:7], v[126:127]
	v_pk_fma_f32 v[120:121], v[40:41], v[8:9], v[120:121]
	v_pk_fma_f32 v[122:123], v[42:43], v[10:11], v[122:123]
	v_pk_fma_f32 v[124:125], v[44:45], v[8:9], v[124:125]
	v_pk_fma_f32 v[126:127], v[46:47], v[10:11], v[126:127]
	v_pk_fma_f32 v[120:121], v[60:61], v[12:13], v[120:121]
	v_pk_fma_f32 v[122:123], v[62:63], v[14:15], v[122:123]
	v_pk_fma_f32 v[124:125], v[64:65], v[12:13], v[124:125]
	v_pk_fma_f32 v[126:127], v[66:67], v[14:15], v[126:127]
	v_pk_fma_f32 v[120:121], v[76:77], v[16:17], v[120:121]
	v_pk_fma_f32 v[122:123], v[78:79], v[18:19], v[122:123]
	v_pk_fma_f32 v[124:125], v[80:81], v[16:17], v[124:125]
	v_pk_fma_f32 v[126:127], v[82:83], v[18:19], v[126:127]
	v_pk_fma_f32 v[120:121], v[44:45], v[20:21], v[120:121]
	v_pk_fma_f32 v[122:123], v[46:47], v[22:23], v[122:123]
	v_pk_fma_f32 v[124:125], v[48:49], v[20:21], v[124:125]
	v_pk_fma_f32 v[126:127], v[50:51], v[22:23], v[126:127]
; __device__ __forceinline__ unsigned cvt_pk_bf16(float lo, float hi) { unsigned r; asm volatile("v_cvt_pk_bf16_f32 %0, %1, %2" : "=v"(r) : "v"(lo), "v"(hi)); return r; }
; __device__ __forceinline__ float gelu_as(float v) {
;   const float av = fabsf(v); const float t = __builtin_amdgcn_rcpf(av * 0.2316418882f + 1.0f);
;   float q = t * 0.5307027145f + (-0.7265760135f); q = q * t + 0.7107068705f; q = q * t + (-0.142248368f); q = q * t + 0.127414796f; q = q * t;
;   const float e = __builtin_amdgcn_exp2f((v * v) * (-0.72134752044f));
;   const float m = v * (q * e);
;   return v < 0.f ? m : v - m;
; }
; __device__ __forceinline__ void phase_conv(KP p, int l, int tid) {
;     ...
;             o[k] = gelu_as(a) * uv[k];
;           }
;           u32x2 ow; ow.x = cvt_pk_bf16(o[0], o[1]); ow.y = cvt_pk_bf16(o[2], o[3]);
;           *(u32x2*)(G + (size_t)((r0 + rr) * 64 + jb + q) * DFF + c0) = ow;
	v_pk_fma_f32 v[120:121], v[64:65], v[24:25], v[120:121]
	v_pk_fma_f32 v[122:123], v[66:67], v[26:27], v[122:123]
	v_pk_fma_f32 v[124:125], v[68:69], v[24:25], v[124:125]
	v_pk_fma_f32 v[126:127], v[70:71], v[26:27], v[126:127]
	v_pk_fma_f32 v[120:121], v[80:81], v[28:29], v[120:121]
	v_pk_fma_f32 v[122:123], v[82:83], v[30:31], v[122:123]
	v_pk_fma_f32 v[124:125], v[84:85], v[28:29], v[124:125]
	v_pk_fma_f32 v[126:127], v[86:87], v[30:31], v[126:127]
	v_pk_fma_f32 v[120:121], v[48:49], v[32:33], v[120:121]
	v_pk_fma_f32 v[122:123], v[50:51], v[34:35], v[122:123]
	v_pk_fma_f32 v[124:125], v[52:53], v[32:33], v[124:125]
	v_pk_fma_f32 v[126:127], v[54:55], v[34:35], v[126:127]
	v_and_b32_e32 v128, 0x7fffffff, v120
	v_and_b32_e32 v129, 0x7fffffff, v121
	v_and_b32_e32 v130, 0x7fffffff, v122
	v_and_b32_e32 v131, 0x7fffffff, v123
	v_and_b32_e32 v132, 0x7fffffff, v124
	v_and_b32_e32 v133, 0x7fffffff, v125
	v_and_b32_e32 v134, 0x7fffffff, v126
	v_and_b32_e32 v135, 0x7fffffff, v127
	v_pk_fma_f32 v[148:149], v[128:129], v[184:185], v[186:187]
	v_pk_fma_f32 v[150:151], v[130:131], v[184:185], v[186:187]
	v_pk_fma_f32 v[152:153], v[132:133], v[184:185], v[186:187]
	v_pk_fma_f32 v[154:155], v[134:135], v[184:185], v[186:187]
	v_rcp_f32_e32 v148, v148
	v_rcp_f32_e32 v149, v149
	v_rcp_f32_e32 v150, v150
	v_rcp_f32_e32 v151, v151
	v_rcp_f32_e32 v152, v152
	v_rcp_f32_e32 v153, v153
	v_rcp_f32_e32 v154, v154
	v_rcp_f32_e32 v155, v155
	v_pk_fma_f32 v[156:157], v[148:149], v[188:189], v[190:191]
	v_pk_fma_f32 v[158:159], v[150:151], v[188:189], v[190:191]
	v_pk_fma_f32 v[160:161], v[152:153], v[188:189], v[190:191]
	v_pk_fma_f32 v[162:163], v[154:155], v[188:189], v[190:191]
	v_pk_fma_f32 v[156:157], v[156:157], v[148:149], v[192:193]
	v_pk_fma_f32 v[158:159], v[158:159], v[150:151], v[192:193]
	v_pk_fma_f32 v[160:161], v[160:161], v[152:153], v[192:193]
	v_pk_fma_f32 v[162:163], v[162:163], v[154:155], v[192:193]
	v_pk_fma_f32 v[156:157], v[156:157], v[148:149], v[194:195]
	v_pk_fma_f32 v[158:159], v[158:159], v[150:151], v[194:195]
	v_pk_fma_f32 v[160:161], v[160:161], v[152:153], v[194:195]
	v_pk_fma_f32 v[162:163], v[162:163], v[154:155], v[194:195]
	v_pk_fma_f32 v[156:157], v[156:157], v[148:149], v[196:197]
	v_pk_fma_f32 v[158:159], v[158:159], v[150:151], v[196:197]
	v_pk_fma_f32 v[160:161], v[160:161], v[152:153], v[196:197]
	v_pk_fma_f32 v[162:163], v[162:163], v[154:155], v[196:197]
	v_pk_mul_f32 v[156:157], v[156:157], v[148:149]
	v_pk_mul_f32 v[158:159], v[158:159], v[150:151]
	v_pk_mul_f32 v[160:161], v[160:161], v[152:153]
	v_pk_mul_f32 v[162:163], v[162:163], v[154:155]
	v_pk_mul_f32 v[164:165], v[120:121], v[120:121]
	v_pk_mul_f32 v[166:167], v[122:123], v[122:123]
	v_pk_mul_f32 v[168:169], v[124:125], v[124:125]
	v_pk_mul_f32 v[170:171], v[126:127], v[126:127]
	v_pk_mul_f32 v[164:165], v[164:165], v[198:199]
	v_pk_mul_f32 v[166:167], v[166:167], v[198:199]
	v_pk_mul_f32 v[168:169], v[168:169], v[198:199]
	v_pk_mul_f32 v[170:171], v[170:171], v[198:199]
	v_exp_f32_e32 v164, v164
	v_exp_f32_e32 v165, v165
	v_exp_f32_e32 v166, v166
	v_exp_f32_e32 v167, v167
	v_exp_f32_e32 v168, v168
	v_exp_f32_e32 v169, v169
	v_exp_f32_e32 v170, v170
	v_exp_f32_e32 v171, v171
	v_pk_mul_f32 v[156:157], v[156:157], v[164:165]
	v_pk_mul_f32 v[158:159], v[158:159], v[166:167]
	v_pk_mul_f32 v[160:161], v[160:161], v[168:169]
	v_pk_mul_f32 v[162:163], v[162:163], v[170:171]
	v_pk_mul_f32 v[156:157], v[128:129], v[156:157]
	v_pk_mul_f32 v[158:159], v[130:131], v[158:159]
	v_pk_mul_f32 v[160:161], v[132:133], v[160:161]
	v_pk_mul_f32 v[162:163], v[134:135], v[162:163]
	v_max_f32_e32 v172, 0, v120
	v_max_f32_e32 v173, 0, v121
	v_max_f32_e32 v174, 0, v122
	v_max_f32_e32 v175, 0, v123
	v_max_f32_e32 v176, 0, v124
	v_max_f32_e32 v177, 0, v125
	v_max_f32_e32 v178, 0, v126
	v_max_f32_e32 v179, 0, v127
	v_pk_add_f32 v[172:173], v[172:173], v[156:157] neg_lo:[0,1] neg_hi:[0,1]
	v_pk_add_f32 v[174:175], v[174:175], v[158:159] neg_lo:[0,1] neg_hi:[0,1]
	v_pk_add_f32 v[176:177], v[176:177], v[160:161] neg_lo:[0,1] neg_hi:[0,1]
	v_pk_add_f32 v[178:179], v[178:179], v[162:163] neg_lo:[0,1] neg_hi:[0,1]
	v_pk_mul_f32 v[172:173], v[172:173], v[112:113]
	v_pk_mul_f32 v[174:175], v[174:175], v[114:115]
	v_pk_mul_f32 v[176:177], v[176:177], v[116:117]
	v_pk_mul_f32 v[178:179], v[178:179], v[118:119]
	v_cvt_pk_bf16_f32 v180, v172, v173
	v_cvt_pk_bf16_f32 v181, v174, v175
	v_cvt_pk_bf16_f32 v182, v176, v177
	v_cvt_pk_bf16_f32 v183, v178, v179
	global_store_dwordx2 v218, v[180:181], s[10:11]
	global_store_dwordx2 v219, v[182:183], s[10:11]
	v_add_u32_e32 v210, 0x2c00, v210
	v_add_u32_e32 v211, 0x2c00, v210
	v_add_u32_e32 v212, v206, v211
	global_load_dwordx2 v[96:97], v212, s[6:7]
	v_add_u32_e32 v213, v207, v211
	global_load_dwordx2 v[98:99], v213, s[6:7]
	v_add_u32_e32 v214, v208, v211
	global_load_dwordx2 v[100:101], v214, s[6:7]
	v_add_u32_e32 v215, v209, v211
	global_load_dwordx2 v[102:103], v215, s[6:7]
	v_add_u32_e32 v218, v207, v210
	global_load_dwordx2 v[108:109], v218, s[8:9]
	v_add_u32_e32 v219, v208, v210
	global_load_dwordx2 v[110:111], v219, s[8:9]
	s_waitcnt vmcnt(8)
; __device__ __forceinline__ unsigned cvt_pk_bf16(float lo, float hi) { unsigned r; asm volatile("v_cvt_pk_bf16_f32 %0, %1, %2" : "=v"(r) : "v"(lo), "v"(hi)); return r; }
; __device__ __forceinline__ float gelu_as(float v) {
;   const float av = fabsf(v); const float t = __builtin_amdgcn_rcpf(av * 0.2316418882f + 1.0f);
;   float q = t * 0.5307027145f + (-0.7265760135f); q = q * t + 0.7107068705f; q = q * t + (-0.142248368f); q = q * t + 0.127414796f; q = q * t;
;   const float e = __builtin_amdgcn_exp2f((v * v) * (-0.72134752044f));
;   const float m = v * (q * e);
;   return v < 0.f ? m : v - m;
; }
; __device__ __forceinline__ void phase_conv(KP p, int l, int tid) {
;     ...
;     for (int jb = j0; jb < j0 + 16; jb += CB) {
;       u32x2 an[CB][RB + 2], ur[CB][RB];
; #pragma unroll
;       for (int q = 0; q < CB; ++q) { const int col = jb + q + 1; const int cl = col > 63 ? 63 : col;
; #pragma unroll
;         for (int di = 0; di < RB + 2; ++di) an[q][di] = *(const u32x2*)(rowp[di] + (size_t)cl * DFF);
; #pragma unroll
;         for (int rr = 0; rr < RB; ++rr) ur[q][rr] = *(const u32x2*)(U + (size_t)((r0 + rr) * 64 + jb + q) * DFF + c0); }
;       __builtin_amdgcn_sched_barrier(0);
; #pragma unroll
;       for (int q = 0; q < CB; ++q) {
;         const int col = jb + q + 1;
; #pragma unroll
;         for (int di = 0; di < RB + 2; ++di) { const bool ok = rv[di] && (col < 64); unpack4(an[q][di], win[2][di]);
; #pragma unroll
;           for (int k = 0; k < 4; ++k) win[2][di][k] = ok ? win[2][di][k] : 0.f; }
; #pragma unroll
;         for (int rr = 0; rr < RB; ++rr) {
;           float uv[4]; unpack4(ur[q][rr], uv);
;           float o[4];
; #pragma unroll
;           for (int k = 0; k < 4; ++k) {
;             float a = bsv[k];
; #pragma unroll
;             for (int di = 0; di < 3; ++di)
; #pragma unroll
;               for (int dj = 0; dj < 3; ++dj) a += win[dj][rr + di][k] * w[di * 3 + dj][k];
;             o[k] = gelu_as(a) * uv[k];
;           }
;           u32x2 ow; ow.x = cvt_pk_bf16(o[0], o[1]); ow.y = cvt_pk_bf16(o[2], o[3]);
;           *(u32x2*)(G + (size_t)((r0 + rr) * 64 + jb + q) * DFF + c0) = ow;
	v_lshlrev_b32_e32 v56, 16, v88
	v_and_b32_e32 v57, 0xffff0000, v88
	v_lshlrev_b32_e32 v58, 16, v89
	v_and_b32_e32 v59, 0xffff0000, v89
	v_lshlrev_b32_e32 v60, 16, v90
	v_and_b32_e32 v61, 0xffff0000, v90
	v_lshlrev_b32_e32 v62, 16, v91
	v_and_b32_e32 v63, 0xffff0000, v91
	v_lshlrev_b32_e32 v64, 16, v92
	v_and_b32_e32 v65, 0xffff0000, v92
	v_lshlrev_b32_e32 v66, 16, v93
	v_and_b32_e32 v67, 0xffff0000, v93
	v_lshlrev_b32_e32 v68, 16, v94
	v_and_b32_e32 v69, 0xffff0000, v94
	v_lshlrev_b32_e32 v70, 16, v95
	v_and_b32_e32 v71, 0xffff0000, v95
	v_pk_mul_f32 v[56:57], v[56:57], v[200:201]
	v_pk_mul_f32 v[58:59], v[58:59], v[200:201]
	v_pk_mul_f32 v[68:69], v[68:69], v[202:203]
	v_pk_mul_f32 v[70:71], v[70:71], v[202:203]
	v_lshlrev_b32_e32 v112, 16, v104
	v_and_b32_e32 v113, 0xffff0000, v104
	v_lshlrev_b32_e32 v114, 16, v105
	v_and_b32_e32 v115, 0xffff0000, v105
	v_lshlrev_b32_e32 v116, 16, v106
	v_and_b32_e32 v117, 0xffff0000, v106
	v_lshlrev_b32_e32 v118, 16, v107
	v_and_b32_e32 v119, 0xffff0000, v107
	v_pk_fma_f32 v[120:121], v[72:73], v[0:1], v[36:37]
	v_pk_fma_f32 v[122:123], v[74:75], v[2:3], v[38:39]
	v_pk_fma_f32 v[124:125], v[76:77], v[0:1], v[36:37]
	v_pk_fma_f32 v[126:127], v[78:79], v[2:3], v[38:39]
	v_pk_fma_f32 v[120:121], v[40:41], v[4:5], v[120:121]
	v_pk_fma_f32 v[122:123], v[42:43], v[6:7], v[122:123]
	v_pk_fma_f32 v[124:125], v[44:45], v[4:5], v[124:125]
	v_pk_fma_f32 v[126:127], v[46:47], v[6:7], v[126:127]
	v_pk_fma_f32 v[120:121], v[56:57], v[8:9], v[120:121]
	v_pk_fma_f32 v[122:123], v[58:59], v[10:11], v[122:123]
	v_pk_fma_f32 v[124:125], v[60:61], v[8:9], v[124:125]
	v_pk_fma_f32 v[126:127], v[62:63], v[10:11], v[126:127]
	v_pk_fma_f32 v[120:121], v[76:77], v[12:13], v[120:121]
	v_pk_fma_f32 v[122:123], v[78:79], v[14:15], v[122:123]
	v_pk_fma_f32 v[124:125], v[80:81], v[12:13], v[124:125]
	v_pk_fma_f32 v[126:127], v[82:83], v[14:15], v[126:127]
	v_pk_fma_f32 v[120:121], v[44:45], v[16:17], v[120:121]
	v_pk_fma_f32 v[122:123], v[46:47], v[18:19], v[122:123]
	v_pk_fma_f32 v[124:125], v[48:49], v[16:17], v[124:125]
	v_pk_fma_f32 v[126:127], v[50:51], v[18:19], v[126:127]
	v_pk_fma_f32 v[120:121], v[60:61], v[20:21], v[120:121]
	v_pk_fma_f32 v[122:123], v[62:63], v[22:23], v[122:123]
	v_pk_fma_f32 v[124:125], v[64:65], v[20:21], v[124:125]
	v_pk_fma_f32 v[126:127], v[66:67], v[22:23], v[126:127]
	v_pk_fma_f32 v[120:121], v[80:81], v[24:25], v[120:121]
	v_pk_fma_f32 v[122:123], v[82:83], v[26:27], v[122:123]
	v_pk_fma_f32 v[124:125], v[84:85], v[24:25], v[124:125]
	v_pk_fma_f32 v[126:127], v[86:87], v[26:27], v[126:127]
	v_pk_fma_f32 v[120:121], v[48:49], v[28:29], v[120:121]
	v_pk_fma_f32 v[122:123], v[50:51], v[30:31], v[122:123]
	v_pk_fma_f32 v[124:125], v[52:53], v[28:29], v[124:125]
	v_pk_fma_f32 v[126:127], v[54:55], v[30:31], v[126:127]
	v_pk_fma_f32 v[120:121], v[64:65], v[32:33], v[120:121]
	v_pk_fma_f32 v[122:123], v[66:67], v[34:35], v[122:123]
	v_pk_fma_f32 v[124:125], v[68:69], v[32:33], v[124:125]
	v_pk_fma_f32 v[126:127], v[70:71], v[34:35], v[126:127]
	v_and_b32_e32 v128, 0x7fffffff, v120
	v_and_b32_e32 v129, 0x7fffffff, v121
	v_and_b32_e32 v130, 0x7fffffff, v122
	v_and_b32_e32 v131, 0x7fffffff, v123
	v_and_b32_e32 v132, 0x7fffffff, v124
	v_and_b32_e32 v133, 0x7fffffff, v125
	v_and_b32_e32 v134, 0x7fffffff, v126
	v_and_b32_e32 v135, 0x7fffffff, v127
	v_pk_fma_f32 v[148:149], v[128:129], v[184:185], v[186:187]
	v_pk_fma_f32 v[150:151], v[130:131], v[184:185], v[186:187]
	v_pk_fma_f32 v[152:153], v[132:133], v[184:185], v[186:187]
	v_pk_fma_f32 v[154:155], v[134:135], v[184:185], v[186:187]
	v_rcp_f32_e32 v148, v148
	v_rcp_f32_e32 v149, v149
	v_rcp_f32_e32 v150, v150
	v_rcp_f32_e32 v151, v151
	v_rcp_f32_e32 v152, v152
	v_rcp_f32_e32 v153, v153
	v_rcp_f32_e32 v154, v154
	v_rcp_f32_e32 v155, v155
	v_pk_fma_f32 v[156:157], v[148:149], v[188:189], v[190:191]
	v_pk_fma_f32 v[158:159], v[150:151], v[188:189], v[190:191]
	v_pk_fma_f32 v[160:161], v[152:153], v[188:189], v[190:191]
	v_pk_fma_f32 v[162:163], v[154:155], v[188:189], v[190:191]
	v_pk_fma_f32 v[156:157], v[156:157], v[148:149], v[192:193]
	v_pk_fma_f32 v[158:159], v[158:159], v[150:151], v[192:193]
	v_pk_fma_f32 v[160:161], v[160:161], v[152:153], v[192:193]
	v_pk_fma_f32 v[162:163], v[162:163], v[154:155], v[192:193]
	v_pk_fma_f32 v[156:157], v[156:157], v[148:149], v[194:195]
	v_pk_fma_f32 v[158:159], v[158:159], v[150:151], v[194:195]
	v_pk_fma_f32 v[160:161], v[160:161], v[152:153], v[194:195]
	v_pk_fma_f32 v[162:163], v[162:163], v[154:155], v[194:195]
	v_pk_fma_f32 v[156:157], v[156:157], v[148:149], v[196:197]
	v_pk_fma_f32 v[158:159], v[158:159], v[150:151], v[196:197]
	v_pk_fma_f32 v[160:161], v[160:161], v[152:153], v[196:197]
	v_pk_fma_f32 v[162:163], v[162:163], v[154:155], v[196:197]
	v_pk_mul_f32 v[156:157], v[156:157], v[148:149]
	v_pk_mul_f32 v[158:159], v[158:159], v[150:151]
	v_pk_mul_f32 v[160:161], v[160:161], v[152:153]
	v_pk_mul_f32 v[162:163], v[162:163], v[154:155]
	v_pk_mul_f32 v[164:165], v[120:121], v[120:121]
	v_pk_mul_f32 v[166:167], v[122:123], v[122:123]
	v_pk_mul_f32 v[168:169], v[124:125], v[124:125]
	v_pk_mul_f32 v[170:171], v[126:127], v[126:127]
	v_pk_mul_f32 v[164:165], v[164:165], v[198:199]
	v_pk_mul_f32 v[166:167], v[166:167], v[198:199]
	v_pk_mul_f32 v[168:169], v[168:169], v[198:199]
	v_pk_mul_f32 v[170:171], v[170:171], v[198:199]
	v_exp_f32_e32 v164, v164
	v_exp_f32_e32 v165, v165
	v_exp_f32_e32 v166, v166
	v_exp_f32_e32 v167, v167
	v_exp_f32_e32 v168, v168
	v_exp_f32_e32 v169, v169
	v_exp_f32_e32 v170, v170
	v_exp_f32_e32 v171, v171
	v_pk_mul_f32 v[156:157], v[156:157], v[164:165]
	v_pk_mul_f32 v[158:159], v[158:159], v[166:167]
; __device__ __forceinline__ unsigned cvt_pk_bf16(float lo, float hi) { unsigned r; asm volatile("v_cvt_pk_bf16_f32 %0, %1, %2" : "=v"(r) : "v"(lo), "v"(hi)); return r; }
; __device__ __forceinline__ float gelu_as(float v) {
;   const float av = fabsf(v); const float t = __builtin_amdgcn_rcpf(av * 0.2316418882f + 1.0f);
;   float q = t * 0.5307027145f + (-0.7265760135f); q = q * t + 0.7107068705f; q = q * t + (-0.142248368f); q = q * t + 0.127414796f; q = q * t;
;   const float e = __builtin_amdgcn_exp2f((v * v) * (-0.72134752044f));
;   const float m = v * (q * e);
;   return v < 0.f ? m : v - m;
; }
; __device__ __forceinline__ void phase_conv(KP p, int l, int tid) {
;     ...
;     for (int jb = j0; jb < j0 + 16; jb += CB) {
;       u32x2 an[CB][RB + 2], ur[CB][RB];
; #pragma unroll
;       for (int q = 0; q < CB; ++q) { const int col = jb + q + 1; const int cl = col > 63 ? 63 : col;
; #pragma unroll
;         for (int di = 0; di < RB + 2; ++di) an[q][di] = *(const u32x2*)(rowp[di] + (size_t)cl * DFF);
; #pragma unroll
;         for (int rr = 0; rr < RB; ++rr) ur[q][rr] = *(const u32x2*)(U + (size_t)((r0 + rr) * 64 + jb + q) * DFF + c0); }
;       __builtin_amdgcn_sched_barrier(0);
; #pragma unroll
;       for (int q = 0; q < CB; ++q) {
;         const int col = jb + q + 1;
; #pragma unroll
;         for (int di = 0; di < RB + 2; ++di) { const bool ok = rv[di] && (col < 64); unpack4(an[q][di], win[2][di]);
; #pragma unroll
;           for (int k = 0; k < 4; ++k) win[2][di][k] = ok ? win[2][di][k] : 0.f; }
; #pragma unroll
;         for (int rr = 0; rr < RB; ++rr) {
;           float uv[4]; unpack4(ur[q][rr], uv);
;           float o[4];
; #pragma unroll
;           for (int k = 0; k < 4; ++k) {
;             float a = bsv[k];
; #pragma unroll
;             for (int di = 0; di < 3; ++di)
; #pragma unroll
;               for (int dj = 0; dj < 3; ++dj) a += win[dj][rr + di][k] * w[di * 3 + dj][k];
;             o[k] = gelu_as(a) * uv[k];
;           }
;           u32x2 ow; ow.x = cvt_pk_bf16(o[0], o[1]); ow.y = cvt_pk_bf16(o[2], o[3]);
;           *(u32x2*)(G + (size_t)((r0 + rr) * 64 + jb + q) * DFF + c0) = ow;
	v_pk_mul_f32 v[160:161], v[160:161], v[168:169]
	v_pk_mul_f32 v[162:163], v[162:163], v[170:171]
	v_pk_mul_f32 v[156:157], v[128:129], v[156:157]
	v_pk_mul_f32 v[158:159], v[130:131], v[158:159]
	v_pk_mul_f32 v[160:161], v[132:133], v[160:161]
	v_pk_mul_f32 v[162:163], v[134:135], v[162:163]
	v_max_f32_e32 v172, 0, v120
	v_max_f32_e32 v173, 0, v121
	v_max_f32_e32 v174, 0, v122
	v_max_f32_e32 v175, 0, v123
	v_max_f32_e32 v176, 0, v124
	v_max_f32_e32 v177, 0, v125
	v_max_f32_e32 v178, 0, v126
	v_max_f32_e32 v179, 0, v127
	v_pk_add_f32 v[172:173], v[172:173], v[156:157] neg_lo:[0,1] neg_hi:[0,1]
	v_pk_add_f32 v[174:175], v[174:175], v[158:159] neg_lo:[0,1] neg_hi:[0,1]
	v_pk_add_f32 v[176:177], v[176:177], v[160:161] neg_lo:[0,1] neg_hi:[0,1]
	v_pk_add_f32 v[178:179], v[178:179], v[162:163] neg_lo:[0,1] neg_hi:[0,1]
	v_pk_mul_f32 v[172:173], v[172:173], v[112:113]
	v_pk_mul_f32 v[174:175], v[174:175], v[114:115]
	v_pk_mul_f32 v[176:177], v[176:177], v[116:117]
	v_pk_mul_f32 v[178:179], v[178:179], v[118:119]
	v_cvt_pk_bf16_f32 v180, v172, v173
	v_cvt_pk_bf16_f32 v181, v174, v175
	v_cvt_pk_bf16_f32 v182, v176, v177
	v_cvt_pk_bf16_f32 v183, v178, v179
	global_store_dwordx2 v216, v[180:181], s[10:11]
	global_store_dwordx2 v217, v[182:183], s[10:11]
	v_add_u32_e32 v210, 0x2c00, v210
	v_add_u32_e32 v211, 0x2c00, v210
	v_add_u32_e32 v212, v206, v211
	global_load_dwordx2 v[88:89], v212, s[6:7]
	v_add_u32_e32 v213, v207, v211
	global_load_dwordx2 v[90:91], v213, s[6:7]
	v_add_u32_e32 v214, v208, v211
	global_load_dwordx2 v[92:93], v214, s[6:7]
	v_add_u32_e32 v215, v209, v211
	global_load_dwordx2 v[94:95], v215, s[6:7]
	v_add_u32_e32 v216, v207, v210
	global_load_dwordx2 v[104:105], v216, s[8:9]
	v_add_u32_e32 v217, v208, v210
	global_load_dwordx2 v[106:107], v217, s[8:9]
	s_waitcnt vmcnt(8)
	v_lshlrev_b32_e32 v72, 16, v96
	v_and_b32_e32 v73, 0xffff0000, v96
	v_lshlrev_b32_e32 v74, 16, v97
	v_and_b32_e32 v75, 0xffff0000, v97
	v_lshlrev_b32_e32 v76, 16, v98
	v_and_b32_e32 v77, 0xffff0000, v98
	v_lshlrev_b32_e32 v78, 16, v99
	v_and_b32_e32 v79, 0xffff0000, v99
	v_lshlrev_b32_e32 v80, 16, v100
	v_and_b32_e32 v81, 0xffff0000, v100
	v_lshlrev_b32_e32 v82, 16, v101
	v_and_b32_e32 v83, 0xffff0000, v101
	v_lshlrev_b32_e32 v84, 16, v102
	v_and_b32_e32 v85, 0xffff0000, v102
	v_lshlrev_b32_e32 v86, 16, v103
	v_and_b32_e32 v87, 0xffff0000, v103
	v_pk_mul_f32 v[72:73], v[72:73], v[200:201]
	v_pk_mul_f32 v[74:75], v[74:75], v[200:201]
	v_pk_mul_f32 v[84:85], v[84:85], v[202:203]
	v_pk_mul_f32 v[86:87], v[86:87], v[202:203]
	v_lshlrev_b32_e32 v112, 16, v108
	v_and_b32_e32 v113, 0xffff0000, v108
	v_lshlrev_b32_e32 v114, 16, v109
	v_and_b32_e32 v115, 0xffff0000, v109
	v_lshlrev_b32_e32 v116, 16, v110
	v_and_b32_e32 v117, 0xffff0000, v110
	v_lshlrev_b32_e32 v118, 16, v111
	v_and_b32_e32 v119, 0xffff0000, v111
	v_pk_fma_f32 v[120:121], v[40:41], v[0:1], v[36:37]
	v_pk_fma_f32 v[122:123], v[42:43], v[2:3], v[38:39]
	v_pk_fma_f32 v[124:125], v[44:45], v[0:1], v[36:37]
	v_pk_fma_f32 v[126:127], v[46:47], v[2:3], v[38:39]
	v_pk_fma_f32 v[120:121], v[56:57], v[4:5], v[120:121]
	v_pk_fma_f32 v[122:123], v[58:59], v[6:7], v[122:123]
	v_pk_fma_f32 v[124:125], v[60:61], v[4:5], v[124:125]
	v_pk_fma_f32 v[126:127], v[62:63], v[6:7], v[126:127]
	v_pk_fma_f32 v[120:121], v[72:73], v[8:9], v[120:121]
	v_pk_fma_f32 v[122:123], v[74:75], v[10:11], v[122:123]
	v_pk_fma_f32 v[124:125], v[76:77], v[8:9], v[124:125]
	v_pk_fma_f32 v[126:127], v[78:79], v[10:11], v[126:127]
	v_pk_fma_f32 v[120:121], v[44:45], v[12:13], v[120:121]
	v_pk_fma_f32 v[122:123], v[46:47], v[14:15], v[122:123]
	v_pk_fma_f32 v[124:125], v[48:49], v[12:13], v[124:125]
	v_pk_fma_f32 v[126:127], v[50:51], v[14:15], v[126:127]
	v_pk_fma_f32 v[120:121], v[60:61], v[16:17], v[120:121]
	v_pk_fma_f32 v[122:123], v[62:63], v[18:19], v[122:123]
	v_pk_fma_f32 v[124:125], v[64:65], v[16:17], v[124:125]
	v_pk_fma_f32 v[126:127], v[66:67], v[18:19], v[126:127]
	v_pk_fma_f32 v[120:121], v[76:77], v[20:21], v[120:121]
	v_pk_fma_f32 v[122:123], v[78:79], v[22:23], v[122:123]
	v_pk_fma_f32 v[124:125], v[80:81], v[20:21], v[124:125]
	v_pk_fma_f32 v[126:127], v[82:83], v[22:23], v[126:127]
	v_pk_fma_f32 v[120:121], v[48:49], v[24:25], v[120:121]
	v_pk_fma_f32 v[122:123], v[50:51], v[26:27], v[122:123]
	v_pk_fma_f32 v[124:125], v[52:53], v[24:25], v[124:125]
	v_pk_fma_f32 v[126:127], v[54:55], v[26:27], v[126:127]
	v_pk_fma_f32 v[120:121], v[64:65], v[28:29], v[120:121]
	v_pk_fma_f32 v[122:123], v[66:67], v[30:31], v[122:123]
	v_pk_fma_f32 v[124:125], v[68:69], v[28:29], v[124:125]
	v_pk_fma_f32 v[126:127], v[70:71], v[30:31], v[126:127]
	v_pk_fma_f32 v[120:121], v[80:81], v[32:33], v[120:121]
	v_pk_fma_f32 v[122:123], v[82:83], v[34:35], v[122:123]
	v_pk_fma_f32 v[124:125], v[84:85], v[32:33], v[124:125]
	v_pk_fma_f32 v[126:127], v[86:87], v[34:35], v[126:127]
	v_and_b32_e32 v128, 0x7fffffff, v120
	v_and_b32_e32 v129, 0x7fffffff, v121
	v_and_b32_e32 v130, 0x7fffffff, v122
	v_and_b32_e32 v131, 0x7fffffff, v123
	v_and_b32_e32 v132, 0x7fffffff, v124
	v_and_b32_e32 v133, 0x7fffffff, v125
	v_and_b32_e32 v134, 0x7fffffff, v126
	v_and_b32_e32 v135, 0x7fffffff, v127
	v_pk_fma_f32 v[148:149], v[128:129], v[184:185], v[186:187]
	v_pk_fma_f32 v[150:151], v[130:131], v[184:185], v[186:187]
	v_pk_fma_f32 v[152:153], v[132:133], v[184:185], v[186:187]
	v_pk_fma_f32 v[154:155], v[134:135], v[184:185], v[186:187]
	v_rcp_f32_e32 v148, v148
	v_rcp_f32_e32 v149, v149
	v_rcp_f32_e32 v150, v150
	v_rcp_f32_e32 v151, v151
	v_rcp_f32_e32 v152, v152
	v_rcp_f32_e32 v153, v153
	v_rcp_f32_e32 v154, v154
	v_rcp_f32_e32 v155, v155
; __device__ __forceinline__ unsigned cvt_pk_bf16(float lo, float hi) { unsigned r; asm volatile("v_cvt_pk_bf16_f32 %0, %1, %2" : "=v"(r) : "v"(lo), "v"(hi)); return r; }
; __device__ __forceinline__ float gelu_as(float v) {
;   const float av = fabsf(v); const float t = __builtin_amdgcn_rcpf(av * 0.2316418882f + 1.0f);
;   float q = t * 0.5307027145f + (-0.7265760135f); q = q * t + 0.7107068705f; q = q * t + (-0.142248368f); q = q * t + 0.127414796f; q = q * t;
;   const float e = __builtin_amdgcn_exp2f((v * v) * (-0.72134752044f));
;   const float m = v * (q * e);
;   return v < 0.f ? m : v - m;
; }
; __device__ __forceinline__ void phase_conv(KP p, int l, int tid) {
;     ...
;     for (int jb = j0; jb < j0 + 16; jb += CB) {
;       u32x2 an[CB][RB + 2], ur[CB][RB];
; #pragma unroll
;       for (int q = 0; q < CB; ++q) { const int col = jb + q + 1; const int cl = col > 63 ? 63 : col;
; #pragma unroll
;         for (int di = 0; di < RB + 2; ++di) an[q][di] = *(const u32x2*)(rowp[di] + (size_t)cl * DFF);
; #pragma unroll
;         for (int rr = 0; rr < RB; ++rr) ur[q][rr] = *(const u32x2*)(U + (size_t)((r0 + rr) * 64 + jb + q) * DFF + c0); }
;       __builtin_amdgcn_sched_barrier(0);
; #pragma unroll
;       for (int q = 0; q < CB; ++q) {
;         const int col = jb + q + 1;
; #pragma unroll
;         for (int di = 0; di < RB + 2; ++di) { const bool ok = rv[di] && (col < 64); unpack4(an[q][di], win[2][di]);
; #pragma unroll
;           for (int k = 0; k < 4; ++k) win[2][di][k] = ok ? win[2][di][k] : 0.f; }
; #pragma unroll
;         for (int rr = 0; rr < RB; ++rr) {
;           float uv[4]; unpack4(ur[q][rr], uv);
;           float o[4];
; #pragma unroll
;           for (int k = 0; k < 4; ++k) {
;             float a = bsv[k];
; #pragma unroll
;             for (int di = 0; di < 3; ++di)
; #pragma unroll
;               for (int dj = 0; dj < 3; ++dj) a += win[dj][rr + di][k] * w[di * 3 + dj][k];
;             o[k] = gelu_as(a) * uv[k];
;           }
;           u32x2 ow; ow.x = cvt_pk_bf16(o[0], o[1]); ow.y = cvt_pk_bf16(o[2], o[3]);
;           *(u32x2*)(G + (size_t)((r0 + rr) * 64 + jb + q) * DFF + c0) = ow;
	v_pk_fma_f32 v[156:157], v[148:149], v[188:189], v[190:191]
	v_pk_fma_f32 v[158:159], v[150:151], v[188:189], v[190:191]
	v_pk_fma_f32 v[160:161], v[152:153], v[188:189], v[190:191]
	v_pk_fma_f32 v[162:163], v[154:155], v[188:189], v[190:191]
	v_pk_fma_f32 v[156:157], v[156:157], v[148:149], v[192:193]
	v_pk_fma_f32 v[158:159], v[158:159], v[150:151], v[192:193]
	v_pk_fma_f32 v[160:161], v[160:161], v[152:153], v[192:193]
	v_pk_fma_f32 v[162:163], v[162:163], v[154:155], v[192:193]
	v_pk_fma_f32 v[156:157], v[156:157], v[148:149], v[194:195]
	v_pk_fma_f32 v[158:159], v[158:159], v[150:151], v[194:195]
	v_pk_fma_f32 v[160:161], v[160:161], v[152:153], v[194:195]
	v_pk_fma_f32 v[162:163], v[162:163], v[154:155], v[194:195]
	v_pk_fma_f32 v[156:157], v[156:157], v[148:149], v[196:197]
	v_pk_fma_f32 v[158:159], v[158:159], v[150:151], v[196:197]
	v_pk_fma_f32 v[160:161], v[160:161], v[152:153], v[196:197]
	v_pk_fma_f32 v[162:163], v[162:163], v[154:155], v[196:197]
	v_pk_mul_f32 v[156:157], v[156:157], v[148:149]
	v_pk_mul_f32 v[158:159], v[158:159], v[150:151]
	v_pk_mul_f32 v[160:161], v[160:161], v[152:153]
	v_pk_mul_f32 v[162:163], v[162:163], v[154:155]
	v_pk_mul_f32 v[164:165], v[120:121], v[120:121]
	v_pk_mul_f32 v[166:167], v[122:123], v[122:123]
	v_pk_mul_f32 v[168:169], v[124:125], v[124:125]
	v_pk_mul_f32 v[170:171], v[126:127], v[126:127]
	v_pk_mul_f32 v[164:165], v[164:165], v[198:199]
	v_pk_mul_f32 v[166:167], v[166:167], v[198:199]
	v_pk_mul_f32 v[168:169], v[168:169], v[198:199]
	v_pk_mul_f32 v[170:171], v[170:171], v[198:199]
	v_exp_f32_e32 v164, v164
	v_exp_f32_e32 v165, v165
	v_exp_f32_e32 v166, v166
	v_exp_f32_e32 v167, v167
	v_exp_f32_e32 v168, v168
	v_exp_f32_e32 v169, v169
	v_exp_f32_e32 v170, v170
	v_exp_f32_e32 v171, v171
	v_pk_mul_f32 v[156:157], v[156:157], v[164:165]
	v_pk_mul_f32 v[158:159], v[158:159], v[166:167]
	v_pk_mul_f32 v[160:161], v[160:161], v[168:169]
	v_pk_mul_f32 v[162:163], v[162:163], v[170:171]
	v_pk_mul_f32 v[156:157], v[128:129], v[156:157]
	v_pk_mul_f32 v[158:159], v[130:131], v[158:159]
	v_pk_mul_f32 v[160:161], v[132:133], v[160:161]
	v_pk_mul_f32 v[162:163], v[134:135], v[162:163]
	v_max_f32_e32 v172, 0, v120
	v_max_f32_e32 v173, 0, v121
	v_max_f32_e32 v174, 0, v122
	v_max_f32_e32 v175, 0, v123
	v_max_f32_e32 v176, 0, v124
	v_max_f32_e32 v177, 0, v125
	v_max_f32_e32 v178, 0, v126
	v_max_f32_e32 v179, 0, v127
	v_pk_add_f32 v[172:173], v[172:173], v[156:157] neg_lo:[0,1] neg_hi:[0,1]
	v_pk_add_f32 v[174:175], v[174:175], v[158:159] neg_lo:[0,1] neg_hi:[0,1]
	v_pk_add_f32 v[176:177], v[176:177], v[160:161] neg_lo:[0,1] neg_hi:[0,1]
	v_pk_add_f32 v[178:179], v[178:179], v[162:163] neg_lo:[0,1] neg_hi:[0,1]
	v_pk_mul_f32 v[172:173], v[172:173], v[112:113]
	v_pk_mul_f32 v[174:175], v[174:175], v[114:115]
	v_pk_mul_f32 v[176:177], v[176:177], v[116:117]
	v_pk_mul_f32 v[178:179], v[178:179], v[118:119]
	v_cvt_pk_bf16_f32 v180, v172, v173
	v_cvt_pk_bf16_f32 v181, v174, v175
	v_cvt_pk_bf16_f32 v182, v176, v177
	v_cvt_pk_bf16_f32 v183, v178, v179
	global_store_dwordx2 v218, v[180:181], s[10:11]
	global_store_dwordx2 v219, v[182:183], s[10:11]
	v_add_u32_e32 v210, 0x2c00, v210
	v_add_u32_e32 v211, 0x2c00, v210
	v_add_u32_e32 v212, v206, v211
	global_load_dwordx2 v[96:97], v212, s[6:7]
	v_add_u32_e32 v213, v207, v211
	global_load_dwordx2 v[98:99], v213, s[6:7]
	v_add_u32_e32 v214, v208, v211
	global_load_dwordx2 v[100:101], v214, s[6:7]
	v_add_u32_e32 v215, v209, v211
	global_load_dwordx2 v[102:103], v215, s[6:7]
	v_add_u32_e32 v218, v207, v210
	global_load_dwordx2 v[108:109], v218, s[8:9]
	v_add_u32_e32 v219, v208, v210
	global_load_dwordx2 v[110:111], v219, s[8:9]
	s_waitcnt vmcnt(8)
	v_lshlrev_b32_e32 v40, 16, v88
	v_and_b32_e32 v41, 0xffff0000, v88
	v_lshlrev_b32_e32 v42, 16, v89
	v_and_b32_e32 v43, 0xffff0000, v89
	v_lshlrev_b32_e32 v44, 16, v90
	v_and_b32_e32 v45, 0xffff0000, v90
	v_lshlrev_b32_e32 v46, 16, v91
	v_and_b32_e32 v47, 0xffff0000, v91
	v_lshlrev_b32_e32 v48, 16, v92
	v_and_b32_e32 v49, 0xffff0000, v92
	v_lshlrev_b32_e32 v50, 16, v93
	v_and_b32_e32 v51, 0xffff0000, v93
	v_lshlrev_b32_e32 v52, 16, v94
	v_and_b32_e32 v53, 0xffff0000, v94
	v_lshlrev_b32_e32 v54, 16, v95
	v_and_b32_e32 v55, 0xffff0000, v95
	v_pk_mul_f32 v[40:41], v[40:41], v[200:201]
	v_pk_mul_f32 v[42:43], v[42:43], v[200:201]
	v_pk_mul_f32 v[52:53], v[52:53], v[202:203]
	v_pk_mul_f32 v[54:55], v[54:55], v[202:203]
	v_lshlrev_b32_e32 v112, 16, v104
	v_and_b32_e32 v113, 0xffff0000, v104
	v_lshlrev_b32_e32 v114, 16, v105
	v_and_b32_e32 v115, 0xffff0000, v105
	v_lshlrev_b32_e32 v116, 16, v106
	v_and_b32_e32 v117, 0xffff0000, v106
	v_lshlrev_b32_e32 v118, 16, v107
	v_and_b32_e32 v119, 0xffff0000, v107
	v_pk_fma_f32 v[120:121], v[56:57], v[0:1], v[36:37]
	v_pk_fma_f32 v[122:123], v[58:59], v[2:3], v[38:39]
	v_pk_fma_f32 v[124:125], v[60:61], v[0:1], v[36:37]
	v_pk_fma_f32 v[126:127], v[62:63], v[2:3], v[38:39]
	v_pk_fma_f32 v[120:121], v[72:73], v[4:5], v[120:121]
	v_pk_fma_f32 v[122:123], v[74:75], v[6:7], v[122:123]
	v_pk_fma_f32 v[124:125], v[76:77], v[4:5], v[124:125]
	v_pk_fma_f32 v[126:127], v[78:79], v[6:7], v[126:127]
	v_pk_fma_f32 v[120:121], v[40:41], v[8:9], v[120:121]
	v_pk_fma_f32 v[122:123], v[42:43], v[10:11], v[122:123]
	v_pk_fma_f32 v[124:125], v[44:45], v[8:9], v[124:125]
	v_pk_fma_f32 v[126:127], v[46:47], v[10:11], v[126:127]
	v_pk_fma_f32 v[120:121], v[60:61], v[12:13], v[120:121]
	v_pk_fma_f32 v[122:123], v[62:63], v[14:15], v[122:123]
	v_pk_fma_f32 v[124:125], v[64:65], v[12:13], v[124:125]
	v_pk_fma_f32 v[126:127], v[66:67], v[14:15], v[126:127]
	v_pk_fma_f32 v[120:121], v[76:77], v[16:17], v[120:121]
; __device__ __forceinline__ unsigned cvt_pk_bf16(float lo, float hi) { unsigned r; asm volatile("v_cvt_pk_bf16_f32 %0, %1, %2" : "=v"(r) : "v"(lo), "v"(hi)); return r; }
; __device__ __forceinline__ float gelu_as(float v) {
;   const float av = fabsf(v); const float t = __builtin_amdgcn_rcpf(av * 0.2316418882f + 1.0f);
;   float q = t * 0.5307027145f + (-0.7265760135f); q = q * t + 0.7107068705f; q = q * t + (-0.142248368f); q = q * t + 0.127414796f; q = q * t;
;   const float e = __builtin_amdgcn_exp2f((v * v) * (-0.72134752044f));
;   const float m = v * (q * e);
;   return v < 0.f ? m : v - m;
; }
; __device__ __forceinline__ void phase_conv(KP p, int l, int tid) {
;     ...
;             o[k] = gelu_as(a) * uv[k];
;           }
;           u32x2 ow; ow.x = cvt_pk_bf16(o[0], o[1]); ow.y = cvt_pk_bf16(o[2], o[3]);
;           *(u32x2*)(G + (size_t)((r0 + rr) * 64 + jb + q) * DFF + c0) = ow;
	v_pk_fma_f32 v[122:123], v[78:79], v[18:19], v[122:123]
	v_pk_fma_f32 v[124:125], v[80:81], v[16:17], v[124:125]
	v_pk_fma_f32 v[126:127], v[82:83], v[18:19], v[126:127]
	v_pk_fma_f32 v[120:121], v[44:45], v[20:21], v[120:121]
	v_pk_fma_f32 v[122:123], v[46:47], v[22:23], v[122:123]
	v_pk_fma_f32 v[124:125], v[48:49], v[20:21], v[124:125]
	v_pk_fma_f32 v[126:127], v[50:51], v[22:23], v[126:127]
	v_pk_fma_f32 v[120:121], v[64:65], v[24:25], v[120:121]
	v_pk_fma_f32 v[122:123], v[66:67], v[26:27], v[122:123]
	v_pk_fma_f32 v[124:125], v[68:69], v[24:25], v[124:125]
	v_pk_fma_f32 v[126:127], v[70:71], v[26:27], v[126:127]
	v_pk_fma_f32 v[120:121], v[80:81], v[28:29], v[120:121]
	v_pk_fma_f32 v[122:123], v[82:83], v[30:31], v[122:123]
	v_pk_fma_f32 v[124:125], v[84:85], v[28:29], v[124:125]
	v_pk_fma_f32 v[126:127], v[86:87], v[30:31], v[126:127]
	v_pk_fma_f32 v[120:121], v[48:49], v[32:33], v[120:121]
	v_pk_fma_f32 v[122:123], v[50:51], v[34:35], v[122:123]
	v_pk_fma_f32 v[124:125], v[52:53], v[32:33], v[124:125]
	v_pk_fma_f32 v[126:127], v[54:55], v[34:35], v[126:127]
	v_and_b32_e32 v128, 0x7fffffff, v120
	v_and_b32_e32 v129, 0x7fffffff, v121
	v_and_b32_e32 v130, 0x7fffffff, v122
	v_and_b32_e32 v131, 0x7fffffff, v123
	v_and_b32_e32 v132, 0x7fffffff, v124
	v_and_b32_e32 v133, 0x7fffffff, v125
	v_and_b32_e32 v134, 0x7fffffff, v126
	v_and_b32_e32 v135, 0x7fffffff, v127
	v_pk_fma_f32 v[148:149], v[128:129], v[184:185], v[186:187]
	v_pk_fma_f32 v[150:151], v[130:131], v[184:185], v[186:187]
	v_pk_fma_f32 v[152:153], v[132:133], v[184:185], v[186:187]
	v_pk_fma_f32 v[154:155], v[134:135], v[184:185], v[186:187]
	v_rcp_f32_e32 v148, v148
	v_rcp_f32_e32 v149, v149
	v_rcp_f32_e32 v150, v150
	v_rcp_f32_e32 v151, v151
	v_rcp_f32_e32 v152, v152
	v_rcp_f32_e32 v153, v153
	v_rcp_f32_e32 v154, v154
	v_rcp_f32_e32 v155, v155
	v_pk_fma_f32 v[156:157], v[148:149], v[188:189], v[190:191]
	v_pk_fma_f32 v[158:159], v[150:151], v[188:189], v[190:191]
	v_pk_fma_f32 v[160:161], v[152:153], v[188:189], v[190:191]
	v_pk_fma_f32 v[162:163], v[154:155], v[188:189], v[190:191]
	v_pk_fma_f32 v[156:157], v[156:157], v[148:149], v[192:193]
	v_pk_fma_f32 v[158:159], v[158:159], v[150:151], v[192:193]
	v_pk_fma_f32 v[160:161], v[160:161], v[152:153], v[192:193]
	v_pk_fma_f32 v[162:163], v[162:163], v[154:155], v[192:193]
	v_pk_fma_f32 v[156:157], v[156:157], v[148:149], v[194:195]
	v_pk_fma_f32 v[158:159], v[158:159], v[150:151], v[194:195]
	v_pk_fma_f32 v[160:161], v[160:161], v[152:153], v[194:195]
	v_pk_fma_f32 v[162:163], v[162:163], v[154:155], v[194:195]
	v_pk_fma_f32 v[156:157], v[156:157], v[148:149], v[196:197]
	v_pk_fma_f32 v[158:159], v[158:159], v[150:151], v[196:197]
	v_pk_fma_f32 v[160:161], v[160:161], v[152:153], v[196:197]
	v_pk_fma_f32 v[162:163], v[162:163], v[154:155], v[196:197]
	v_pk_mul_f32 v[156:157], v[156:157], v[148:149]
	v_pk_mul_f32 v[158:159], v[158:159], v[150:151]
	v_pk_mul_f32 v[160:161], v[160:161], v[152:153]
	v_pk_mul_f32 v[162:163], v[162:163], v[154:155]
	v_pk_mul_f32 v[164:165], v[120:121], v[120:121]
	v_pk_mul_f32 v[166:167], v[122:123], v[122:123]
	v_pk_mul_f32 v[168:169], v[124:125], v[124:125]
	v_pk_mul_f32 v[170:171], v[126:127], v[126:127]
	v_pk_mul_f32 v[164:165], v[164:165], v[198:199]
	v_pk_mul_f32 v[166:167], v[166:167], v[198:199]
	v_pk_mul_f32 v[168:169], v[168:169], v[198:199]
	v_pk_mul_f32 v[170:171], v[170:171], v[198:199]
	v_exp_f32_e32 v164, v164
	v_exp_f32_e32 v165, v165
	v_exp_f32_e32 v166, v166
	v_exp_f32_e32 v167, v167
	v_exp_f32_e32 v168, v168
	v_exp_f32_e32 v169, v169
	v_exp_f32_e32 v170, v170
	v_exp_f32_e32 v171, v171
	v_pk_mul_f32 v[156:157], v[156:157], v[164:165]
	v_pk_mul_f32 v[158:159], v[158:159], v[166:167]
	v_pk_mul_f32 v[160:161], v[160:161], v[168:169]
	v_pk_mul_f32 v[162:163], v[162:163], v[170:171]
	v_pk_mul_f32 v[156:157], v[128:129], v[156:157]
	v_pk_mul_f32 v[158:159], v[130:131], v[158:159]
	v_pk_mul_f32 v[160:161], v[132:133], v[160:161]
	v_pk_mul_f32 v[162:163], v[134:135], v[162:163]
	v_max_f32_e32 v172, 0, v120
	v_max_f32_e32 v173, 0, v121
	v_max_f32_e32 v174, 0, v122
	v_max_f32_e32 v175, 0, v123
	v_max_f32_e32 v176, 0, v124
	v_max_f32_e32 v177, 0, v125
	v_max_f32_e32 v178, 0, v126
	v_max_f32_e32 v179, 0, v127
	v_pk_add_f32 v[172:173], v[172:173], v[156:157] neg_lo:[0,1] neg_hi:[0,1]
	v_pk_add_f32 v[174:175], v[174:175], v[158:159] neg_lo:[0,1] neg_hi:[0,1]
	v_pk_add_f32 v[176:177], v[176:177], v[160:161] neg_lo:[0,1] neg_hi:[0,1]
	v_pk_add_f32 v[178:179], v[178:179], v[162:163] neg_lo:[0,1] neg_hi:[0,1]
	v_pk_mul_f32 v[172:173], v[172:173], v[112:113]
	v_pk_mul_f32 v[174:175], v[174:175], v[114:115]
	v_pk_mul_f32 v[176:177], v[176:177], v[116:117]
	v_pk_mul_f32 v[178:179], v[178:179], v[118:119]
	v_cvt_pk_bf16_f32 v180, v172, v173
	v_cvt_pk_bf16_f32 v181, v174, v175
	v_cvt_pk_bf16_f32 v182, v176, v177
	v_cvt_pk_bf16_f32 v183, v178, v179
	global_store_dwordx2 v216, v[180:181], s[10:11]
	global_store_dwordx2 v217, v[182:183], s[10:11]
	v_add_u32_e32 v210, 0x2c00, v210
	v_add_u32_e32 v211, 0x2c00, v210
	v_add_u32_e32 v212, v206, v211
	global_load_dwordx2 v[88:89], v212, s[6:7]
	v_add_u32_e32 v213, v207, v211
	global_load_dwordx2 v[90:91], v213, s[6:7]
	v_add_u32_e32 v214, v208, v211
	global_load_dwordx2 v[92:93], v214, s[6:7]
	v_add_u32_e32 v215, v209, v211
	global_load_dwordx2 v[94:95], v215, s[6:7]
	v_add_u32_e32 v216, v207, v210
	global_load_dwordx2 v[104:105], v216, s[8:9]
	v_add_u32_e32 v217, v208, v210
	global_load_dwordx2 v[106:107], v217, s[8:9]
	s_waitcnt vmcnt(8)
; __device__ __forceinline__ unsigned cvt_pk_bf16(float lo, float hi) { unsigned r; asm volatile("v_cvt_pk_bf16_f32 %0, %1, %2" : "=v"(r) : "v"(lo), "v"(hi)); return r; }
; __device__ __forceinline__ float gelu_as(float v) {
;   const float av = fabsf(v); const float t = __builtin_amdgcn_rcpf(av * 0.2316418882f + 1.0f);
;   float q = t * 0.5307027145f + (-0.7265760135f); q = q * t + 0.7107068705f; q = q * t + (-0.142248368f); q = q * t + 0.127414796f; q = q * t;
;   const float e = __builtin_amdgcn_exp2f((v * v) * (-0.72134752044f));
;   const float m = v * (q * e);
;   return v < 0.f ? m : v - m;
; }
; __device__ __forceinline__ void phase_conv(KP p, int l, int tid) {
;     ...
;     for (int jb = j0; jb < j0 + 16; jb += CB) {
;       u32x2 an[CB][RB + 2], ur[CB][RB];
; #pragma unroll
;       for (int q = 0; q < CB; ++q) { const int col = jb + q + 1; const int cl = col > 63 ? 63 : col;
; #pragma unroll
;         for (int di = 0; di < RB + 2; ++di) an[q][di] = *(const u32x2*)(rowp[di] + (size_t)cl * DFF);
; #pragma unroll
;         for (int rr = 0; rr < RB; ++rr) ur[q][rr] = *(const u32x2*)(U + (size_t)((r0 + rr) * 64 + jb + q) * DFF + c0); }
;       __builtin_amdgcn_sched_barrier(0);
; #pragma unroll
;       for (int q = 0; q < CB; ++q) {
;         const int col = jb + q + 1;
; #pragma unroll
;         for (int di = 0; di < RB + 2; ++di) { const bool ok = rv[di] && (col < 64); unpack4(an[q][di], win[2][di]);
; #pragma unroll
;           for (int k = 0; k < 4; ++k) win[2][di][k] = ok ? win[2][di][k] : 0.f; }
; #pragma unroll
;         for (int rr = 0; rr < RB; ++rr) {
;           float uv[4]; unpack4(ur[q][rr], uv);
;           float o[4];
; #pragma unroll
;           for (int k = 0; k < 4; ++k) {
;             float a = bsv[k];
; #pragma unroll
;             for (int di = 0; di < 3; ++di)
; #pragma unroll
;               for (int dj = 0; dj < 3; ++dj) a += win[dj][rr + di][k] * w[di * 3 + dj][k];
;             o[k] = gelu_as(a) * uv[k];
;           }
;           u32x2 ow; ow.x = cvt_pk_bf16(o[0], o[1]); ow.y = cvt_pk_bf16(o[2], o[3]);
;           *(u32x2*)(G + (size_t)((r0 + rr) * 64 + jb + q) * DFF + c0) = ow;
	v_lshlrev_b32_e32 v56, 16, v96
	v_and_b32_e32 v57, 0xffff0000, v96
	v_lshlrev_b32_e32 v58, 16, v97
	v_and_b32_e32 v59, 0xffff0000, v97
	v_lshlrev_b32_e32 v60, 16, v98
	v_and_b32_e32 v61, 0xffff0000, v98
	v_lshlrev_b32_e32 v62, 16, v99
	v_and_b32_e32 v63, 0xffff0000, v99
	v_lshlrev_b32_e32 v64, 16, v100
	v_and_b32_e32 v65, 0xffff0000, v100
	v_lshlrev_b32_e32 v66, 16, v101
	v_and_b32_e32 v67, 0xffff0000, v101
	v_lshlrev_b32_e32 v68, 16, v102
	v_and_b32_e32 v69, 0xffff0000, v102
	v_lshlrev_b32_e32 v70, 16, v103
	v_and_b32_e32 v71, 0xffff0000, v103
	v_pk_mul_f32 v[56:57], v[56:57], v[200:201]
	v_pk_mul_f32 v[58:59], v[58:59], v[200:201]
	v_pk_mul_f32 v[68:69], v[68:69], v[202:203]
	v_pk_mul_f32 v[70:71], v[70:71], v[202:203]
	v_lshlrev_b32_e32 v112, 16, v108
	v_and_b32_e32 v113, 0xffff0000, v108
	v_lshlrev_b32_e32 v114, 16, v109
	v_and_b32_e32 v115, 0xffff0000, v109
	v_lshlrev_b32_e32 v116, 16, v110
	v_and_b32_e32 v117, 0xffff0000, v110
	v_lshlrev_b32_e32 v118, 16, v111
	v_and_b32_e32 v119, 0xffff0000, v111
	v_pk_fma_f32 v[120:121], v[72:73], v[0:1], v[36:37]
	v_pk_fma_f32 v[122:123], v[74:75], v[2:3], v[38:39]
	v_pk_fma_f32 v[124:125], v[76:77], v[0:1], v[36:37]
	v_pk_fma_f32 v[126:127], v[78:79], v[2:3], v[38:39]
	v_pk_fma_f32 v[120:121], v[40:41], v[4:5], v[120:121]
	v_pk_fma_f32 v[122:123], v[42:43], v[6:7], v[122:123]
	v_pk_fma_f32 v[124:125], v[44:45], v[4:5], v[124:125]
	v_pk_fma_f32 v[126:127], v[46:47], v[6:7], v[126:127]
	v_pk_fma_f32 v[120:121], v[56:57], v[8:9], v[120:121]
	v_pk_fma_f32 v[122:123], v[58:59], v[10:11], v[122:123]
	v_pk_fma_f32 v[124:125], v[60:61], v[8:9], v[124:125]
	v_pk_fma_f32 v[126:127], v[62:63], v[10:11], v[126:127]
	v_pk_fma_f32 v[120:121], v[76:77], v[12:13], v[120:121]
	v_pk_fma_f32 v[122:123], v[78:79], v[14:15], v[122:123]
	v_pk_fma_f32 v[124:125], v[80:81], v[12:13], v[124:125]
	v_pk_fma_f32 v[126:127], v[82:83], v[14:15], v[126:127]
	v_pk_fma_f32 v[120:121], v[44:45], v[16:17], v[120:121]
	v_pk_fma_f32 v[122:123], v[46:47], v[18:19], v[122:123]
	v_pk_fma_f32 v[124:125], v[48:49], v[16:17], v[124:125]
	v_pk_fma_f32 v[126:127], v[50:51], v[18:19], v[126:127]
	v_pk_fma_f32 v[120:121], v[60:61], v[20:21], v[120:121]
	v_pk_fma_f32 v[122:123], v[62:63], v[22:23], v[122:123]
	v_pk_fma_f32 v[124:125], v[64:65], v[20:21], v[124:125]
	v_pk_fma_f32 v[126:127], v[66:67], v[22:23], v[126:127]
	v_pk_fma_f32 v[120:121], v[80:81], v[24:25], v[120:121]
	v_pk_fma_f32 v[122:123], v[82:83], v[26:27], v[122:123]
	v_pk_fma_f32 v[124:125], v[84:85], v[24:25], v[124:125]
	v_pk_fma_f32 v[126:127], v[86:87], v[26:27], v[126:127]
	v_pk_fma_f32 v[120:121], v[48:49], v[28:29], v[120:121]
	v_pk_fma_f32 v[122:123], v[50:51], v[30:31], v[122:123]
	v_pk_fma_f32 v[124:125], v[52:53], v[28:29], v[124:125]
	v_pk_fma_f32 v[126:127], v[54:55], v[30:31], v[126:127]
	v_pk_fma_f32 v[120:121], v[64:65], v[32:33], v[120:121]
	v_pk_fma_f32 v[122:123], v[66:67], v[34:35], v[122:123]
	v_pk_fma_f32 v[124:125], v[68:69], v[32:33], v[124:125]
	v_pk_fma_f32 v[126:127], v[70:71], v[34:35], v[126:127]
	v_and_b32_e32 v128, 0x7fffffff, v120
	v_and_b32_e32 v129, 0x7fffffff, v121
	v_and_b32_e32 v130, 0x7fffffff, v122
	v_and_b32_e32 v131, 0x7fffffff, v123
	v_and_b32_e32 v132, 0x7fffffff, v124
	v_and_b32_e32 v133, 0x7fffffff, v125
	v_and_b32_e32 v134, 0x7fffffff, v126
	v_and_b32_e32 v135, 0x7fffffff, v127
	v_pk_fma_f32 v[148:149], v[128:129], v[184:185], v[186:187]
	v_pk_fma_f32 v[150:151], v[130:131], v[184:185], v[186:187]
	v_pk_fma_f32 v[152:153], v[132:133], v[184:185], v[186:187]
	v_pk_fma_f32 v[154:155], v[134:135], v[184:185], v[186:187]
	v_rcp_f32_e32 v148, v148
	v_rcp_f32_e32 v149, v149
	v_rcp_f32_e32 v150, v150
	v_rcp_f32_e32 v151, v151
	v_rcp_f32_e32 v152, v152
	v_rcp_f32_e32 v153, v153
	v_rcp_f32_e32 v154, v154
	v_rcp_f32_e32 v155, v155
	v_pk_fma_f32 v[156:157], v[148:149], v[188:189], v[190:191]
	v_pk_fma_f32 v[158:159], v[150:151], v[188:189], v[190:191]
	v_pk_fma_f32 v[160:161], v[152:153], v[188:189], v[190:191]
	v_pk_fma_f32 v[162:163], v[154:155], v[188:189], v[190:191]
	v_pk_fma_f32 v[156:157], v[156:157], v[148:149], v[192:193]
	v_pk_fma_f32 v[158:159], v[158:159], v[150:151], v[192:193]
	v_pk_fma_f32 v[160:161], v[160:161], v[152:153], v[192:193]
	v_pk_fma_f32 v[162:163], v[162:163], v[154:155], v[192:193]
	v_pk_fma_f32 v[156:157], v[156:157], v[148:149], v[194:195]
	v_pk_fma_f32 v[158:159], v[158:159], v[150:151], v[194:195]
	v_pk_fma_f32 v[160:161], v[160:161], v[152:153], v[194:195]
	v_pk_fma_f32 v[162:163], v[162:163], v[154:155], v[194:195]
	v_pk_fma_f32 v[156:157], v[156:157], v[148:149], v[196:197]
	v_pk_fma_f32 v[158:159], v[158:159], v[150:151], v[196:197]
	v_pk_fma_f32 v[160:161], v[160:161], v[152:153], v[196:197]
	v_pk_fma_f32 v[162:163], v[162:163], v[154:155], v[196:197]
	v_pk_mul_f32 v[156:157], v[156:157], v[148:149]
	v_pk_mul_f32 v[158:159], v[158:159], v[150:151]
	v_pk_mul_f32 v[160:161], v[160:161], v[152:153]
	v_pk_mul_f32 v[162:163], v[162:163], v[154:155]
	v_pk_mul_f32 v[164:165], v[120:121], v[120:121]
	v_pk_mul_f32 v[166:167], v[122:123], v[122:123]
	v_pk_mul_f32 v[168:169], v[124:125], v[124:125]
	v_pk_mul_f32 v[170:171], v[126:127], v[126:127]
	v_pk_mul_f32 v[164:165], v[164:165], v[198:199]
	v_pk_mul_f32 v[166:167], v[166:167], v[198:199]
	v_pk_mul_f32 v[168:169], v[168:169], v[198:199]
	v_pk_mul_f32 v[170:171], v[170:171], v[198:199]
	v_exp_f32_e32 v164, v164
	v_exp_f32_e32 v165, v165
	v_exp_f32_e32 v166, v166
	v_exp_f32_e32 v167, v167
	v_exp_f32_e32 v168, v168
	v_exp_f32_e32 v169, v169
	v_exp_f32_e32 v170, v170
	v_exp_f32_e32 v171, v171
	v_pk_mul_f32 v[156:157], v[156:157], v[164:165]
; __device__ __forceinline__ unsigned cvt_pk_bf16(float lo, float hi) { unsigned r; asm volatile("v_cvt_pk_bf16_f32 %0, %1, %2" : "=v"(r) : "v"(lo), "v"(hi)); return r; }
; __device__ __forceinline__ float gelu_as(float v) {
;   const float av = fabsf(v); const float t = __builtin_amdgcn_rcpf(av * 0.2316418882f + 1.0f);
;   float q = t * 0.5307027145f + (-0.7265760135f); q = q * t + 0.7107068705f; q = q * t + (-0.142248368f); q = q * t + 0.127414796f; q = q * t;
;   const float e = __builtin_amdgcn_exp2f((v * v) * (-0.72134752044f));
;   const float m = v * (q * e);
;   return v < 0.f ? m : v - m;
; }
; __device__ __forceinline__ void phase_conv(KP p, int l, int tid) {
;     ...
;     for (int jb = j0; jb < j0 + 16; jb += CB) {
;       u32x2 an[CB][RB + 2], ur[CB][RB];
; #pragma unroll
;       for (int q = 0; q < CB; ++q) { const int col = jb + q + 1; const int cl = col > 63 ? 63 : col;
; #pragma unroll
;         for (int di = 0; di < RB + 2; ++di) an[q][di] = *(const u32x2*)(rowp[di] + (size_t)cl * DFF);
; #pragma unroll
;         for (int rr = 0; rr < RB; ++rr) ur[q][rr] = *(const u32x2*)(U + (size_t)((r0 + rr) * 64 + jb + q) * DFF + c0); }
;       __builtin_amdgcn_sched_barrier(0);
; #pragma unroll
;       for (int q = 0; q < CB; ++q) {
;         const int col = jb + q + 1;
; #pragma unroll
;         for (int di = 0; di < RB + 2; ++di) { const bool ok = rv[di] && (col < 64); unpack4(an[q][di], win[2][di]);
; #pragma unroll
;           for (int k = 0; k < 4; ++k) win[2][di][k] = ok ? win[2][di][k] : 0.f; }
; #pragma unroll
;         for (int rr = 0; rr < RB; ++rr) {
;           float uv[4]; unpack4(ur[q][rr], uv);
;           float o[4];
; #pragma unroll
;           for (int k = 0; k < 4; ++k) {
;             float a = bsv[k];
; #pragma unroll
;             for (int di = 0; di < 3; ++di)
; #pragma unroll
;               for (int dj = 0; dj < 3; ++dj) a += win[dj][rr + di][k] * w[di * 3 + dj][k];
;             o[k] = gelu_as(a) * uv[k];
;           }
;           u32x2 ow; ow.x = cvt_pk_bf16(o[0], o[1]); ow.y = cvt_pk_bf16(o[2], o[3]);
;           *(u32x2*)(G + (size_t)((r0 + rr) * 64 + jb + q) * DFF + c0) = ow;
	v_pk_mul_f32 v[158:159], v[158:159], v[166:167]
	v_pk_mul_f32 v[160:161], v[160:161], v[168:169]
	v_pk_mul_f32 v[162:163], v[162:163], v[170:171]
	v_pk_mul_f32 v[156:157], v[128:129], v[156:157]
	v_pk_mul_f32 v[158:159], v[130:131], v[158:159]
	v_pk_mul_f32 v[160:161], v[132:133], v[160:161]
	v_pk_mul_f32 v[162:163], v[134:135], v[162:163]
	v_max_f32_e32 v172, 0, v120
	v_max_f32_e32 v173, 0, v121
	v_max_f32_e32 v174, 0, v122
	v_max_f32_e32 v175, 0, v123
	v_max_f32_e32 v176, 0, v124
	v_max_f32_e32 v177, 0, v125
	v_max_f32_e32 v178, 0, v126
	v_max_f32_e32 v179, 0, v127
	v_pk_add_f32 v[172:173], v[172:173], v[156:157] neg_lo:[0,1] neg_hi:[0,1]
	v_pk_add_f32 v[174:175], v[174:175], v[158:159] neg_lo:[0,1] neg_hi:[0,1]
	v_pk_add_f32 v[176:177], v[176:177], v[160:161] neg_lo:[0,1] neg_hi:[0,1]
	v_pk_add_f32 v[178:179], v[178:179], v[162:163] neg_lo:[0,1] neg_hi:[0,1]
	v_pk_mul_f32 v[172:173], v[172:173], v[112:113]
	v_pk_mul_f32 v[174:175], v[174:175], v[114:115]
	v_pk_mul_f32 v[176:177], v[176:177], v[116:117]
	v_pk_mul_f32 v[178:179], v[178:179], v[118:119]
	v_cvt_pk_bf16_f32 v180, v172, v173
	v_cvt_pk_bf16_f32 v181, v174, v175
	v_cvt_pk_bf16_f32 v182, v176, v177
	v_cvt_pk_bf16_f32 v183, v178, v179
	global_store_dwordx2 v218, v[180:181], s[10:11]
	global_store_dwordx2 v219, v[182:183], s[10:11]
	v_add_u32_e32 v210, 0x2c00, v210
	v_add_u32_e32 v211, 0x2c00, v210
	v_add_u32_e32 v212, v206, v211
	global_load_dwordx2 v[96:97], v212, s[6:7]
	v_add_u32_e32 v213, v207, v211
	global_load_dwordx2 v[98:99], v213, s[6:7]
	v_add_u32_e32 v214, v208, v211
	global_load_dwordx2 v[100:101], v214, s[6:7]
	v_add_u32_e32 v215, v209, v211
	global_load_dwordx2 v[102:103], v215, s[6:7]
	v_add_u32_e32 v218, v207, v210
	global_load_dwordx2 v[108:109], v218, s[8:9]
	v_add_u32_e32 v219, v208, v210
	global_load_dwordx2 v[110:111], v219, s[8:9]
	s_waitcnt vmcnt(8)
	v_lshlrev_b32_e32 v72, 16, v88
	v_and_b32_e32 v73, 0xffff0000, v88
	v_lshlrev_b32_e32 v74, 16, v89
	v_and_b32_e32 v75, 0xffff0000, v89
	v_lshlrev_b32_e32 v76, 16, v90
	v_and_b32_e32 v77, 0xffff0000, v90
	v_lshlrev_b32_e32 v78, 16, v91
	v_and_b32_e32 v79, 0xffff0000, v91
	v_lshlrev_b32_e32 v80, 16, v92
	v_and_b32_e32 v81, 0xffff0000, v92
	v_lshlrev_b32_e32 v82, 16, v93
	v_and_b32_e32 v83, 0xffff0000, v93
	v_lshlrev_b32_e32 v84, 16, v94
	v_and_b32_e32 v85, 0xffff0000, v94
	v_lshlrev_b32_e32 v86, 16, v95
	v_and_b32_e32 v87, 0xffff0000, v95
	v_pk_mul_f32 v[72:73], v[72:73], v[200:201]
	v_pk_mul_f32 v[74:75], v[74:75], v[200:201]
	v_pk_mul_f32 v[84:85], v[84:85], v[202:203]
	v_pk_mul_f32 v[86:87], v[86:87], v[202:203]
	v_lshlrev_b32_e32 v112, 16, v104
	v_and_b32_e32 v113, 0xffff0000, v104
	v_lshlrev_b32_e32 v114, 16, v105
	v_and_b32_e32 v115, 0xffff0000, v105
	v_lshlrev_b32_e32 v116, 16, v106
	v_and_b32_e32 v117, 0xffff0000, v106
	v_lshlrev_b32_e32 v118, 16, v107
	v_and_b32_e32 v119, 0xffff0000, v107
	v_pk_fma_f32 v[120:121], v[40:41], v[0:1], v[36:37]
	v_pk_fma_f32 v[122:123], v[42:43], v[2:3], v[38:39]
	v_pk_fma_f32 v[124:125], v[44:45], v[0:1], v[36:37]
	v_pk_fma_f32 v[126:127], v[46:47], v[2:3], v[38:39]
	v_pk_fma_f32 v[120:121], v[56:57], v[4:5], v[120:121]
	v_pk_fma_f32 v[122:123], v[58:59], v[6:7], v[122:123]
	v_pk_fma_f32 v[124:125], v[60:61], v[4:5], v[124:125]
	v_pk_fma_f32 v[126:127], v[62:63], v[6:7], v[126:127]
	v_pk_fma_f32 v[120:121], v[72:73], v[8:9], v[120:121]
	v_pk_fma_f32 v[122:123], v[74:75], v[10:11], v[122:123]
	v_pk_fma_f32 v[124:125], v[76:77], v[8:9], v[124:125]
	v_pk_fma_f32 v[126:127], v[78:79], v[10:11], v[126:127]
	v_pk_fma_f32 v[120:121], v[44:45], v[12:13], v[120:121]
	v_pk_fma_f32 v[122:123], v[46:47], v[14:15], v[122:123]
	v_pk_fma_f32 v[124:125], v[48:49], v[12:13], v[124:125]
	v_pk_fma_f32 v[126:127], v[50:51], v[14:15], v[126:127]
	v_pk_fma_f32 v[120:121], v[60:61], v[16:17], v[120:121]
	v_pk_fma_f32 v[122:123], v[62:63], v[18:19], v[122:123]
	v_pk_fma_f32 v[124:125], v[64:65], v[16:17], v[124:125]
	v_pk_fma_f32 v[126:127], v[66:67], v[18:19], v[126:127]
	v_pk_fma_f32 v[120:121], v[76:77], v[20:21], v[120:121]
	v_pk_fma_f32 v[122:123], v[78:79], v[22:23], v[122:123]
	v_pk_fma_f32 v[124:125], v[80:81], v[20:21], v[124:125]
	v_pk_fma_f32 v[126:127], v[82:83], v[22:23], v[126:127]
	v_pk_fma_f32 v[120:121], v[48:49], v[24:25], v[120:121]
	v_pk_fma_f32 v[122:123], v[50:51], v[26:27], v[122:123]
	v_pk_fma_f32 v[124:125], v[52:53], v[24:25], v[124:125]
	v_pk_fma_f32 v[126:127], v[54:55], v[26:27], v[126:127]
	v_pk_fma_f32 v[120:121], v[64:65], v[28:29], v[120:121]
	v_pk_fma_f32 v[122:123], v[66:67], v[30:31], v[122:123]
	v_pk_fma_f32 v[124:125], v[68:69], v[28:29], v[124:125]
	v_pk_fma_f32 v[126:127], v[70:71], v[30:31], v[126:127]
	v_pk_fma_f32 v[120:121], v[80:81], v[32:33], v[120:121]
	v_pk_fma_f32 v[122:123], v[82:83], v[34:35], v[122:123]
	v_pk_fma_f32 v[124:125], v[84:85], v[32:33], v[124:125]
	v_pk_fma_f32 v[126:127], v[86:87], v[34:35], v[126:127]
	v_and_b32_e32 v128, 0x7fffffff, v120
	v_and_b32_e32 v129, 0x7fffffff, v121
	v_and_b32_e32 v130, 0x7fffffff, v122
	v_and_b32_e32 v131, 0x7fffffff, v123
	v_and_b32_e32 v132, 0x7fffffff, v124
	v_and_b32_e32 v133, 0x7fffffff, v125
	v_and_b32_e32 v134, 0x7fffffff, v126
	v_and_b32_e32 v135, 0x7fffffff, v127
	v_pk_fma_f32 v[148:149], v[128:129], v[184:185], v[186:187]
	v_pk_fma_f32 v[150:151], v[130:131], v[184:185], v[186:187]
	v_pk_fma_f32 v[152:153], v[132:133], v[184:185], v[186:187]
	v_pk_fma_f32 v[154:155], v[134:135], v[184:185], v[186:187]
	v_rcp_f32_e32 v148, v148
	v_rcp_f32_e32 v149, v149
	v_rcp_f32_e32 v150, v150
	v_rcp_f32_e32 v151, v151
	v_rcp_f32_e32 v152, v152
	v_rcp_f32_e32 v153, v153
	v_rcp_f32_e32 v154, v154
; __device__ __forceinline__ unsigned cvt_pk_bf16(float lo, float hi) { unsigned r; asm volatile("v_cvt_pk_bf16_f32 %0, %1, %2" : "=v"(r) : "v"(lo), "v"(hi)); return r; }
; __device__ __forceinline__ float gelu_as(float v) {
;   const float av = fabsf(v); const float t = __builtin_amdgcn_rcpf(av * 0.2316418882f + 1.0f);
;   float q = t * 0.5307027145f + (-0.7265760135f); q = q * t + 0.7107068705f; q = q * t + (-0.142248368f); q = q * t + 0.127414796f; q = q * t;
;   const float e = __builtin_amdgcn_exp2f((v * v) * (-0.72134752044f));
;   const float m = v * (q * e);
;   return v < 0.f ? m : v - m;
; }
; __device__ __forceinline__ void phase_conv(KP p, int l, int tid) {
;     ...
;     for (int jb = j0; jb < j0 + 16; jb += CB) {
;       u32x2 an[CB][RB + 2], ur[CB][RB];
; #pragma unroll
;       for (int q = 0; q < CB; ++q) { const int col = jb + q + 1; const int cl = col > 63 ? 63 : col;
; #pragma unroll
;         for (int di = 0; di < RB + 2; ++di) an[q][di] = *(const u32x2*)(rowp[di] + (size_t)cl * DFF);
; #pragma unroll
;         for (int rr = 0; rr < RB; ++rr) ur[q][rr] = *(const u32x2*)(U + (size_t)((r0 + rr) * 64 + jb + q) * DFF + c0); }
;       __builtin_amdgcn_sched_barrier(0);
; #pragma unroll
;       for (int q = 0; q < CB; ++q) {
;         const int col = jb + q + 1;
; #pragma unroll
;         for (int di = 0; di < RB + 2; ++di) { const bool ok = rv[di] && (col < 64); unpack4(an[q][di], win[2][di]);
; #pragma unroll
;           for (int k = 0; k < 4; ++k) win[2][di][k] = ok ? win[2][di][k] : 0.f; }
; #pragma unroll
;         for (int rr = 0; rr < RB; ++rr) {
;           float uv[4]; unpack4(ur[q][rr], uv);
;           float o[4];
; #pragma unroll
;           for (int k = 0; k < 4; ++k) {
;             float a = bsv[k];
; #pragma unroll
;             for (int di = 0; di < 3; ++di)
; #pragma unroll
;               for (int dj = 0; dj < 3; ++dj) a += win[dj][rr + di][k] * w[di * 3 + dj][k];
;             o[k] = gelu_as(a) * uv[k];
;           }
;           u32x2 ow; ow.x = cvt_pk_bf16(o[0], o[1]); ow.y = cvt_pk_bf16(o[2], o[3]);
;           *(u32x2*)(G + (size_t)((r0 + rr) * 64 + jb + q) * DFF + c0) = ow;
	v_rcp_f32_e32 v155, v155
	v_pk_fma_f32 v[156:157], v[148:149], v[188:189], v[190:191]
	v_pk_fma_f32 v[158:159], v[150:151], v[188:189], v[190:191]
	v_pk_fma_f32 v[160:161], v[152:153], v[188:189], v[190:191]
	v_pk_fma_f32 v[162:163], v[154:155], v[188:189], v[190:191]
	v_pk_fma_f32 v[156:157], v[156:157], v[148:149], v[192:193]
	v_pk_fma_f32 v[158:159], v[158:159], v[150:151], v[192:193]
	v_pk_fma_f32 v[160:161], v[160:161], v[152:153], v[192:193]
	v_pk_fma_f32 v[162:163], v[162:163], v[154:155], v[192:193]
	v_pk_fma_f32 v[156:157], v[156:157], v[148:149], v[194:195]
	v_pk_fma_f32 v[158:159], v[158:159], v[150:151], v[194:195]
	v_pk_fma_f32 v[160:161], v[160:161], v[152:153], v[194:195]
	v_pk_fma_f32 v[162:163], v[162:163], v[154:155], v[194:195]
	v_pk_fma_f32 v[156:157], v[156:157], v[148:149], v[196:197]
	v_pk_fma_f32 v[158:159], v[158:159], v[150:151], v[196:197]
	v_pk_fma_f32 v[160:161], v[160:161], v[152:153], v[196:197]
	v_pk_fma_f32 v[162:163], v[162:163], v[154:155], v[196:197]
	v_pk_mul_f32 v[156:157], v[156:157], v[148:149]
	v_pk_mul_f32 v[158:159], v[158:159], v[150:151]
	v_pk_mul_f32 v[160:161], v[160:161], v[152:153]
	v_pk_mul_f32 v[162:163], v[162:163], v[154:155]
	v_pk_mul_f32 v[164:165], v[120:121], v[120:121]
	v_pk_mul_f32 v[166:167], v[122:123], v[122:123]
	v_pk_mul_f32 v[168:169], v[124:125], v[124:125]
	v_pk_mul_f32 v[170:171], v[126:127], v[126:127]
	v_pk_mul_f32 v[164:165], v[164:165], v[198:199]
	v_pk_mul_f32 v[166:167], v[166:167], v[198:199]
	v_pk_mul_f32 v[168:169], v[168:169], v[198:199]
	v_pk_mul_f32 v[170:171], v[170:171], v[198:199]
	v_exp_f32_e32 v164, v164
	v_exp_f32_e32 v165, v165
	v_exp_f32_e32 v166, v166
	v_exp_f32_e32 v167, v167
	v_exp_f32_e32 v168, v168
	v_exp_f32_e32 v169, v169
	v_exp_f32_e32 v170, v170
	v_exp_f32_e32 v171, v171
	v_pk_mul_f32 v[156:157], v[156:157], v[164:165]
	v_pk_mul_f32 v[158:159], v[158:159], v[166:167]
	v_pk_mul_f32 v[160:161], v[160:161], v[168:169]
	v_pk_mul_f32 v[162:163], v[162:163], v[170:171]
	v_pk_mul_f32 v[156:157], v[128:129], v[156:157]
	v_pk_mul_f32 v[158:159], v[130:131], v[158:159]
	v_pk_mul_f32 v[160:161], v[132:133], v[160:161]
	v_pk_mul_f32 v[162:163], v[134:135], v[162:163]
	v_max_f32_e32 v172, 0, v120
	v_max_f32_e32 v173, 0, v121
	v_max_f32_e32 v174, 0, v122
	v_max_f32_e32 v175, 0, v123
	v_max_f32_e32 v176, 0, v124
	v_max_f32_e32 v177, 0, v125
	v_max_f32_e32 v178, 0, v126
	v_max_f32_e32 v179, 0, v127
	v_pk_add_f32 v[172:173], v[172:173], v[156:157] neg_lo:[0,1] neg_hi:[0,1]
	v_pk_add_f32 v[174:175], v[174:175], v[158:159] neg_lo:[0,1] neg_hi:[0,1]
	v_pk_add_f32 v[176:177], v[176:177], v[160:161] neg_lo:[0,1] neg_hi:[0,1]
	v_pk_add_f32 v[178:179], v[178:179], v[162:163] neg_lo:[0,1] neg_hi:[0,1]
	v_pk_mul_f32 v[172:173], v[172:173], v[112:113]
	v_pk_mul_f32 v[174:175], v[174:175], v[114:115]
	v_pk_mul_f32 v[176:177], v[176:177], v[116:117]
	v_pk_mul_f32 v[178:179], v[178:179], v[118:119]
	v_cvt_pk_bf16_f32 v180, v172, v173
	v_cvt_pk_bf16_f32 v181, v174, v175
	v_cvt_pk_bf16_f32 v182, v176, v177
	v_cvt_pk_bf16_f32 v183, v178, v179
	global_store_dwordx2 v216, v[180:181], s[10:11]
	global_store_dwordx2 v217, v[182:183], s[10:11]
	v_add_u32_e32 v210, 0x2c00, v210
	v_add_u32_e32 v211, 0x2c00, v210
	v_add_u32_e32 v212, v206, v211
	global_load_dwordx2 v[88:89], v212, s[6:7]
	v_add_u32_e32 v213, v207, v211
	global_load_dwordx2 v[90:91], v213, s[6:7]
	v_add_u32_e32 v214, v208, v211
	global_load_dwordx2 v[92:93], v214, s[6:7]
	v_add_u32_e32 v215, v209, v211
	global_load_dwordx2 v[94:95], v215, s[6:7]
	v_add_u32_e32 v216, v207, v210
	global_load_dwordx2 v[104:105], v216, s[8:9]
	v_add_u32_e32 v217, v208, v210
	global_load_dwordx2 v[106:107], v217, s[8:9]
	s_waitcnt vmcnt(8)
	v_lshlrev_b32_e32 v40, 16, v96
	v_and_b32_e32 v41, 0xffff0000, v96
	v_lshlrev_b32_e32 v42, 16, v97
	v_and_b32_e32 v43, 0xffff0000, v97
	v_lshlrev_b32_e32 v44, 16, v98
	v_and_b32_e32 v45, 0xffff0000, v98
	v_lshlrev_b32_e32 v46, 16, v99
	v_and_b32_e32 v47, 0xffff0000, v99
	v_lshlrev_b32_e32 v48, 16, v100
	v_and_b32_e32 v49, 0xffff0000, v100
	v_lshlrev_b32_e32 v50, 16, v101
	v_and_b32_e32 v51, 0xffff0000, v101
	v_lshlrev_b32_e32 v52, 16, v102
	v_and_b32_e32 v53, 0xffff0000, v102
	v_lshlrev_b32_e32 v54, 16, v103
	v_and_b32_e32 v55, 0xffff0000, v103
	v_pk_mul_f32 v[40:41], v[40:41], v[200:201]
	v_pk_mul_f32 v[42:43], v[42:43], v[200:201]
	v_pk_mul_f32 v[52:53], v[52:53], v[202:203]
	v_pk_mul_f32 v[54:55], v[54:55], v[202:203]
	v_lshlrev_b32_e32 v112, 16, v108
	v_and_b32_e32 v113, 0xffff0000, v108
	v_lshlrev_b32_e32 v114, 16, v109
	v_and_b32_e32 v115, 0xffff0000, v109
	v_lshlrev_b32_e32 v116, 16, v110
	v_and_b32_e32 v117, 0xffff0000, v110
	v_lshlrev_b32_e32 v118, 16, v111
	v_and_b32_e32 v119, 0xffff0000, v111
	v_pk_fma_f32 v[120:121], v[56:57], v[0:1], v[36:37]
	v_pk_fma_f32 v[122:123], v[58:59], v[2:3], v[38:39]
	v_pk_fma_f32 v[124:125], v[60:61], v[0:1], v[36:37]
	v_pk_fma_f32 v[126:127], v[62:63], v[2:3], v[38:39]
	v_pk_fma_f32 v[120:121], v[72:73], v[4:5], v[120:121]
	v_pk_fma_f32 v[122:123], v[74:75], v[6:7], v[122:123]
	v_pk_fma_f32 v[124:125], v[76:77], v[4:5], v[124:125]
	v_pk_fma_f32 v[126:127], v[78:79], v[6:7], v[126:127]
	v_pk_fma_f32 v[120:121], v[40:41], v[8:9], v[120:121]
	v_pk_fma_f32 v[122:123], v[42:43], v[10:11], v[122:123]
	v_pk_fma_f32 v[124:125], v[44:45], v[8:9], v[124:125]
	v_pk_fma_f32 v[126:127], v[46:47], v[10:11], v[126:127]
	v_pk_fma_f32 v[120:121], v[60:61], v[12:13], v[120:121]
	v_pk_fma_f32 v[122:123], v[62:63], v[14:15], v[122:123]
	v_pk_fma_f32 v[124:125], v[64:65], v[12:13], v[124:125]
	v_pk_fma_f32 v[126:127], v[66:67], v[14:15], v[126:127]
; __device__ __forceinline__ unsigned cvt_pk_bf16(float lo, float hi) { unsigned r; asm volatile("v_cvt_pk_bf16_f32 %0, %1, %2" : "=v"(r) : "v"(lo), "v"(hi)); return r; }
; __device__ __forceinline__ float gelu_as(float v) {
;   const float av = fabsf(v); const float t = __builtin_amdgcn_rcpf(av * 0.2316418882f + 1.0f);
;   float q = t * 0.5307027145f + (-0.7265760135f); q = q * t + 0.7107068705f; q = q * t + (-0.142248368f); q = q * t + 0.127414796f; q = q * t;
;   const float e = __builtin_amdgcn_exp2f((v * v) * (-0.72134752044f));
;   const float m = v * (q * e);
;   return v < 0.f ? m : v - m;
; }
; __device__ __forceinline__ void phase_conv(KP p, int l, int tid) {
;     ...
;     for (int jb = j0; jb < j0 + 16; jb += CB) {
;       u32x2 an[CB][RB + 2], ur[CB][RB];
; #pragma unroll
;       for (int q = 0; q < CB; ++q) { const int col = jb + q + 1; const int cl = col > 63 ? 63 : col;
; #pragma unroll
;         for (int di = 0; di < RB + 2; ++di) an[q][di] = *(const u32x2*)(rowp[di] + (size_t)cl * DFF);
; #pragma unroll
;         for (int rr = 0; rr < RB; ++rr) ur[q][rr] = *(const u32x2*)(U + (size_t)((r0 + rr) * 64 + jb + q) * DFF + c0); }
;       __builtin_amdgcn_sched_barrier(0);
; #pragma unroll
;       for (int q = 0; q < CB; ++q) {
;         const int col = jb + q + 1;
; #pragma unroll
;         for (int di = 0; di < RB + 2; ++di) { const bool ok = rv[di] && (col < 64); unpack4(an[q][di], win[2][di]);
; #pragma unroll
;           for (int k = 0; k < 4; ++k) win[2][di][k] = ok ? win[2][di][k] : 0.f; }
; #pragma unroll
;         for (int rr = 0; rr < RB; ++rr) {
;           float uv[4]; unpack4(ur[q][rr], uv);
;           float o[4];
; #pragma unroll
;           for (int k = 0; k < 4; ++k) {
;             float a = bsv[k];
; #pragma unroll
;             for (int di = 0; di < 3; ++di)
; #pragma unroll
;               for (int dj = 0; dj < 3; ++dj) a += win[dj][rr + di][k] * w[di * 3 + dj][k];
;             o[k] = gelu_as(a) * uv[k];
;           }
;           u32x2 ow; ow.x = cvt_pk_bf16(o[0], o[1]); ow.y = cvt_pk_bf16(o[2], o[3]);
;           *(u32x2*)(G + (size_t)((r0 + rr) * 64 + jb + q) * DFF + c0) = ow;
	v_pk_fma_f32 v[120:121], v[76:77], v[16:17], v[120:121]
	v_pk_fma_f32 v[122:123], v[78:79], v[18:19], v[122:123]
	v_pk_fma_f32 v[124:125], v[80:81], v[16:17], v[124:125]
	v_pk_fma_f32 v[126:127], v[82:83], v[18:19], v[126:127]
	v_pk_fma_f32 v[120:121], v[44:45], v[20:21], v[120:121]
	v_pk_fma_f32 v[122:123], v[46:47], v[22:23], v[122:123]
	v_pk_fma_f32 v[124:125], v[48:49], v[20:21], v[124:125]
	v_pk_fma_f32 v[126:127], v[50:51], v[22:23], v[126:127]
	v_pk_fma_f32 v[120:121], v[64:65], v[24:25], v[120:121]
	v_pk_fma_f32 v[122:123], v[66:67], v[26:27], v[122:123]
	v_pk_fma_f32 v[124:125], v[68:69], v[24:25], v[124:125]
	v_pk_fma_f32 v[126:127], v[70:71], v[26:27], v[126:127]
	v_pk_fma_f32 v[120:121], v[80:81], v[28:29], v[120:121]
	v_pk_fma_f32 v[122:123], v[82:83], v[30:31], v[122:123]
	v_pk_fma_f32 v[124:125], v[84:85], v[28:29], v[124:125]
	v_pk_fma_f32 v[126:127], v[86:87], v[30:31], v[126:127]
	v_pk_fma_f32 v[120:121], v[48:49], v[32:33], v[120:121]
	v_pk_fma_f32 v[122:123], v[50:51], v[34:35], v[122:123]
	v_pk_fma_f32 v[124:125], v[52:53], v[32:33], v[124:125]
	v_pk_fma_f32 v[126:127], v[54:55], v[34:35], v[126:127]
	v_and_b32_e32 v128, 0x7fffffff, v120
	v_and_b32_e32 v129, 0x7fffffff, v121
	v_and_b32_e32 v130, 0x7fffffff, v122
	v_and_b32_e32 v131, 0x7fffffff, v123
	v_and_b32_e32 v132, 0x7fffffff, v124
	v_and_b32_e32 v133, 0x7fffffff, v125
	v_and_b32_e32 v134, 0x7fffffff, v126
	v_and_b32_e32 v135, 0x7fffffff, v127
	v_pk_fma_f32 v[148:149], v[128:129], v[184:185], v[186:187]
	v_pk_fma_f32 v[150:151], v[130:131], v[184:185], v[186:187]
	v_pk_fma_f32 v[152:153], v[132:133], v[184:185], v[186:187]
	v_pk_fma_f32 v[154:155], v[134:135], v[184:185], v[186:187]
	v_rcp_f32_e32 v148, v148
	v_rcp_f32_e32 v149, v149
	v_rcp_f32_e32 v150, v150
	v_rcp_f32_e32 v151, v151
	v_rcp_f32_e32 v152, v152
	v_rcp_f32_e32 v153, v153
	v_rcp_f32_e32 v154, v154
	v_rcp_f32_e32 v155, v155
	v_pk_fma_f32 v[156:157], v[148:149], v[188:189], v[190:191]
	v_pk_fma_f32 v[158:159], v[150:151], v[188:189], v[190:191]
	v_pk_fma_f32 v[160:161], v[152:153], v[188:189], v[190:191]
	v_pk_fma_f32 v[162:163], v[154:155], v[188:189], v[190:191]
	v_pk_fma_f32 v[156:157], v[156:157], v[148:149], v[192:193]
	v_pk_fma_f32 v[158:159], v[158:159], v[150:151], v[192:193]
	v_pk_fma_f32 v[160:161], v[160:161], v[152:153], v[192:193]
	v_pk_fma_f32 v[162:163], v[162:163], v[154:155], v[192:193]
	v_pk_fma_f32 v[156:157], v[156:157], v[148:149], v[194:195]
	v_pk_fma_f32 v[158:159], v[158:159], v[150:151], v[194:195]
	v_pk_fma_f32 v[160:161], v[160:161], v[152:153], v[194:195]
	v_pk_fma_f32 v[162:163], v[162:163], v[154:155], v[194:195]
	v_pk_fma_f32 v[156:157], v[156:157], v[148:149], v[196:197]
	v_pk_fma_f32 v[158:159], v[158:159], v[150:151], v[196:197]
	v_pk_fma_f32 v[160:161], v[160:161], v[152:153], v[196:197]
	v_pk_fma_f32 v[162:163], v[162:163], v[154:155], v[196:197]
	v_pk_mul_f32 v[156:157], v[156:157], v[148:149]
	v_pk_mul_f32 v[158:159], v[158:159], v[150:151]
	v_pk_mul_f32 v[160:161], v[160:161], v[152:153]
	v_pk_mul_f32 v[162:163], v[162:163], v[154:155]
	v_pk_mul_f32 v[164:165], v[120:121], v[120:121]
	v_pk_mul_f32 v[166:167], v[122:123], v[122:123]
	v_pk_mul_f32 v[168:169], v[124:125], v[124:125]
	v_pk_mul_f32 v[170:171], v[126:127], v[126:127]
	v_pk_mul_f32 v[164:165], v[164:165], v[198:199]
	v_pk_mul_f32 v[166:167], v[166:167], v[198:199]
	v_pk_mul_f32 v[168:169], v[168:169], v[198:199]
	v_pk_mul_f32 v[170:171], v[170:171], v[198:199]
	v_exp_f32_e32 v164, v164
	v_exp_f32_e32 v165, v165
	v_exp_f32_e32 v166, v166
	v_exp_f32_e32 v167, v167
	v_exp_f32_e32 v168, v168
	v_exp_f32_e32 v169, v169
	v_exp_f32_e32 v170, v170
	v_exp_f32_e32 v171, v171
	v_pk_mul_f32 v[156:157], v[156:157], v[164:165]
	v_pk_mul_f32 v[158:159], v[158:159], v[166:167]
	v_pk_mul_f32 v[160:161], v[160:161], v[168:169]
	v_pk_mul_f32 v[162:163], v[162:163], v[170:171]
	v_pk_mul_f32 v[156:157], v[128:129], v[156:157]
	v_pk_mul_f32 v[158:159], v[130:131], v[158:159]
	v_pk_mul_f32 v[160:161], v[132:133], v[160:161]
	v_pk_mul_f32 v[162:163], v[134:135], v[162:163]
	v_max_f32_e32 v172, 0, v120
	v_max_f32_e32 v173, 0, v121
	v_max_f32_e32 v174, 0, v122
	v_max_f32_e32 v175, 0, v123
	v_max_f32_e32 v176, 0, v124
	v_max_f32_e32 v177, 0, v125
	v_max_f32_e32 v178, 0, v126
	v_max_f32_e32 v179, 0, v127
	v_pk_add_f32 v[172:173], v[172:173], v[156:157] neg_lo:[0,1] neg_hi:[0,1]
	v_pk_add_f32 v[174:175], v[174:175], v[158:159] neg_lo:[0,1] neg_hi:[0,1]
	v_pk_add_f32 v[176:177], v[176:177], v[160:161] neg_lo:[0,1] neg_hi:[0,1]
	v_pk_add_f32 v[178:179], v[178:179], v[162:163] neg_lo:[0,1] neg_hi:[0,1]
	v_pk_mul_f32 v[172:173], v[172:173], v[112:113]
	v_pk_mul_f32 v[174:175], v[174:175], v[114:115]
	v_pk_mul_f32 v[176:177], v[176:177], v[116:117]
	v_pk_mul_f32 v[178:179], v[178:179], v[118:119]
	v_cvt_pk_bf16_f32 v180, v172, v173
	v_cvt_pk_bf16_f32 v181, v174, v175
	v_cvt_pk_bf16_f32 v182, v176, v177
	v_cvt_pk_bf16_f32 v183, v178, v179
	global_store_dwordx2 v218, v[180:181], s[10:11]
	global_store_dwordx2 v219, v[182:183], s[10:11]
	v_add_u32_e32 v210, 0x2c00, v210
	v_add_u32_e32 v211, 0x2c00, v210
	v_add_u32_e32 v212, v206, v211
	global_load_dwordx2 v[96:97], v212, s[6:7]
	v_add_u32_e32 v213, v207, v211
	global_load_dwordx2 v[98:99], v213, s[6:7]
	v_add_u32_e32 v214, v208, v211
	global_load_dwordx2 v[100:101], v214, s[6:7]
	v_add_u32_e32 v215, v209, v211
	global_load_dwordx2 v[102:103], v215, s[6:7]
	v_add_u32_e32 v218, v207, v210
	global_load_dwordx2 v[108:109], v218, s[8:9]
	v_add_u32_e32 v219, v208, v210
	global_load_dwordx2 v[110:111], v219, s[8:9]
	s_waitcnt vmcnt(8)
; __device__ __forceinline__ unsigned cvt_pk_bf16(float lo, float hi) { unsigned r; asm volatile("v_cvt_pk_bf16_f32 %0, %1, %2" : "=v"(r) : "v"(lo), "v"(hi)); return r; }
; __device__ __forceinline__ float gelu_as(float v) {
;   const float av = fabsf(v); const float t = __builtin_amdgcn_rcpf(av * 0.2316418882f + 1.0f);
;   float q = t * 0.5307027145f + (-0.7265760135f); q = q * t + 0.7107068705f; q = q * t + (-0.142248368f); q = q * t + 0.127414796f; q = q * t;
;   const float e = __builtin_amdgcn_exp2f((v * v) * (-0.72134752044f));
;   const float m = v * (q * e);
;   return v < 0.f ? m : v - m;
; }
; __device__ __forceinline__ void phase_conv(KP p, int l, int tid) {
;     ...
;     for (int jb = j0; jb < j0 + 16; jb += CB) {
;       u32x2 an[CB][RB + 2], ur[CB][RB];
; #pragma unroll
;       for (int q = 0; q < CB; ++q) { const int col = jb + q + 1; const int cl = col > 63 ? 63 : col;
; #pragma unroll
;         for (int di = 0; di < RB + 2; ++di) an[q][di] = *(const u32x2*)(rowp[di] + (size_t)cl * DFF);
; #pragma unroll
;         for (int rr = 0; rr < RB; ++rr) ur[q][rr] = *(const u32x2*)(U + (size_t)((r0 + rr) * 64 + jb + q) * DFF + c0); }
;       __builtin_amdgcn_sched_barrier(0);
; #pragma unroll
;       for (int q = 0; q < CB; ++q) {
;         const int col = jb + q + 1;
; #pragma unroll
;         for (int di = 0; di < RB + 2; ++di) { const bool ok = rv[di] && (col < 64); unpack4(an[q][di], win[2][di]);
; #pragma unroll
;           for (int k = 0; k < 4; ++k) win[2][di][k] = ok ? win[2][di][k] : 0.f; }
; #pragma unroll
;         for (int rr = 0; rr < RB; ++rr) {
;           float uv[4]; unpack4(ur[q][rr], uv);
;           float o[4];
; #pragma unroll
;           for (int k = 0; k < 4; ++k) {
;             float a = bsv[k];
; #pragma unroll
;             for (int di = 0; di < 3; ++di)
; #pragma unroll
;               for (int dj = 0; dj < 3; ++dj) a += win[dj][rr + di][k] * w[di * 3 + dj][k];
;             o[k] = gelu_as(a) * uv[k];
;           }
;           u32x2 ow; ow.x = cvt_pk_bf16(o[0], o[1]); ow.y = cvt_pk_bf16(o[2], o[3]);
;           *(u32x2*)(G + (size_t)((r0 + rr) * 64 + jb + q) * DFF + c0) = ow;
	v_lshlrev_b32_e32 v56, 16, v88
	v_and_b32_e32 v57, 0xffff0000, v88
	v_lshlrev_b32_e32 v58, 16, v89
	v_and_b32_e32 v59, 0xffff0000, v89
	v_lshlrev_b32_e32 v60, 16, v90
	v_and_b32_e32 v61, 0xffff0000, v90
	v_lshlrev_b32_e32 v62, 16, v91
	v_and_b32_e32 v63, 0xffff0000, v91
	v_lshlrev_b32_e32 v64, 16, v92
	v_and_b32_e32 v65, 0xffff0000, v92
	v_lshlrev_b32_e32 v66, 16, v93
	v_and_b32_e32 v67, 0xffff0000, v93
	v_lshlrev_b32_e32 v68, 16, v94
	v_and_b32_e32 v69, 0xffff0000, v94
	v_lshlrev_b32_e32 v70, 16, v95
	v_and_b32_e32 v71, 0xffff0000, v95
	v_pk_mul_f32 v[56:57], v[56:57], v[200:201]
	v_pk_mul_f32 v[58:59], v[58:59], v[200:201]
	v_pk_mul_f32 v[68:69], v[68:69], v[202:203]
	v_pk_mul_f32 v[70:71], v[70:71], v[202:203]
	v_lshlrev_b32_e32 v112, 16, v104
	v_and_b32_e32 v113, 0xffff0000, v104
	v_lshlrev_b32_e32 v114, 16, v105
	v_and_b32_e32 v115, 0xffff0000, v105
	v_lshlrev_b32_e32 v116, 16, v106
	v_and_b32_e32 v117, 0xffff0000, v106
	v_lshlrev_b32_e32 v118, 16, v107
	v_and_b32_e32 v119, 0xffff0000, v107
	v_pk_fma_f32 v[120:121], v[72:73], v[0:1], v[36:37]
	v_pk_fma_f32 v[122:123], v[74:75], v[2:3], v[38:39]
	v_pk_fma_f32 v[124:125], v[76:77], v[0:1], v[36:37]
	v_pk_fma_f32 v[126:127], v[78:79], v[2:3], v[38:39]
	v_pk_fma_f32 v[120:121], v[40:41], v[4:5], v[120:121]
	v_pk_fma_f32 v[122:123], v[42:43], v[6:7], v[122:123]
	v_pk_fma_f32 v[124:125], v[44:45], v[4:5], v[124:125]
	v_pk_fma_f32 v[126:127], v[46:47], v[6:7], v[126:127]
	v_pk_fma_f32 v[120:121], v[56:57], v[8:9], v[120:121]
	v_pk_fma_f32 v[122:123], v[58:59], v[10:11], v[122:123]
	v_pk_fma_f32 v[124:125], v[60:61], v[8:9], v[124:125]
	v_pk_fma_f32 v[126:127], v[62:63], v[10:11], v[126:127]
	v_pk_fma_f32 v[120:121], v[76:77], v[12:13], v[120:121]
	v_pk_fma_f32 v[122:123], v[78:79], v[14:15], v[122:123]
	v_pk_fma_f32 v[124:125], v[80:81], v[12:13], v[124:125]
	v_pk_fma_f32 v[126:127], v[82:83], v[14:15], v[126:127]
	v_pk_fma_f32 v[120:121], v[44:45], v[16:17], v[120:121]
	v_pk_fma_f32 v[122:123], v[46:47], v[18:19], v[122:123]
	v_pk_fma_f32 v[124:125], v[48:49], v[16:17], v[124:125]
	v_pk_fma_f32 v[126:127], v[50:51], v[18:19], v[126:127]
	v_pk_fma_f32 v[120:121], v[60:61], v[20:21], v[120:121]
	v_pk_fma_f32 v[122:123], v[62:63], v[22:23], v[122:123]
	v_pk_fma_f32 v[124:125], v[64:65], v[20:21], v[124:125]
	v_pk_fma_f32 v[126:127], v[66:67], v[22:23], v[126:127]
	v_pk_fma_f32 v[120:121], v[80:81], v[24:25], v[120:121]
	v_pk_fma_f32 v[122:123], v[82:83], v[26:27], v[122:123]
	v_pk_fma_f32 v[124:125], v[84:85], v[24:25], v[124:125]
	v_pk_fma_f32 v[126:127], v[86:87], v[26:27], v[126:127]
	v_pk_fma_f32 v[120:121], v[48:49], v[28:29], v[120:121]
	v_pk_fma_f32 v[122:123], v[50:51], v[30:31], v[122:123]
	v_pk_fma_f32 v[124:125], v[52:53], v[28:29], v[124:125]
	v_pk_fma_f32 v[126:127], v[54:55], v[30:31], v[126:127]
	v_pk_fma_f32 v[120:121], v[64:65], v[32:33], v[120:121]
	v_pk_fma_f32 v[122:123], v[66:67], v[34:35], v[122:123]
	v_pk_fma_f32 v[124:125], v[68:69], v[32:33], v[124:125]
	v_pk_fma_f32 v[126:127], v[70:71], v[34:35], v[126:127]
	v_and_b32_e32 v128, 0x7fffffff, v120
	v_and_b32_e32 v129, 0x7fffffff, v121
	v_and_b32_e32 v130, 0x7fffffff, v122
	v_and_b32_e32 v131, 0x7fffffff, v123
	v_and_b32_e32 v132, 0x7fffffff, v124
	v_and_b32_e32 v133, 0x7fffffff, v125
	v_and_b32_e32 v134, 0x7fffffff, v126
	v_and_b32_e32 v135, 0x7fffffff, v127
	v_pk_fma_f32 v[148:149], v[128:129], v[184:185], v[186:187]
	v_pk_fma_f32 v[150:151], v[130:131], v[184:185], v[186:187]
	v_pk_fma_f32 v[152:153], v[132:133], v[184:185], v[186:187]
	v_pk_fma_f32 v[154:155], v[134:135], v[184:185], v[186:187]
	v_rcp_f32_e32 v148, v148
	v_rcp_f32_e32 v149, v149
	v_rcp_f32_e32 v150, v150
	v_rcp_f32_e32 v151, v151
	v_rcp_f32_e32 v152, v152
	v_rcp_f32_e32 v153, v153
	v_rcp_f32_e32 v154, v154
	v_rcp_f32_e32 v155, v155
	v_pk_fma_f32 v[156:157], v[148:149], v[188:189], v[190:191]
	v_pk_fma_f32 v[158:159], v[150:151], v[188:189], v[190:191]
	v_pk_fma_f32 v[160:161], v[152:153], v[188:189], v[190:191]
	v_pk_fma_f32 v[162:163], v[154:155], v[188:189], v[190:191]
	v_pk_fma_f32 v[156:157], v[156:157], v[148:149], v[192:193]
	v_pk_fma_f32 v[158:159], v[158:159], v[150:151], v[192:193]
	v_pk_fma_f32 v[160:161], v[160:161], v[152:153], v[192:193]
	v_pk_fma_f32 v[162:163], v[162:163], v[154:155], v[192:193]
	v_pk_fma_f32 v[156:157], v[156:157], v[148:149], v[194:195]
	v_pk_fma_f32 v[158:159], v[158:159], v[150:151], v[194:195]
	v_pk_fma_f32 v[160:161], v[160:161], v[152:153], v[194:195]
	v_pk_fma_f32 v[162:163], v[162:163], v[154:155], v[194:195]
	v_pk_fma_f32 v[156:157], v[156:157], v[148:149], v[196:197]
	v_pk_fma_f32 v[158:159], v[158:159], v[150:151], v[196:197]
	v_pk_fma_f32 v[160:161], v[160:161], v[152:153], v[196:197]
	v_pk_fma_f32 v[162:163], v[162:163], v[154:155], v[196:197]
	v_pk_mul_f32 v[156:157], v[156:157], v[148:149]
	v_pk_mul_f32 v[158:159], v[158:159], v[150:151]
	v_pk_mul_f32 v[160:161], v[160:161], v[152:153]
	v_pk_mul_f32 v[162:163], v[162:163], v[154:155]
	v_pk_mul_f32 v[164:165], v[120:121], v[120:121]
	v_pk_mul_f32 v[166:167], v[122:123], v[122:123]
	v_pk_mul_f32 v[168:169], v[124:125], v[124:125]
	v_pk_mul_f32 v[170:171], v[126:127], v[126:127]
	v_pk_mul_f32 v[164:165], v[164:165], v[198:199]
	v_pk_mul_f32 v[166:167], v[166:167], v[198:199]
	v_pk_mul_f32 v[168:169], v[168:169], v[198:199]
	v_pk_mul_f32 v[170:171], v[170:171], v[198:199]
	v_exp_f32_e32 v164, v164
	v_exp_f32_e32 v165, v165
	v_exp_f32_e32 v166, v166
	v_exp_f32_e32 v167, v167
	v_exp_f32_e32 v168, v168
	v_exp_f32_e32 v169, v169
	v_exp_f32_e32 v170, v170
	v_exp_f32_e32 v171, v171
	v_pk_mul_f32 v[156:157], v[156:157], v[164:165]
	v_pk_mul_f32 v[158:159], v[158:159], v[166:167]
; __device__ __forceinline__ unsigned cvt_pk_bf16(float lo, float hi) { unsigned r; asm volatile("v_cvt_pk_bf16_f32 %0, %1, %2" : "=v"(r) : "v"(lo), "v"(hi)); return r; }
; __device__ __forceinline__ float gelu_as(float v) {
;   const float av = fabsf(v); const float t = __builtin_amdgcn_rcpf(av * 0.2316418882f + 1.0f);
;   float q = t * 0.5307027145f + (-0.7265760135f); q = q * t + 0.7107068705f; q = q * t + (-0.142248368f); q = q * t + 0.127414796f; q = q * t;
;   const float e = __builtin_amdgcn_exp2f((v * v) * (-0.72134752044f));
;   const float m = v * (q * e);
;   return v < 0.f ? m : v - m;
; }
; __device__ __forceinline__ void phase_conv(KP p, int l, int tid) {
;     ...
;     for (int jb = j0; jb < j0 + 16; jb += CB) {
;       u32x2 an[CB][RB + 2], ur[CB][RB];
; #pragma unroll
;       for (int q = 0; q < CB; ++q) { const int col = jb + q + 1; const int cl = col > 63 ? 63 : col;
; #pragma unroll
;         for (int di = 0; di < RB + 2; ++di) an[q][di] = *(const u32x2*)(rowp[di] + (size_t)cl * DFF);
; #pragma unroll
;         for (int rr = 0; rr < RB; ++rr) ur[q][rr] = *(const u32x2*)(U + (size_t)((r0 + rr) * 64 + jb + q) * DFF + c0); }
;       __builtin_amdgcn_sched_barrier(0);
; #pragma unroll
;       for (int q = 0; q < CB; ++q) {
;         const int col = jb + q + 1;
; #pragma unroll
;         for (int di = 0; di < RB + 2; ++di) { const bool ok = rv[di] && (col < 64); unpack4(an[q][di], win[2][di]);
; #pragma unroll
;           for (int k = 0; k < 4; ++k) win[2][di][k] = ok ? win[2][di][k] : 0.f; }
; #pragma unroll
;         for (int rr = 0; rr < RB; ++rr) {
;           float uv[4]; unpack4(ur[q][rr], uv);
;           float o[4];
; #pragma unroll
;           for (int k = 0; k < 4; ++k) {
;             float a = bsv[k];
; #pragma unroll
;             for (int di = 0; di < 3; ++di)
; #pragma unroll
;               for (int dj = 0; dj < 3; ++dj) a += win[dj][rr + di][k] * w[di * 3 + dj][k];
;             o[k] = gelu_as(a) * uv[k];
;           }
;           u32x2 ow; ow.x = cvt_pk_bf16(o[0], o[1]); ow.y = cvt_pk_bf16(o[2], o[3]);
;           *(u32x2*)(G + (size_t)((r0 + rr) * 64 + jb + q) * DFF + c0) = ow;
	v_pk_mul_f32 v[160:161], v[160:161], v[168:169]
	v_pk_mul_f32 v[162:163], v[162:163], v[170:171]
	v_pk_mul_f32 v[156:157], v[128:129], v[156:157]
	v_pk_mul_f32 v[158:159], v[130:131], v[158:159]
	v_pk_mul_f32 v[160:161], v[132:133], v[160:161]
	v_pk_mul_f32 v[162:163], v[134:135], v[162:163]
	v_max_f32_e32 v172, 0, v120
	v_max_f32_e32 v173, 0, v121
	v_max_f32_e32 v174, 0, v122
	v_max_f32_e32 v175, 0, v123
	v_max_f32_e32 v176, 0, v124
	v_max_f32_e32 v177, 0, v125
	v_max_f32_e32 v178, 0, v126
	v_max_f32_e32 v179, 0, v127
	v_pk_add_f32 v[172:173], v[172:173], v[156:157] neg_lo:[0,1] neg_hi:[0,1]
	v_pk_add_f32 v[174:175], v[174:175], v[158:159] neg_lo:[0,1] neg_hi:[0,1]
	v_pk_add_f32 v[176:177], v[176:177], v[160:161] neg_lo:[0,1] neg_hi:[0,1]
	v_pk_add_f32 v[178:179], v[178:179], v[162:163] neg_lo:[0,1] neg_hi:[0,1]
	v_pk_mul_f32 v[172:173], v[172:173], v[112:113]
	v_pk_mul_f32 v[174:175], v[174:175], v[114:115]
	v_pk_mul_f32 v[176:177], v[176:177], v[116:117]
	v_pk_mul_f32 v[178:179], v[178:179], v[118:119]
	v_cvt_pk_bf16_f32 v180, v172, v173
	v_cvt_pk_bf16_f32 v181, v174, v175
	v_cvt_pk_bf16_f32 v182, v176, v177
	v_cvt_pk_bf16_f32 v183, v178, v179
	global_store_dwordx2 v216, v[180:181], s[10:11]
	global_store_dwordx2 v217, v[182:183], s[10:11]
	v_add_u32_e32 v210, 0x2c00, v210
	v_add_u32_e32 v211, 0x2c00, v210
	v_add_u32_e32 v212, v206, v211
	global_load_dwordx2 v[88:89], v212, s[6:7]
	v_add_u32_e32 v213, v207, v211
	global_load_dwordx2 v[90:91], v213, s[6:7]
	v_add_u32_e32 v214, v208, v211
	global_load_dwordx2 v[92:93], v214, s[6:7]
	v_add_u32_e32 v215, v209, v211
	global_load_dwordx2 v[94:95], v215, s[6:7]
	v_add_u32_e32 v216, v207, v210
	global_load_dwordx2 v[104:105], v216, s[8:9]
	v_add_u32_e32 v217, v208, v210
	global_load_dwordx2 v[106:107], v217, s[8:9]
	s_waitcnt vmcnt(8)
	v_lshlrev_b32_e32 v72, 16, v96
	v_and_b32_e32 v73, 0xffff0000, v96
	v_lshlrev_b32_e32 v74, 16, v97
	v_and_b32_e32 v75, 0xffff0000, v97
	v_lshlrev_b32_e32 v76, 16, v98
	v_and_b32_e32 v77, 0xffff0000, v98
	v_lshlrev_b32_e32 v78, 16, v99
	v_and_b32_e32 v79, 0xffff0000, v99
	v_lshlrev_b32_e32 v80, 16, v100
	v_and_b32_e32 v81, 0xffff0000, v100
	v_lshlrev_b32_e32 v82, 16, v101
	v_and_b32_e32 v83, 0xffff0000, v101
	v_lshlrev_b32_e32 v84, 16, v102
	v_and_b32_e32 v85, 0xffff0000, v102
	v_lshlrev_b32_e32 v86, 16, v103
	v_and_b32_e32 v87, 0xffff0000, v103
	v_pk_mul_f32 v[72:73], v[72:73], v[200:201]
	v_pk_mul_f32 v[74:75], v[74:75], v[200:201]
	v_pk_mul_f32 v[84:85], v[84:85], v[202:203]
	v_pk_mul_f32 v[86:87], v[86:87], v[202:203]
	v_lshlrev_b32_e32 v112, 16, v108
	v_and_b32_e32 v113, 0xffff0000, v108
	v_lshlrev_b32_e32 v114, 16, v109
	v_and_b32_e32 v115, 0xffff0000, v109
	v_lshlrev_b32_e32 v116, 16, v110
	v_and_b32_e32 v117, 0xffff0000, v110
	v_lshlrev_b32_e32 v118, 16, v111
	v_and_b32_e32 v119, 0xffff0000, v111
	v_pk_fma_f32 v[120:121], v[40:41], v[0:1], v[36:37]
	v_pk_fma_f32 v[122:123], v[42:43], v[2:3], v[38:39]
	v_pk_fma_f32 v[124:125], v[44:45], v[0:1], v[36:37]
	v_pk_fma_f32 v[126:127], v[46:47], v[2:3], v[38:39]
	v_pk_fma_f32 v[120:121], v[56:57], v[4:5], v[120:121]
	v_pk_fma_f32 v[122:123], v[58:59], v[6:7], v[122:123]
	v_pk_fma_f32 v[124:125], v[60:61], v[4:5], v[124:125]
	v_pk_fma_f32 v[126:127], v[62:63], v[6:7], v[126:127]
	v_pk_fma_f32 v[120:121], v[72:73], v[8:9], v[120:121]
	v_pk_fma_f32 v[122:123], v[74:75], v[10:11], v[122:123]
	v_pk_fma_f32 v[124:125], v[76:77], v[8:9], v[124:125]
	v_pk_fma_f32 v[126:127], v[78:79], v[10:11], v[126:127]
	v_pk_fma_f32 v[120:121], v[44:45], v[12:13], v[120:121]
	v_pk_fma_f32 v[122:123], v[46:47], v[14:15], v[122:123]
	v_pk_fma_f32 v[124:125], v[48:49], v[12:13], v[124:125]
	v_pk_fma_f32 v[126:127], v[50:51], v[14:15], v[126:127]
	v_pk_fma_f32 v[120:121], v[60:61], v[16:17], v[120:121]
	v_pk_fma_f32 v[122:123], v[62:63], v[18:19], v[122:123]
	v_pk_fma_f32 v[124:125], v[64:65], v[16:17], v[124:125]
	v_pk_fma_f32 v[126:127], v[66:67], v[18:19], v[126:127]
	v_pk_fma_f32 v[120:121], v[76:77], v[20:21], v[120:121]
	v_pk_fma_f32 v[122:123], v[78:79], v[22:23], v[122:123]
	v_pk_fma_f32 v[124:125], v[80:81], v[20:21], v[124:125]
	v_pk_fma_f32 v[126:127], v[82:83], v[22:23], v[126:127]
	v_pk_fma_f32 v[120:121], v[48:49], v[24:25], v[120:121]
	v_pk_fma_f32 v[122:123], v[50:51], v[26:27], v[122:123]
	v_pk_fma_f32 v[124:125], v[52:53], v[24:25], v[124:125]
	v_pk_fma_f32 v[126:127], v[54:55], v[26:27], v[126:127]
	v_pk_fma_f32 v[120:121], v[64:65], v[28:29], v[120:121]
	v_pk_fma_f32 v[122:123], v[66:67], v[30:31], v[122:123]
	v_pk_fma_f32 v[124:125], v[68:69], v[28:29], v[124:125]
	v_pk_fma_f32 v[126:127], v[70:71], v[30:31], v[126:127]
	v_pk_fma_f32 v[120:121], v[80:81], v[32:33], v[120:121]
	v_pk_fma_f32 v[122:123], v[82:83], v[34:35], v[122:123]
	v_pk_fma_f32 v[124:125], v[84:85], v[32:33], v[124:125]
	v_pk_fma_f32 v[126:127], v[86:87], v[34:35], v[126:127]
	v_and_b32_e32 v128, 0x7fffffff, v120
	v_and_b32_e32 v129, 0x7fffffff, v121
	v_and_b32_e32 v130, 0x7fffffff, v122
	v_and_b32_e32 v131, 0x7fffffff, v123
	v_and_b32_e32 v132, 0x7fffffff, v124
	v_and_b32_e32 v133, 0x7fffffff, v125
	v_and_b32_e32 v134, 0x7fffffff, v126
	v_and_b32_e32 v135, 0x7fffffff, v127
	v_pk_fma_f32 v[148:149], v[128:129], v[184:185], v[186:187]
	v_pk_fma_f32 v[150:151], v[130:131], v[184:185], v[186:187]
	v_pk_fma_f32 v[152:153], v[132:133], v[184:185], v[186:187]
	v_pk_fma_f32 v[154:155], v[134:135], v[184:185], v[186:187]
	v_rcp_f32_e32 v148, v148
	v_rcp_f32_e32 v149, v149
	v_rcp_f32_e32 v150, v150
	v_rcp_f32_e32 v151, v151
	v_rcp_f32_e32 v152, v152
	v_rcp_f32_e32 v153, v153
	v_rcp_f32_e32 v154, v154
	v_rcp_f32_e32 v155, v155
; __device__ __forceinline__ unsigned cvt_pk_bf16(float lo, float hi) { unsigned r; asm volatile("v_cvt_pk_bf16_f32 %0, %1, %2" : "=v"(r) : "v"(lo), "v"(hi)); return r; }
; __device__ __forceinline__ float gelu_as(float v) {
;   const float av = fabsf(v); const float t = __builtin_amdgcn_rcpf(av * 0.2316418882f + 1.0f);
;   float q = t * 0.5307027145f + (-0.7265760135f); q = q * t + 0.7107068705f; q = q * t + (-0.142248368f); q = q * t + 0.127414796f; q = q * t;
;   const float e = __builtin_amdgcn_exp2f((v * v) * (-0.72134752044f));
;   const float m = v * (q * e);
;   return v < 0.f ? m : v - m;
; }
; __device__ __forceinline__ void phase_conv(KP p, int l, int tid) {
;     ...
;     for (int jb = j0; jb < j0 + 16; jb += CB) {
;       u32x2 an[CB][RB + 2], ur[CB][RB];
; #pragma unroll
;       for (int q = 0; q < CB; ++q) { const int col = jb + q + 1; const int cl = col > 63 ? 63 : col;
; #pragma unroll
;         for (int di = 0; di < RB + 2; ++di) an[q][di] = *(const u32x2*)(rowp[di] + (size_t)cl * DFF);
; #pragma unroll
;         for (int rr = 0; rr < RB; ++rr) ur[q][rr] = *(const u32x2*)(U + (size_t)((r0 + rr) * 64 + jb + q) * DFF + c0); }
;       __builtin_amdgcn_sched_barrier(0);
; #pragma unroll
;       for (int q = 0; q < CB; ++q) {
;         const int col = jb + q + 1;
; #pragma unroll
;         for (int di = 0; di < RB + 2; ++di) { const bool ok = rv[di] && (col < 64); unpack4(an[q][di], win[2][di]);
; #pragma unroll
;           for (int k = 0; k < 4; ++k) win[2][di][k] = ok ? win[2][di][k] : 0.f; }
; #pragma unroll
;         for (int rr = 0; rr < RB; ++rr) {
;           float uv[4]; unpack4(ur[q][rr], uv);
;           float o[4];
; #pragma unroll
;           for (int k = 0; k < 4; ++k) {
;             float a = bsv[k];
; #pragma unroll
;             for (int di = 0; di < 3; ++di)
; #pragma unroll
;               for (int dj = 0; dj < 3; ++dj) a += win[dj][rr + di][k] * w[di * 3 + dj][k];
;             o[k] = gelu_as(a) * uv[k];
;           }
;           u32x2 ow; ow.x = cvt_pk_bf16(o[0], o[1]); ow.y = cvt_pk_bf16(o[2], o[3]);
;           *(u32x2*)(G + (size_t)((r0 + rr) * 64 + jb + q) * DFF + c0) = ow;
	v_pk_fma_f32 v[156:157], v[148:149], v[188:189], v[190:191]
	v_pk_fma_f32 v[158:159], v[150:151], v[188:189], v[190:191]
	v_pk_fma_f32 v[160:161], v[152:153], v[188:189], v[190:191]
	v_pk_fma_f32 v[162:163], v[154:155], v[188:189], v[190:191]
	v_pk_fma_f32 v[156:157], v[156:157], v[148:149], v[192:193]
	v_pk_fma_f32 v[158:159], v[158:159], v[150:151], v[192:193]
	v_pk_fma_f32 v[160:161], v[160:161], v[152:153], v[192:193]
	v_pk_fma_f32 v[162:163], v[162:163], v[154:155], v[192:193]
	v_pk_fma_f32 v[156:157], v[156:157], v[148:149], v[194:195]
	v_pk_fma_f32 v[158:159], v[158:159], v[150:151], v[194:195]
	v_pk_fma_f32 v[160:161], v[160:161], v[152:153], v[194:195]
	v_pk_fma_f32 v[162:163], v[162:163], v[154:155], v[194:195]
	v_pk_fma_f32 v[156:157], v[156:157], v[148:149], v[196:197]
	v_pk_fma_f32 v[158:159], v[158:159], v[150:151], v[196:197]
	v_pk_fma_f32 v[160:161], v[160:161], v[152:153], v[196:197]
	v_pk_fma_f32 v[162:163], v[162:163], v[154:155], v[196:197]
	v_pk_mul_f32 v[156:157], v[156:157], v[148:149]
	v_pk_mul_f32 v[158:159], v[158:159], v[150:151]
	v_pk_mul_f32 v[160:161], v[160:161], v[152:153]
	v_pk_mul_f32 v[162:163], v[162:163], v[154:155]
	v_pk_mul_f32 v[164:165], v[120:121], v[120:121]
	v_pk_mul_f32 v[166:167], v[122:123], v[122:123]
	v_pk_mul_f32 v[168:169], v[124:125], v[124:125]
	v_pk_mul_f32 v[170:171], v[126:127], v[126:127]
	v_pk_mul_f32 v[164:165], v[164:165], v[198:199]
	v_pk_mul_f32 v[166:167], v[166:167], v[198:199]
	v_pk_mul_f32 v[168:169], v[168:169], v[198:199]
	v_pk_mul_f32 v[170:171], v[170:171], v[198:199]
	v_exp_f32_e32 v164, v164
	v_exp_f32_e32 v165, v165
	v_exp_f32_e32 v166, v166
	v_exp_f32_e32 v167, v167
	v_exp_f32_e32 v168, v168
	v_exp_f32_e32 v169, v169
	v_exp_f32_e32 v170, v170
	v_exp_f32_e32 v171, v171
	v_pk_mul_f32 v[156:157], v[156:157], v[164:165]
	v_pk_mul_f32 v[158:159], v[158:159], v[166:167]
	v_pk_mul_f32 v[160:161], v[160:161], v[168:169]
	v_pk_mul_f32 v[162:163], v[162:163], v[170:171]
	v_pk_mul_f32 v[156:157], v[128:129], v[156:157]
	v_pk_mul_f32 v[158:159], v[130:131], v[158:159]
	v_pk_mul_f32 v[160:161], v[132:133], v[160:161]
	v_pk_mul_f32 v[162:163], v[134:135], v[162:163]
	v_max_f32_e32 v172, 0, v120
	v_max_f32_e32 v173, 0, v121
	v_max_f32_e32 v174, 0, v122
	v_max_f32_e32 v175, 0, v123
	v_max_f32_e32 v176, 0, v124
	v_max_f32_e32 v177, 0, v125
	v_max_f32_e32 v178, 0, v126
	v_max_f32_e32 v179, 0, v127
	v_pk_add_f32 v[172:173], v[172:173], v[156:157] neg_lo:[0,1] neg_hi:[0,1]
	v_pk_add_f32 v[174:175], v[174:175], v[158:159] neg_lo:[0,1] neg_hi:[0,1]
	v_pk_add_f32 v[176:177], v[176:177], v[160:161] neg_lo:[0,1] neg_hi:[0,1]
	v_pk_add_f32 v[178:179], v[178:179], v[162:163] neg_lo:[0,1] neg_hi:[0,1]
	v_pk_mul_f32 v[172:173], v[172:173], v[112:113]
	v_pk_mul_f32 v[174:175], v[174:175], v[114:115]
	v_pk_mul_f32 v[176:177], v[176:177], v[116:117]
	v_pk_mul_f32 v[178:179], v[178:179], v[118:119]
	v_cvt_pk_bf16_f32 v180, v172, v173
	v_cvt_pk_bf16_f32 v181, v174, v175
	v_cvt_pk_bf16_f32 v182, v176, v177
	v_cvt_pk_bf16_f32 v183, v178, v179
	global_store_dwordx2 v218, v[180:181], s[10:11]
	global_store_dwordx2 v219, v[182:183], s[10:11]
	v_add_u32_e32 v210, 0x2c00, v210
	v_add_u32_e32 v211, 0x2c00, v210
	v_add_u32_e32 v212, v206, v211
	global_load_dwordx2 v[96:97], v212, s[6:7]
	v_add_u32_e32 v213, v207, v211
	global_load_dwordx2 v[98:99], v213, s[6:7]
	v_add_u32_e32 v214, v208, v211
	global_load_dwordx2 v[100:101], v214, s[6:7]
	v_add_u32_e32 v215, v209, v211
	global_load_dwordx2 v[102:103], v215, s[6:7]
	v_add_u32_e32 v218, v207, v210
	global_load_dwordx2 v[108:109], v218, s[8:9]
	v_add_u32_e32 v219, v208, v210
	global_load_dwordx2 v[110:111], v219, s[8:9]
	s_waitcnt vmcnt(8)
	v_lshlrev_b32_e32 v40, 16, v88
	v_and_b32_e32 v41, 0xffff0000, v88
	v_lshlrev_b32_e32 v42, 16, v89
	v_and_b32_e32 v43, 0xffff0000, v89
	v_lshlrev_b32_e32 v44, 16, v90
	v_and_b32_e32 v45, 0xffff0000, v90
	v_lshlrev_b32_e32 v46, 16, v91
	v_and_b32_e32 v47, 0xffff0000, v91
	v_lshlrev_b32_e32 v48, 16, v92
	v_and_b32_e32 v49, 0xffff0000, v92
	v_lshlrev_b32_e32 v50, 16, v93
	v_and_b32_e32 v51, 0xffff0000, v93
	v_lshlrev_b32_e32 v52, 16, v94
	v_and_b32_e32 v53, 0xffff0000, v94
	v_lshlrev_b32_e32 v54, 16, v95
	v_and_b32_e32 v55, 0xffff0000, v95
	v_pk_mul_f32 v[40:41], v[40:41], v[200:201]
	v_pk_mul_f32 v[42:43], v[42:43], v[200:201]
	v_pk_mul_f32 v[52:53], v[52:53], v[202:203]
	v_pk_mul_f32 v[54:55], v[54:55], v[202:203]
	v_lshlrev_b32_e32 v112, 16, v104
	v_and_b32_e32 v113, 0xffff0000, v104
	v_lshlrev_b32_e32 v114, 16, v105
	v_and_b32_e32 v115, 0xffff0000, v105
	v_lshlrev_b32_e32 v116, 16, v106
	v_and_b32_e32 v117, 0xffff0000, v106
	v_lshlrev_b32_e32 v118, 16, v107
	v_and_b32_e32 v119, 0xffff0000, v107
	v_pk_fma_f32 v[120:121], v[56:57], v[0:1], v[36:37]
	v_pk_fma_f32 v[122:123], v[58:59], v[2:3], v[38:39]
	v_pk_fma_f32 v[124:125], v[60:61], v[0:1], v[36:37]
	v_pk_fma_f32 v[126:127], v[62:63], v[2:3], v[38:39]
	v_pk_fma_f32 v[120:121], v[72:73], v[4:5], v[120:121]
	v_pk_fma_f32 v[122:123], v[74:75], v[6:7], v[122:123]
	v_pk_fma_f32 v[124:125], v[76:77], v[4:5], v[124:125]
	v_pk_fma_f32 v[126:127], v[78:79], v[6:7], v[126:127]
	v_pk_fma_f32 v[120:121], v[40:41], v[8:9], v[120:121]
	v_pk_fma_f32 v[122:123], v[42:43], v[10:11], v[122:123]
	v_pk_fma_f32 v[124:125], v[44:45], v[8:9], v[124:125]
	v_pk_fma_f32 v[126:127], v[46:47], v[10:11], v[126:127]
	v_pk_fma_f32 v[120:121], v[60:61], v[12:13], v[120:121]
	v_pk_fma_f32 v[122:123], v[62:63], v[14:15], v[122:123]
	v_pk_fma_f32 v[124:125], v[64:65], v[12:13], v[124:125]
	v_pk_fma_f32 v[126:127], v[66:67], v[14:15], v[126:127]
	v_pk_fma_f32 v[120:121], v[76:77], v[16:17], v[120:121]
; __device__ __forceinline__ unsigned cvt_pk_bf16(float lo, float hi) { unsigned r; asm volatile("v_cvt_pk_bf16_f32 %0, %1, %2" : "=v"(r) : "v"(lo), "v"(hi)); return r; }
; __device__ __forceinline__ float gelu_as(float v) {
;   const float av = fabsf(v); const float t = __builtin_amdgcn_rcpf(av * 0.2316418882f + 1.0f);
;   float q = t * 0.5307027145f + (-0.7265760135f); q = q * t + 0.7107068705f; q = q * t + (-0.142248368f); q = q * t + 0.127414796f; q = q * t;
;   const float e = __builtin_amdgcn_exp2f((v * v) * (-0.72134752044f));
;   const float m = v * (q * e);
;   return v < 0.f ? m : v - m;
; }
; __device__ __forceinline__ void phase_conv(KP p, int l, int tid) {
;     ...
;     for (int jb = j0; jb < j0 + 16; jb += CB) {
;       u32x2 an[CB][RB + 2], ur[CB][RB];
; #pragma unroll
;       for (int q = 0; q < CB; ++q) { const int col = jb + q + 1; const int cl = col > 63 ? 63 : col;
; #pragma unroll
;         for (int di = 0; di < RB + 2; ++di) an[q][di] = *(const u32x2*)(rowp[di] + (size_t)cl * DFF);
; #pragma unroll
;         for (int rr = 0; rr < RB; ++rr) ur[q][rr] = *(const u32x2*)(U + (size_t)((r0 + rr) * 64 + jb + q) * DFF + c0); }
;       __builtin_amdgcn_sched_barrier(0);
; #pragma unroll
;       for (int q = 0; q < CB; ++q) {
;         const int col = jb + q + 1;
; #pragma unroll
;         for (int di = 0; di < RB + 2; ++di) { const bool ok = rv[di] && (col < 64); unpack4(an[q][di], win[2][di]);
; #pragma unroll
;           for (int k = 0; k < 4; ++k) win[2][di][k] = ok ? win[2][di][k] : 0.f; }
; #pragma unroll
;         for (int rr = 0; rr < RB; ++rr) {
;           float uv[4]; unpack4(ur[q][rr], uv);
;           float o[4];
; #pragma unroll
;           for (int k = 0; k < 4; ++k) {
;             float a = bsv[k];
; #pragma unroll
;             for (int di = 0; di < 3; ++di)
; #pragma unroll
;               for (int dj = 0; dj < 3; ++dj) a += win[dj][rr + di][k] * w[di * 3 + dj][k];
;             o[k] = gelu_as(a) * uv[k];
;           }
;           u32x2 ow; ow.x = cvt_pk_bf16(o[0], o[1]); ow.y = cvt_pk_bf16(o[2], o[3]);
;           *(u32x2*)(G + (size_t)((r0 + rr) * 64 + jb + q) * DFF + c0) = ow;
	v_pk_fma_f32 v[122:123], v[78:79], v[18:19], v[122:123]
	v_pk_fma_f32 v[124:125], v[80:81], v[16:17], v[124:125]
	v_pk_fma_f32 v[126:127], v[82:83], v[18:19], v[126:127]
	v_pk_fma_f32 v[120:121], v[44:45], v[20:21], v[120:121]
	v_pk_fma_f32 v[122:123], v[46:47], v[22:23], v[122:123]
	v_pk_fma_f32 v[124:125], v[48:49], v[20:21], v[124:125]
	v_pk_fma_f32 v[126:127], v[50:51], v[22:23], v[126:127]
	v_pk_fma_f32 v[120:121], v[64:65], v[24:25], v[120:121]
	v_pk_fma_f32 v[122:123], v[66:67], v[26:27], v[122:123]
	v_pk_fma_f32 v[124:125], v[68:69], v[24:25], v[124:125]
	v_pk_fma_f32 v[126:127], v[70:71], v[26:27], v[126:127]
	v_pk_fma_f32 v[120:121], v[80:81], v[28:29], v[120:121]
	v_pk_fma_f32 v[122:123], v[82:83], v[30:31], v[122:123]
	v_pk_fma_f32 v[124:125], v[84:85], v[28:29], v[124:125]
	v_pk_fma_f32 v[126:127], v[86:87], v[30:31], v[126:127]
	v_pk_fma_f32 v[120:121], v[48:49], v[32:33], v[120:121]
	v_pk_fma_f32 v[122:123], v[50:51], v[34:35], v[122:123]
	v_pk_fma_f32 v[124:125], v[52:53], v[32:33], v[124:125]
	v_pk_fma_f32 v[126:127], v[54:55], v[34:35], v[126:127]
	v_and_b32_e32 v128, 0x7fffffff, v120
	v_and_b32_e32 v129, 0x7fffffff, v121
	v_and_b32_e32 v130, 0x7fffffff, v122
	v_and_b32_e32 v131, 0x7fffffff, v123
	v_and_b32_e32 v132, 0x7fffffff, v124
	v_and_b32_e32 v133, 0x7fffffff, v125
	v_and_b32_e32 v134, 0x7fffffff, v126
	v_and_b32_e32 v135, 0x7fffffff, v127
	v_pk_fma_f32 v[148:149], v[128:129], v[184:185], v[186:187]
	v_pk_fma_f32 v[150:151], v[130:131], v[184:185], v[186:187]
	v_pk_fma_f32 v[152:153], v[132:133], v[184:185], v[186:187]
	v_pk_fma_f32 v[154:155], v[134:135], v[184:185], v[186:187]
	v_rcp_f32_e32 v148, v148
	v_rcp_f32_e32 v149, v149
	v_rcp_f32_e32 v150, v150
	v_rcp_f32_e32 v151, v151
	v_rcp_f32_e32 v152, v152
	v_rcp_f32_e32 v153, v153
	v_rcp_f32_e32 v154, v154
	v_rcp_f32_e32 v155, v155
	v_pk_fma_f32 v[156:157], v[148:149], v[188:189], v[190:191]
	v_pk_fma_f32 v[158:159], v[150:151], v[188:189], v[190:191]
	v_pk_fma_f32 v[160:161], v[152:153], v[188:189], v[190:191]
	v_pk_fma_f32 v[162:163], v[154:155], v[188:189], v[190:191]
	v_pk_fma_f32 v[156:157], v[156:157], v[148:149], v[192:193]
	v_pk_fma_f32 v[158:159], v[158:159], v[150:151], v[192:193]
	v_pk_fma_f32 v[160:161], v[160:161], v[152:153], v[192:193]
	v_pk_fma_f32 v[162:163], v[162:163], v[154:155], v[192:193]
	v_pk_fma_f32 v[156:157], v[156:157], v[148:149], v[194:195]
	v_pk_fma_f32 v[158:159], v[158:159], v[150:151], v[194:195]
	v_pk_fma_f32 v[160:161], v[160:161], v[152:153], v[194:195]
	v_pk_fma_f32 v[162:163], v[162:163], v[154:155], v[194:195]
	v_pk_fma_f32 v[156:157], v[156:157], v[148:149], v[196:197]
	v_pk_fma_f32 v[158:159], v[158:159], v[150:151], v[196:197]
	v_pk_fma_f32 v[160:161], v[160:161], v[152:153], v[196:197]
	v_pk_fma_f32 v[162:163], v[162:163], v[154:155], v[196:197]
	v_pk_mul_f32 v[156:157], v[156:157], v[148:149]
	v_pk_mul_f32 v[158:159], v[158:159], v[150:151]
	v_pk_mul_f32 v[160:161], v[160:161], v[152:153]
	v_pk_mul_f32 v[162:163], v[162:163], v[154:155]
	v_pk_mul_f32 v[164:165], v[120:121], v[120:121]
	v_pk_mul_f32 v[166:167], v[122:123], v[122:123]
	v_pk_mul_f32 v[168:169], v[124:125], v[124:125]
	v_pk_mul_f32 v[170:171], v[126:127], v[126:127]
	v_pk_mul_f32 v[164:165], v[164:165], v[198:199]
	v_pk_mul_f32 v[166:167], v[166:167], v[198:199]
	v_pk_mul_f32 v[168:169], v[168:169], v[198:199]
	v_pk_mul_f32 v[170:171], v[170:171], v[198:199]
	v_exp_f32_e32 v164, v164
	v_exp_f32_e32 v165, v165
	v_exp_f32_e32 v166, v166
	v_exp_f32_e32 v167, v167
	v_exp_f32_e32 v168, v168
	v_exp_f32_e32 v169, v169
	v_exp_f32_e32 v170, v170
	v_exp_f32_e32 v171, v171
	v_pk_mul_f32 v[156:157], v[156:157], v[164:165]
	v_pk_mul_f32 v[158:159], v[158:159], v[166:167]
	v_pk_mul_f32 v[160:161], v[160:161], v[168:169]
	v_pk_mul_f32 v[162:163], v[162:163], v[170:171]
	v_pk_mul_f32 v[156:157], v[128:129], v[156:157]
	v_pk_mul_f32 v[158:159], v[130:131], v[158:159]
	v_pk_mul_f32 v[160:161], v[132:133], v[160:161]
	v_pk_mul_f32 v[162:163], v[134:135], v[162:163]
	v_max_f32_e32 v172, 0, v120
	v_max_f32_e32 v173, 0, v121
	v_max_f32_e32 v174, 0, v122
	v_max_f32_e32 v175, 0, v123
	v_max_f32_e32 v176, 0, v124
	v_max_f32_e32 v177, 0, v125
	v_max_f32_e32 v178, 0, v126
	v_max_f32_e32 v179, 0, v127
	v_pk_add_f32 v[172:173], v[172:173], v[156:157] neg_lo:[0,1] neg_hi:[0,1]
	v_pk_add_f32 v[174:175], v[174:175], v[158:159] neg_lo:[0,1] neg_hi:[0,1]
	v_pk_add_f32 v[176:177], v[176:177], v[160:161] neg_lo:[0,1] neg_hi:[0,1]
	v_pk_add_f32 v[178:179], v[178:179], v[162:163] neg_lo:[0,1] neg_hi:[0,1]
	v_pk_mul_f32 v[172:173], v[172:173], v[112:113]
	v_pk_mul_f32 v[174:175], v[174:175], v[114:115]
	v_pk_mul_f32 v[176:177], v[176:177], v[116:117]
	v_pk_mul_f32 v[178:179], v[178:179], v[118:119]
	v_cvt_pk_bf16_f32 v180, v172, v173
	v_cvt_pk_bf16_f32 v181, v174, v175
	v_cvt_pk_bf16_f32 v182, v176, v177
	v_cvt_pk_bf16_f32 v183, v178, v179
	global_store_dwordx2 v216, v[180:181], s[10:11]
	global_store_dwordx2 v217, v[182:183], s[10:11]
	v_add_u32_e32 v210, 0x2c00, v210
	v_add_u32_e32 v211, 0x2c00, v210
	v_add_u32_e32 v212, v206, v211
	global_load_dwordx2 v[88:89], v212, s[6:7]
	v_add_u32_e32 v213, v207, v211
	global_load_dwordx2 v[90:91], v213, s[6:7]
	v_add_u32_e32 v214, v208, v211
	global_load_dwordx2 v[92:93], v214, s[6:7]
	v_add_u32_e32 v215, v209, v211
	global_load_dwordx2 v[94:95], v215, s[6:7]
	v_add_u32_e32 v216, v207, v210
	global_load_dwordx2 v[104:105], v216, s[8:9]
	v_add_u32_e32 v217, v208, v210
	global_load_dwordx2 v[106:107], v217, s[8:9]
	s_waitcnt vmcnt(8)
; __device__ __forceinline__ unsigned cvt_pk_bf16(float lo, float hi) { unsigned r; asm volatile("v_cvt_pk_bf16_f32 %0, %1, %2" : "=v"(r) : "v"(lo), "v"(hi)); return r; }
; __device__ __forceinline__ float gelu_as(float v) {
;   const float av = fabsf(v); const float t = __builtin_amdgcn_rcpf(av * 0.2316418882f + 1.0f);
;   float q = t * 0.5307027145f + (-0.7265760135f); q = q * t + 0.7107068705f; q = q * t + (-0.142248368f); q = q * t + 0.127414796f; q = q * t;
;   const float e = __builtin_amdgcn_exp2f((v * v) * (-0.72134752044f));
;   const float m = v * (q * e);
;   return v < 0.f ? m : v - m;
; }
; __device__ __forceinline__ void phase_conv(KP p, int l, int tid) {
;     ...
;     for (int jb = j0; jb < j0 + 16; jb += CB) {
;       u32x2 an[CB][RB + 2], ur[CB][RB];
; #pragma unroll
;       for (int q = 0; q < CB; ++q) { const int col = jb + q + 1; const int cl = col > 63 ? 63 : col;
; #pragma unroll
;         for (int di = 0; di < RB + 2; ++di) an[q][di] = *(const u32x2*)(rowp[di] + (size_t)cl * DFF);
; #pragma unroll
;         for (int rr = 0; rr < RB; ++rr) ur[q][rr] = *(const u32x2*)(U + (size_t)((r0 + rr) * 64 + jb + q) * DFF + c0); }
;       __builtin_amdgcn_sched_barrier(0);
; #pragma unroll
;       for (int q = 0; q < CB; ++q) {
;         const int col = jb + q + 1;
; #pragma unroll
;         for (int di = 0; di < RB + 2; ++di) { const bool ok = rv[di] && (col < 64); unpack4(an[q][di], win[2][di]);
; #pragma unroll
;           for (int k = 0; k < 4; ++k) win[2][di][k] = ok ? win[2][di][k] : 0.f; }
; #pragma unroll
;         for (int rr = 0; rr < RB; ++rr) {
;           float uv[4]; unpack4(ur[q][rr], uv);
;           float o[4];
; #pragma unroll
;           for (int k = 0; k < 4; ++k) {
;             float a = bsv[k];
; #pragma unroll
;             for (int di = 0; di < 3; ++di)
; #pragma unroll
;               for (int dj = 0; dj < 3; ++dj) a += win[dj][rr + di][k] * w[di * 3 + dj][k];
;             o[k] = gelu_as(a) * uv[k];
;           }
;           u32x2 ow; ow.x = cvt_pk_bf16(o[0], o[1]); ow.y = cvt_pk_bf16(o[2], o[3]);
;           *(u32x2*)(G + (size_t)((r0 + rr) * 64 + jb + q) * DFF + c0) = ow;
	v_lshlrev_b32_e32 v56, 16, v96
	v_and_b32_e32 v57, 0xffff0000, v96
	v_lshlrev_b32_e32 v58, 16, v97
	v_and_b32_e32 v59, 0xffff0000, v97
	v_lshlrev_b32_e32 v60, 16, v98
	v_and_b32_e32 v61, 0xffff0000, v98
	v_lshlrev_b32_e32 v62, 16, v99
	v_and_b32_e32 v63, 0xffff0000, v99
	v_lshlrev_b32_e32 v64, 16, v100
	v_and_b32_e32 v65, 0xffff0000, v100
	v_lshlrev_b32_e32 v66, 16, v101
	v_and_b32_e32 v67, 0xffff0000, v101
	v_lshlrev_b32_e32 v68, 16, v102
	v_and_b32_e32 v69, 0xffff0000, v102
	v_lshlrev_b32_e32 v70, 16, v103
	v_and_b32_e32 v71, 0xffff0000, v103
	v_pk_mul_f32 v[56:57], v[56:57], v[200:201]
	v_pk_mul_f32 v[58:59], v[58:59], v[200:201]
	v_pk_mul_f32 v[68:69], v[68:69], v[202:203]
	v_pk_mul_f32 v[70:71], v[70:71], v[202:203]
	v_lshlrev_b32_e32 v112, 16, v108
	v_and_b32_e32 v113, 0xffff0000, v108
	v_lshlrev_b32_e32 v114, 16, v109
	v_and_b32_e32 v115, 0xffff0000, v109
	v_lshlrev_b32_e32 v116, 16, v110
	v_and_b32_e32 v117, 0xffff0000, v110
	v_lshlrev_b32_e32 v118, 16, v111
	v_and_b32_e32 v119, 0xffff0000, v111
	v_pk_fma_f32 v[120:121], v[72:73], v[0:1], v[36:37]
	v_pk_fma_f32 v[122:123], v[74:75], v[2:3], v[38:39]
	v_pk_fma_f32 v[124:125], v[76:77], v[0:1], v[36:37]
	v_pk_fma_f32 v[126:127], v[78:79], v[2:3], v[38:39]
	v_pk_fma_f32 v[120:121], v[40:41], v[4:5], v[120:121]
	v_pk_fma_f32 v[122:123], v[42:43], v[6:7], v[122:123]
	v_pk_fma_f32 v[124:125], v[44:45], v[4:5], v[124:125]
	v_pk_fma_f32 v[126:127], v[46:47], v[6:7], v[126:127]
	v_pk_fma_f32 v[120:121], v[56:57], v[8:9], v[120:121]
	v_pk_fma_f32 v[122:123], v[58:59], v[10:11], v[122:123]
	v_pk_fma_f32 v[124:125], v[60:61], v[8:9], v[124:125]
	v_pk_fma_f32 v[126:127], v[62:63], v[10:11], v[126:127]
	v_pk_fma_f32 v[120:121], v[76:77], v[12:13], v[120:121]
	v_pk_fma_f32 v[122:123], v[78:79], v[14:15], v[122:123]
	v_pk_fma_f32 v[124:125], v[80:81], v[12:13], v[124:125]
	v_pk_fma_f32 v[126:127], v[82:83], v[14:15], v[126:127]
	v_pk_fma_f32 v[120:121], v[44:45], v[16:17], v[120:121]
	v_pk_fma_f32 v[122:123], v[46:47], v[18:19], v[122:123]
	v_pk_fma_f32 v[124:125], v[48:49], v[16:17], v[124:125]
	v_pk_fma_f32 v[126:127], v[50:51], v[18:19], v[126:127]
	v_pk_fma_f32 v[120:121], v[60:61], v[20:21], v[120:121]
	v_pk_fma_f32 v[122:123], v[62:63], v[22:23], v[122:123]
	v_pk_fma_f32 v[124:125], v[64:65], v[20:21], v[124:125]
	v_pk_fma_f32 v[126:127], v[66:67], v[22:23], v[126:127]
	v_pk_fma_f32 v[120:121], v[80:81], v[24:25], v[120:121]
	v_pk_fma_f32 v[122:123], v[82:83], v[26:27], v[122:123]
	v_pk_fma_f32 v[124:125], v[84:85], v[24:25], v[124:125]
	v_pk_fma_f32 v[126:127], v[86:87], v[26:27], v[126:127]
	v_pk_fma_f32 v[120:121], v[48:49], v[28:29], v[120:121]
	v_pk_fma_f32 v[122:123], v[50:51], v[30:31], v[122:123]
	v_pk_fma_f32 v[124:125], v[52:53], v[28:29], v[124:125]
	v_pk_fma_f32 v[126:127], v[54:55], v[30:31], v[126:127]
	v_pk_fma_f32 v[120:121], v[64:65], v[32:33], v[120:121]
	v_pk_fma_f32 v[122:123], v[66:67], v[34:35], v[122:123]
	v_pk_fma_f32 v[124:125], v[68:69], v[32:33], v[124:125]
	v_pk_fma_f32 v[126:127], v[70:71], v[34:35], v[126:127]
	v_and_b32_e32 v128, 0x7fffffff, v120
	v_and_b32_e32 v129, 0x7fffffff, v121
	v_and_b32_e32 v130, 0x7fffffff, v122
	v_and_b32_e32 v131, 0x7fffffff, v123
	v_and_b32_e32 v132, 0x7fffffff, v124
	v_and_b32_e32 v133, 0x7fffffff, v125
	v_and_b32_e32 v134, 0x7fffffff, v126
	v_and_b32_e32 v135, 0x7fffffff, v127
	v_pk_fma_f32 v[148:149], v[128:129], v[184:185], v[186:187]
	v_pk_fma_f32 v[150:151], v[130:131], v[184:185], v[186:187]
	v_pk_fma_f32 v[152:153], v[132:133], v[184:185], v[186:187]
	v_pk_fma_f32 v[154:155], v[134:135], v[184:185], v[186:187]
	v_rcp_f32_e32 v148, v148
	v_rcp_f32_e32 v149, v149
	v_rcp_f32_e32 v150, v150
	v_rcp_f32_e32 v151, v151
	v_rcp_f32_e32 v152, v152
	v_rcp_f32_e32 v153, v153
	v_rcp_f32_e32 v154, v154
	v_rcp_f32_e32 v155, v155
	v_pk_fma_f32 v[156:157], v[148:149], v[188:189], v[190:191]
	v_pk_fma_f32 v[158:159], v[150:151], v[188:189], v[190:191]
	v_pk_fma_f32 v[160:161], v[152:153], v[188:189], v[190:191]
	v_pk_fma_f32 v[162:163], v[154:155], v[188:189], v[190:191]
	v_pk_fma_f32 v[156:157], v[156:157], v[148:149], v[192:193]
	v_pk_fma_f32 v[158:159], v[158:159], v[150:151], v[192:193]
	v_pk_fma_f32 v[160:161], v[160:161], v[152:153], v[192:193]
	v_pk_fma_f32 v[162:163], v[162:163], v[154:155], v[192:193]
	v_pk_fma_f32 v[156:157], v[156:157], v[148:149], v[194:195]
	v_pk_fma_f32 v[158:159], v[158:159], v[150:151], v[194:195]
	v_pk_fma_f32 v[160:161], v[160:161], v[152:153], v[194:195]
	v_pk_fma_f32 v[162:163], v[162:163], v[154:155], v[194:195]
	v_pk_fma_f32 v[156:157], v[156:157], v[148:149], v[196:197]
	v_pk_fma_f32 v[158:159], v[158:159], v[150:151], v[196:197]
	v_pk_fma_f32 v[160:161], v[160:161], v[152:153], v[196:197]
	v_pk_fma_f32 v[162:163], v[162:163], v[154:155], v[196:197]
	v_pk_mul_f32 v[156:157], v[156:157], v[148:149]
	v_pk_mul_f32 v[158:159], v[158:159], v[150:151]
	v_pk_mul_f32 v[160:161], v[160:161], v[152:153]
	v_pk_mul_f32 v[162:163], v[162:163], v[154:155]
	v_pk_mul_f32 v[164:165], v[120:121], v[120:121]
	v_pk_mul_f32 v[166:167], v[122:123], v[122:123]
	v_pk_mul_f32 v[168:169], v[124:125], v[124:125]
	v_pk_mul_f32 v[170:171], v[126:127], v[126:127]
	v_pk_mul_f32 v[164:165], v[164:165], v[198:199]
	v_pk_mul_f32 v[166:167], v[166:167], v[198:199]
	v_pk_mul_f32 v[168:169], v[168:169], v[198:199]
	v_pk_mul_f32 v[170:171], v[170:171], v[198:199]
	v_exp_f32_e32 v164, v164
	v_exp_f32_e32 v165, v165
	v_exp_f32_e32 v166, v166
	v_exp_f32_e32 v167, v167
	v_exp_f32_e32 v168, v168
	v_exp_f32_e32 v169, v169
	v_exp_f32_e32 v170, v170
	v_exp_f32_e32 v171, v171
	v_pk_mul_f32 v[156:157], v[156:157], v[164:165]
; __device__ __forceinline__ unsigned cvt_pk_bf16(float lo, float hi) { unsigned r; asm volatile("v_cvt_pk_bf16_f32 %0, %1, %2" : "=v"(r) : "v"(lo), "v"(hi)); return r; }
; __device__ __forceinline__ float gelu_as(float v) {
;   const float av = fabsf(v); const float t = __builtin_amdgcn_rcpf(av * 0.2316418882f + 1.0f);
;   float q = t * 0.5307027145f + (-0.7265760135f); q = q * t + 0.7107068705f; q = q * t + (-0.142248368f); q = q * t + 0.127414796f; q = q * t;
;   const float e = __builtin_amdgcn_exp2f((v * v) * (-0.72134752044f));
;   const float m = v * (q * e);
;   return v < 0.f ? m : v - m;
; }
; __device__ __forceinline__ void phase_conv(KP p, int l, int tid) {
;     ...
;     for (int jb = j0; jb < j0 + 16; jb += CB) {
;       u32x2 an[CB][RB + 2], ur[CB][RB];
; #pragma unroll
;       for (int q = 0; q < CB; ++q) { const int col = jb + q + 1; const int cl = col > 63 ? 63 : col;
; #pragma unroll
;         for (int di = 0; di < RB + 2; ++di) an[q][di] = *(const u32x2*)(rowp[di] + (size_t)cl * DFF);
; #pragma unroll
;         for (int rr = 0; rr < RB; ++rr) ur[q][rr] = *(const u32x2*)(U + (size_t)((r0 + rr) * 64 + jb + q) * DFF + c0); }
;       __builtin_amdgcn_sched_barrier(0);
; #pragma unroll
;       for (int q = 0; q < CB; ++q) {
;         const int col = jb + q + 1;
; #pragma unroll
;         for (int di = 0; di < RB + 2; ++di) { const bool ok = rv[di] && (col < 64); unpack4(an[q][di], win[2][di]);
; #pragma unroll
;           for (int k = 0; k < 4; ++k) win[2][di][k] = ok ? win[2][di][k] : 0.f; }
; #pragma unroll
;         for (int rr = 0; rr < RB; ++rr) {
;           float uv[4]; unpack4(ur[q][rr], uv);
;           float o[4];
; #pragma unroll
;           for (int k = 0; k < 4; ++k) {
;             float a = bsv[k];
; #pragma unroll
;             for (int di = 0; di < 3; ++di)
; #pragma unroll
;               for (int dj = 0; dj < 3; ++dj) a += win[dj][rr + di][k] * w[di * 3 + dj][k];
;             o[k] = gelu_as(a) * uv[k];
;           }
;           u32x2 ow; ow.x = cvt_pk_bf16(o[0], o[1]); ow.y = cvt_pk_bf16(o[2], o[3]);
;           *(u32x2*)(G + (size_t)((r0 + rr) * 64 + jb + q) * DFF + c0) = ow;
	v_pk_mul_f32 v[158:159], v[158:159], v[166:167]
	v_pk_mul_f32 v[160:161], v[160:161], v[168:169]
	v_pk_mul_f32 v[162:163], v[162:163], v[170:171]
	v_pk_mul_f32 v[156:157], v[128:129], v[156:157]
	v_pk_mul_f32 v[158:159], v[130:131], v[158:159]
	v_pk_mul_f32 v[160:161], v[132:133], v[160:161]
	v_pk_mul_f32 v[162:163], v[134:135], v[162:163]
	v_max_f32_e32 v172, 0, v120
	v_max_f32_e32 v173, 0, v121
	v_max_f32_e32 v174, 0, v122
	v_max_f32_e32 v175, 0, v123
	v_max_f32_e32 v176, 0, v124
	v_max_f32_e32 v177, 0, v125
	v_max_f32_e32 v178, 0, v126
	v_max_f32_e32 v179, 0, v127
	v_pk_add_f32 v[172:173], v[172:173], v[156:157] neg_lo:[0,1] neg_hi:[0,1]
	v_pk_add_f32 v[174:175], v[174:175], v[158:159] neg_lo:[0,1] neg_hi:[0,1]
	v_pk_add_f32 v[176:177], v[176:177], v[160:161] neg_lo:[0,1] neg_hi:[0,1]
	v_pk_add_f32 v[178:179], v[178:179], v[162:163] neg_lo:[0,1] neg_hi:[0,1]
	v_pk_mul_f32 v[172:173], v[172:173], v[112:113]
	v_pk_mul_f32 v[174:175], v[174:175], v[114:115]
	v_pk_mul_f32 v[176:177], v[176:177], v[116:117]
	v_pk_mul_f32 v[178:179], v[178:179], v[118:119]
	v_cvt_pk_bf16_f32 v180, v172, v173
	v_cvt_pk_bf16_f32 v181, v174, v175
	v_cvt_pk_bf16_f32 v182, v176, v177
	v_cvt_pk_bf16_f32 v183, v178, v179
	global_store_dwordx2 v218, v[180:181], s[10:11]
	global_store_dwordx2 v219, v[182:183], s[10:11]
	v_add_u32_e32 v210, 0x2c00, v210
	v_add_u32_e32 v211, 0x2c00, v210
	v_add_u32_e32 v212, v206, v211
	global_load_dwordx2 v[96:97], v212, s[6:7]
	v_add_u32_e32 v213, v207, v211
	global_load_dwordx2 v[98:99], v213, s[6:7]
	v_add_u32_e32 v214, v208, v211
	global_load_dwordx2 v[100:101], v214, s[6:7]
	v_add_u32_e32 v215, v209, v211
	global_load_dwordx2 v[102:103], v215, s[6:7]
	v_add_u32_e32 v218, v207, v210
	global_load_dwordx2 v[108:109], v218, s[8:9]
	v_add_u32_e32 v219, v208, v210
	global_load_dwordx2 v[110:111], v219, s[8:9]
	s_waitcnt vmcnt(8)
	v_lshlrev_b32_e32 v72, 16, v88
	v_and_b32_e32 v73, 0xffff0000, v88
	v_lshlrev_b32_e32 v74, 16, v89
	v_and_b32_e32 v75, 0xffff0000, v89
	v_lshlrev_b32_e32 v76, 16, v90
	v_and_b32_e32 v77, 0xffff0000, v90
	v_lshlrev_b32_e32 v78, 16, v91
	v_and_b32_e32 v79, 0xffff0000, v91
	v_lshlrev_b32_e32 v80, 16, v92
	v_and_b32_e32 v81, 0xffff0000, v92
	v_lshlrev_b32_e32 v82, 16, v93
	v_and_b32_e32 v83, 0xffff0000, v93
	v_lshlrev_b32_e32 v84, 16, v94
	v_and_b32_e32 v85, 0xffff0000, v94
	v_lshlrev_b32_e32 v86, 16, v95
	v_and_b32_e32 v87, 0xffff0000, v95
	v_pk_mul_f32 v[72:73], v[72:73], v[200:201]
	v_pk_mul_f32 v[74:75], v[74:75], v[200:201]
	v_pk_mul_f32 v[84:85], v[84:85], v[202:203]
	v_pk_mul_f32 v[86:87], v[86:87], v[202:203]
	v_lshlrev_b32_e32 v112, 16, v104
	v_and_b32_e32 v113, 0xffff0000, v104
	v_lshlrev_b32_e32 v114, 16, v105
	v_and_b32_e32 v115, 0xffff0000, v105
	v_lshlrev_b32_e32 v116, 16, v106
	v_and_b32_e32 v117, 0xffff0000, v106
	v_lshlrev_b32_e32 v118, 16, v107
	v_and_b32_e32 v119, 0xffff0000, v107
	v_pk_fma_f32 v[120:121], v[40:41], v[0:1], v[36:37]
	v_pk_fma_f32 v[122:123], v[42:43], v[2:3], v[38:39]
	v_pk_fma_f32 v[124:125], v[44:45], v[0:1], v[36:37]
	v_pk_fma_f32 v[126:127], v[46:47], v[2:3], v[38:39]
	v_pk_fma_f32 v[120:121], v[56:57], v[4:5], v[120:121]
	v_pk_fma_f32 v[122:123], v[58:59], v[6:7], v[122:123]
	v_pk_fma_f32 v[124:125], v[60:61], v[4:5], v[124:125]
	v_pk_fma_f32 v[126:127], v[62:63], v[6:7], v[126:127]
	v_pk_fma_f32 v[120:121], v[72:73], v[8:9], v[120:121]
	v_pk_fma_f32 v[122:123], v[74:75], v[10:11], v[122:123]
	v_pk_fma_f32 v[124:125], v[76:77], v[8:9], v[124:125]
	v_pk_fma_f32 v[126:127], v[78:79], v[10:11], v[126:127]
	v_pk_fma_f32 v[120:121], v[44:45], v[12:13], v[120:121]
	v_pk_fma_f32 v[122:123], v[46:47], v[14:15], v[122:123]
	v_pk_fma_f32 v[124:125], v[48:49], v[12:13], v[124:125]
	v_pk_fma_f32 v[126:127], v[50:51], v[14:15], v[126:127]
	v_pk_fma_f32 v[120:121], v[60:61], v[16:17], v[120:121]
	v_pk_fma_f32 v[122:123], v[62:63], v[18:19], v[122:123]
	v_pk_fma_f32 v[124:125], v[64:65], v[16:17], v[124:125]
	v_pk_fma_f32 v[126:127], v[66:67], v[18:19], v[126:127]
	v_pk_fma_f32 v[120:121], v[76:77], v[20:21], v[120:121]
	v_pk_fma_f32 v[122:123], v[78:79], v[22:23], v[122:123]
	v_pk_fma_f32 v[124:125], v[80:81], v[20:21], v[124:125]
	v_pk_fma_f32 v[126:127], v[82:83], v[22:23], v[126:127]
	v_pk_fma_f32 v[120:121], v[48:49], v[24:25], v[120:121]
	v_pk_fma_f32 v[122:123], v[50:51], v[26:27], v[122:123]
	v_pk_fma_f32 v[124:125], v[52:53], v[24:25], v[124:125]
	v_pk_fma_f32 v[126:127], v[54:55], v[26:27], v[126:127]
	v_pk_fma_f32 v[120:121], v[64:65], v[28:29], v[120:121]
	v_pk_fma_f32 v[122:123], v[66:67], v[30:31], v[122:123]
	v_pk_fma_f32 v[124:125], v[68:69], v[28:29], v[124:125]
	v_pk_fma_f32 v[126:127], v[70:71], v[30:31], v[126:127]
	v_pk_fma_f32 v[120:121], v[80:81], v[32:33], v[120:121]
	v_pk_fma_f32 v[122:123], v[82:83], v[34:35], v[122:123]
	v_pk_fma_f32 v[124:125], v[84:85], v[32:33], v[124:125]
	v_pk_fma_f32 v[126:127], v[86:87], v[34:35], v[126:127]
	v_and_b32_e32 v128, 0x7fffffff, v120
	v_and_b32_e32 v129, 0x7fffffff, v121
	v_and_b32_e32 v130, 0x7fffffff, v122
	v_and_b32_e32 v131, 0x7fffffff, v123
	v_and_b32_e32 v132, 0x7fffffff, v124
	v_and_b32_e32 v133, 0x7fffffff, v125
	v_and_b32_e32 v134, 0x7fffffff, v126
	v_and_b32_e32 v135, 0x7fffffff, v127
	v_pk_fma_f32 v[148:149], v[128:129], v[184:185], v[186:187]
	v_pk_fma_f32 v[150:151], v[130:131], v[184:185], v[186:187]
	v_pk_fma_f32 v[152:153], v[132:133], v[184:185], v[186:187]
	v_pk_fma_f32 v[154:155], v[134:135], v[184:185], v[186:187]
	v_rcp_f32_e32 v148, v148
	v_rcp_f32_e32 v149, v149
	v_rcp_f32_e32 v150, v150
	v_rcp_f32_e32 v151, v151
	v_rcp_f32_e32 v152, v152
	v_rcp_f32_e32 v153, v153
	v_rcp_f32_e32 v154, v154
; __device__ __forceinline__ unsigned cvt_pk_bf16(float lo, float hi) { unsigned r; asm volatile("v_cvt_pk_bf16_f32 %0, %1, %2" : "=v"(r) : "v"(lo), "v"(hi)); return r; }
; __device__ __forceinline__ float gelu_as(float v) {
;   const float av = fabsf(v); const float t = __builtin_amdgcn_rcpf(av * 0.2316418882f + 1.0f);
;   float q = t * 0.5307027145f + (-0.7265760135f); q = q * t + 0.7107068705f; q = q * t + (-0.142248368f); q = q * t + 0.127414796f; q = q * t;
;   const float e = __builtin_amdgcn_exp2f((v * v) * (-0.72134752044f));
;   const float m = v * (q * e);
;   return v < 0.f ? m : v - m;
; }
; __device__ __forceinline__ void phase_conv(KP p, int l, int tid) {
;     ...
;     for (int jb = j0; jb < j0 + 16; jb += CB) {
;       u32x2 an[CB][RB + 2], ur[CB][RB];
; #pragma unroll
;       for (int q = 0; q < CB; ++q) { const int col = jb + q + 1; const int cl = col > 63 ? 63 : col;
; #pragma unroll
;         for (int di = 0; di < RB + 2; ++di) an[q][di] = *(const u32x2*)(rowp[di] + (size_t)cl * DFF);
; #pragma unroll
;         for (int rr = 0; rr < RB; ++rr) ur[q][rr] = *(const u32x2*)(U + (size_t)((r0 + rr) * 64 + jb + q) * DFF + c0); }
;       __builtin_amdgcn_sched_barrier(0);
; #pragma unroll
;       for (int q = 0; q < CB; ++q) {
;         const int col = jb + q + 1;
; #pragma unroll
;         for (int di = 0; di < RB + 2; ++di) { const bool ok = rv[di] && (col < 64); unpack4(an[q][di], win[2][di]);
; #pragma unroll
;           for (int k = 0; k < 4; ++k) win[2][di][k] = ok ? win[2][di][k] : 0.f; }
; #pragma unroll
;         for (int rr = 0; rr < RB; ++rr) {
;           float uv[4]; unpack4(ur[q][rr], uv);
;           float o[4];
; #pragma unroll
;           for (int k = 0; k < 4; ++k) {
;             float a = bsv[k];
; #pragma unroll
;             for (int di = 0; di < 3; ++di)
; #pragma unroll
;               for (int dj = 0; dj < 3; ++dj) a += win[dj][rr + di][k] * w[di * 3 + dj][k];
;             o[k] = gelu_as(a) * uv[k];
;           }
;           u32x2 ow; ow.x = cvt_pk_bf16(o[0], o[1]); ow.y = cvt_pk_bf16(o[2], o[3]);
;           *(u32x2*)(G + (size_t)((r0 + rr) * 64 + jb + q) * DFF + c0) = ow;
	v_rcp_f32_e32 v155, v155
	v_pk_fma_f32 v[156:157], v[148:149], v[188:189], v[190:191]
	v_pk_fma_f32 v[158:159], v[150:151], v[188:189], v[190:191]
	v_pk_fma_f32 v[160:161], v[152:153], v[188:189], v[190:191]
	v_pk_fma_f32 v[162:163], v[154:155], v[188:189], v[190:191]
	v_pk_fma_f32 v[156:157], v[156:157], v[148:149], v[192:193]
	v_pk_fma_f32 v[158:159], v[158:159], v[150:151], v[192:193]
	v_pk_fma_f32 v[160:161], v[160:161], v[152:153], v[192:193]
	v_pk_fma_f32 v[162:163], v[162:163], v[154:155], v[192:193]
	v_pk_fma_f32 v[156:157], v[156:157], v[148:149], v[194:195]
	v_pk_fma_f32 v[158:159], v[158:159], v[150:151], v[194:195]
	v_pk_fma_f32 v[160:161], v[160:161], v[152:153], v[194:195]
	v_pk_fma_f32 v[162:163], v[162:163], v[154:155], v[194:195]
	v_pk_fma_f32 v[156:157], v[156:157], v[148:149], v[196:197]
	v_pk_fma_f32 v[158:159], v[158:159], v[150:151], v[196:197]
	v_pk_fma_f32 v[160:161], v[160:161], v[152:153], v[196:197]
	v_pk_fma_f32 v[162:163], v[162:163], v[154:155], v[196:197]
	v_pk_mul_f32 v[156:157], v[156:157], v[148:149]
	v_pk_mul_f32 v[158:159], v[158:159], v[150:151]
	v_pk_mul_f32 v[160:161], v[160:161], v[152:153]
	v_pk_mul_f32 v[162:163], v[162:163], v[154:155]
	v_pk_mul_f32 v[164:165], v[120:121], v[120:121]
	v_pk_mul_f32 v[166:167], v[122:123], v[122:123]
	v_pk_mul_f32 v[168:169], v[124:125], v[124:125]
	v_pk_mul_f32 v[170:171], v[126:127], v[126:127]
	v_pk_mul_f32 v[164:165], v[164:165], v[198:199]
	v_pk_mul_f32 v[166:167], v[166:167], v[198:199]
	v_pk_mul_f32 v[168:169], v[168:169], v[198:199]
	v_pk_mul_f32 v[170:171], v[170:171], v[198:199]
	v_exp_f32_e32 v164, v164
	v_exp_f32_e32 v165, v165
	v_exp_f32_e32 v166, v166
	v_exp_f32_e32 v167, v167
	v_exp_f32_e32 v168, v168
	v_exp_f32_e32 v169, v169
	v_exp_f32_e32 v170, v170
	v_exp_f32_e32 v171, v171
	v_pk_mul_f32 v[156:157], v[156:157], v[164:165]
	v_pk_mul_f32 v[158:159], v[158:159], v[166:167]
	v_pk_mul_f32 v[160:161], v[160:161], v[168:169]
	v_pk_mul_f32 v[162:163], v[162:163], v[170:171]
	v_pk_mul_f32 v[156:157], v[128:129], v[156:157]
	v_pk_mul_f32 v[158:159], v[130:131], v[158:159]
	v_pk_mul_f32 v[160:161], v[132:133], v[160:161]
	v_pk_mul_f32 v[162:163], v[134:135], v[162:163]
	v_max_f32_e32 v172, 0, v120
	v_max_f32_e32 v173, 0, v121
	v_max_f32_e32 v174, 0, v122
	v_max_f32_e32 v175, 0, v123
	v_max_f32_e32 v176, 0, v124
	v_max_f32_e32 v177, 0, v125
	v_max_f32_e32 v178, 0, v126
	v_max_f32_e32 v179, 0, v127
	v_pk_add_f32 v[172:173], v[172:173], v[156:157] neg_lo:[0,1] neg_hi:[0,1]
	v_pk_add_f32 v[174:175], v[174:175], v[158:159] neg_lo:[0,1] neg_hi:[0,1]
	v_pk_add_f32 v[176:177], v[176:177], v[160:161] neg_lo:[0,1] neg_hi:[0,1]
	v_pk_add_f32 v[178:179], v[178:179], v[162:163] neg_lo:[0,1] neg_hi:[0,1]
	v_pk_mul_f32 v[172:173], v[172:173], v[112:113]
	v_pk_mul_f32 v[174:175], v[174:175], v[114:115]
	v_pk_mul_f32 v[176:177], v[176:177], v[116:117]
	v_pk_mul_f32 v[178:179], v[178:179], v[118:119]
	v_cvt_pk_bf16_f32 v180, v172, v173
	v_cvt_pk_bf16_f32 v181, v174, v175
	v_cvt_pk_bf16_f32 v182, v176, v177
	v_cvt_pk_bf16_f32 v183, v178, v179
	global_store_dwordx2 v216, v[180:181], s[10:11]
	global_store_dwordx2 v217, v[182:183], s[10:11]
	v_add_u32_e32 v210, 0x2c00, v210
	v_add_u32_e32 v211, 0x2c00, v210
	v_add_u32_e32 v212, v206, v211
	global_load_dwordx2 v[88:89], v212, s[6:7]
	v_add_u32_e32 v213, v207, v211
	global_load_dwordx2 v[90:91], v213, s[6:7]
	v_add_u32_e32 v214, v208, v211
	global_load_dwordx2 v[92:93], v214, s[6:7]
	v_add_u32_e32 v215, v209, v211
	global_load_dwordx2 v[94:95], v215, s[6:7]
	v_add_u32_e32 v216, v207, v210
	global_load_dwordx2 v[104:105], v216, s[8:9]
	v_add_u32_e32 v217, v208, v210
	global_load_dwordx2 v[106:107], v217, s[8:9]
	s_waitcnt vmcnt(8)
	v_lshlrev_b32_e32 v40, 16, v96
	v_and_b32_e32 v41, 0xffff0000, v96
	v_lshlrev_b32_e32 v42, 16, v97
	v_and_b32_e32 v43, 0xffff0000, v97
	v_lshlrev_b32_e32 v44, 16, v98
	v_and_b32_e32 v45, 0xffff0000, v98
	v_lshlrev_b32_e32 v46, 16, v99
	v_and_b32_e32 v47, 0xffff0000, v99
	v_lshlrev_b32_e32 v48, 16, v100
	v_and_b32_e32 v49, 0xffff0000, v100
	v_lshlrev_b32_e32 v50, 16, v101
	v_and_b32_e32 v51, 0xffff0000, v101
	v_lshlrev_b32_e32 v52, 16, v102
	v_and_b32_e32 v53, 0xffff0000, v102
	v_lshlrev_b32_e32 v54, 16, v103
	v_and_b32_e32 v55, 0xffff0000, v103
	v_pk_mul_f32 v[40:41], v[40:41], v[200:201]
	v_pk_mul_f32 v[42:43], v[42:43], v[200:201]
	v_pk_mul_f32 v[52:53], v[52:53], v[202:203]
	v_pk_mul_f32 v[54:55], v[54:55], v[202:203]
	v_lshlrev_b32_e32 v112, 16, v108
	v_and_b32_e32 v113, 0xffff0000, v108
	v_lshlrev_b32_e32 v114, 16, v109
	v_and_b32_e32 v115, 0xffff0000, v109
	v_lshlrev_b32_e32 v116, 16, v110
	v_and_b32_e32 v117, 0xffff0000, v110
	v_lshlrev_b32_e32 v118, 16, v111
	v_and_b32_e32 v119, 0xffff0000, v111
	v_pk_fma_f32 v[120:121], v[56:57], v[0:1], v[36:37]
	v_pk_fma_f32 v[122:123], v[58:59], v[2:3], v[38:39]
	v_pk_fma_f32 v[124:125], v[60:61], v[0:1], v[36:37]
	v_pk_fma_f32 v[126:127], v[62:63], v[2:3], v[38:39]
	v_pk_fma_f32 v[120:121], v[72:73], v[4:5], v[120:121]
	v_pk_fma_f32 v[122:123], v[74:75], v[6:7], v[122:123]
	v_pk_fma_f32 v[124:125], v[76:77], v[4:5], v[124:125]
	v_pk_fma_f32 v[126:127], v[78:79], v[6:7], v[126:127]
	v_pk_fma_f32 v[120:121], v[40:41], v[8:9], v[120:121]
	v_pk_fma_f32 v[122:123], v[42:43], v[10:11], v[122:123]
	v_pk_fma_f32 v[124:125], v[44:45], v[8:9], v[124:125]
	v_pk_fma_f32 v[126:127], v[46:47], v[10:11], v[126:127]
	v_pk_fma_f32 v[120:121], v[60:61], v[12:13], v[120:121]
	v_pk_fma_f32 v[122:123], v[62:63], v[14:15], v[122:123]
	v_pk_fma_f32 v[124:125], v[64:65], v[12:13], v[124:125]
	v_pk_fma_f32 v[126:127], v[66:67], v[14:15], v[126:127]
; __device__ __forceinline__ unsigned cvt_pk_bf16(float lo, float hi) { unsigned r; asm volatile("v_cvt_pk_bf16_f32 %0, %1, %2" : "=v"(r) : "v"(lo), "v"(hi)); return r; }
; __device__ __forceinline__ float gelu_as(float v) {
;   const float av = fabsf(v); const float t = __builtin_amdgcn_rcpf(av * 0.2316418882f + 1.0f);
;   float q = t * 0.5307027145f + (-0.7265760135f); q = q * t + 0.7107068705f; q = q * t + (-0.142248368f); q = q * t + 0.127414796f; q = q * t;
;   const float e = __builtin_amdgcn_exp2f((v * v) * (-0.72134752044f));
;   const float m = v * (q * e);
;   return v < 0.f ? m : v - m;
; }
; __device__ __forceinline__ void phase_conv(KP p, int l, int tid) {
;     ...
;     for (int jb = j0; jb < j0 + 16; jb += CB) {
;       u32x2 an[CB][RB + 2], ur[CB][RB];
; #pragma unroll
;       for (int q = 0; q < CB; ++q) { const int col = jb + q + 1; const int cl = col > 63 ? 63 : col;
; #pragma unroll
;         for (int di = 0; di < RB + 2; ++di) an[q][di] = *(const u32x2*)(rowp[di] + (size_t)cl * DFF);
; #pragma unroll
;         for (int rr = 0; rr < RB; ++rr) ur[q][rr] = *(const u32x2*)(U + (size_t)((r0 + rr) * 64 + jb + q) * DFF + c0); }
;       __builtin_amdgcn_sched_barrier(0);
; #pragma unroll
;       for (int q = 0; q < CB; ++q) {
;         const int col = jb + q + 1;
; #pragma unroll
;         for (int di = 0; di < RB + 2; ++di) { const bool ok = rv[di] && (col < 64); unpack4(an[q][di], win[2][di]);
; #pragma unroll
;           for (int k = 0; k < 4; ++k) win[2][di][k] = ok ? win[2][di][k] : 0.f; }
; #pragma unroll
;         for (int rr = 0; rr < RB; ++rr) {
;           float uv[4]; unpack4(ur[q][rr], uv);
;           float o[4];
; #pragma unroll
;           for (int k = 0; k < 4; ++k) {
;             float a = bsv[k];
; #pragma unroll
;             for (int di = 0; di < 3; ++di)
; #pragma unroll
;               for (int dj = 0; dj < 3; ++dj) a += win[dj][rr + di][k] * w[di * 3 + dj][k];
;             o[k] = gelu_as(a) * uv[k];
;           }
;           u32x2 ow; ow.x = cvt_pk_bf16(o[0], o[1]); ow.y = cvt_pk_bf16(o[2], o[3]);
;           *(u32x2*)(G + (size_t)((r0 + rr) * 64 + jb + q) * DFF + c0) = ow;
	v_pk_fma_f32 v[120:121], v[76:77], v[16:17], v[120:121]
	v_pk_fma_f32 v[122:123], v[78:79], v[18:19], v[122:123]
	v_pk_fma_f32 v[124:125], v[80:81], v[16:17], v[124:125]
	v_pk_fma_f32 v[126:127], v[82:83], v[18:19], v[126:127]
	v_pk_fma_f32 v[120:121], v[44:45], v[20:21], v[120:121]
	v_pk_fma_f32 v[122:123], v[46:47], v[22:23], v[122:123]
	v_pk_fma_f32 v[124:125], v[48:49], v[20:21], v[124:125]
	v_pk_fma_f32 v[126:127], v[50:51], v[22:23], v[126:127]
	v_pk_fma_f32 v[120:121], v[64:65], v[24:25], v[120:121]
	v_pk_fma_f32 v[122:123], v[66:67], v[26:27], v[122:123]
	v_pk_fma_f32 v[124:125], v[68:69], v[24:25], v[124:125]
	v_pk_fma_f32 v[126:127], v[70:71], v[26:27], v[126:127]
	v_pk_fma_f32 v[120:121], v[80:81], v[28:29], v[120:121]
	v_pk_fma_f32 v[122:123], v[82:83], v[30:31], v[122:123]
	v_pk_fma_f32 v[124:125], v[84:85], v[28:29], v[124:125]
	v_pk_fma_f32 v[126:127], v[86:87], v[30:31], v[126:127]
	v_pk_fma_f32 v[120:121], v[48:49], v[32:33], v[120:121]
	v_pk_fma_f32 v[122:123], v[50:51], v[34:35], v[122:123]
	v_pk_fma_f32 v[124:125], v[52:53], v[32:33], v[124:125]
	v_pk_fma_f32 v[126:127], v[54:55], v[34:35], v[126:127]
	v_and_b32_e32 v128, 0x7fffffff, v120
	v_and_b32_e32 v129, 0x7fffffff, v121
	v_and_b32_e32 v130, 0x7fffffff, v122
	v_and_b32_e32 v131, 0x7fffffff, v123
	v_and_b32_e32 v132, 0x7fffffff, v124
	v_and_b32_e32 v133, 0x7fffffff, v125
	v_and_b32_e32 v134, 0x7fffffff, v126
	v_and_b32_e32 v135, 0x7fffffff, v127
	v_pk_fma_f32 v[148:149], v[128:129], v[184:185], v[186:187]
	v_pk_fma_f32 v[150:151], v[130:131], v[184:185], v[186:187]
	v_pk_fma_f32 v[152:153], v[132:133], v[184:185], v[186:187]
	v_pk_fma_f32 v[154:155], v[134:135], v[184:185], v[186:187]
	v_rcp_f32_e32 v148, v148
	v_rcp_f32_e32 v149, v149
	v_rcp_f32_e32 v150, v150
	v_rcp_f32_e32 v151, v151
	v_rcp_f32_e32 v152, v152
	v_rcp_f32_e32 v153, v153
	v_rcp_f32_e32 v154, v154
	v_rcp_f32_e32 v155, v155
	v_pk_fma_f32 v[156:157], v[148:149], v[188:189], v[190:191]
	v_pk_fma_f32 v[158:159], v[150:151], v[188:189], v[190:191]
	v_pk_fma_f32 v[160:161], v[152:153], v[188:189], v[190:191]
	v_pk_fma_f32 v[162:163], v[154:155], v[188:189], v[190:191]
	v_pk_fma_f32 v[156:157], v[156:157], v[148:149], v[192:193]
	v_pk_fma_f32 v[158:159], v[158:159], v[150:151], v[192:193]
	v_pk_fma_f32 v[160:161], v[160:161], v[152:153], v[192:193]
	v_pk_fma_f32 v[162:163], v[162:163], v[154:155], v[192:193]
	v_pk_fma_f32 v[156:157], v[156:157], v[148:149], v[194:195]
	v_pk_fma_f32 v[158:159], v[158:159], v[150:151], v[194:195]
	v_pk_fma_f32 v[160:161], v[160:161], v[152:153], v[194:195]
	v_pk_fma_f32 v[162:163], v[162:163], v[154:155], v[194:195]
	v_pk_fma_f32 v[156:157], v[156:157], v[148:149], v[196:197]
	v_pk_fma_f32 v[158:159], v[158:159], v[150:151], v[196:197]
	v_pk_fma_f32 v[160:161], v[160:161], v[152:153], v[196:197]
	v_pk_fma_f32 v[162:163], v[162:163], v[154:155], v[196:197]
	v_pk_mul_f32 v[156:157], v[156:157], v[148:149]
	v_pk_mul_f32 v[158:159], v[158:159], v[150:151]
	v_pk_mul_f32 v[160:161], v[160:161], v[152:153]
	v_pk_mul_f32 v[162:163], v[162:163], v[154:155]
	v_pk_mul_f32 v[164:165], v[120:121], v[120:121]
	v_pk_mul_f32 v[166:167], v[122:123], v[122:123]
	v_pk_mul_f32 v[168:169], v[124:125], v[124:125]
	v_pk_mul_f32 v[170:171], v[126:127], v[126:127]
	v_pk_mul_f32 v[164:165], v[164:165], v[198:199]
	v_pk_mul_f32 v[166:167], v[166:167], v[198:199]
	v_pk_mul_f32 v[168:169], v[168:169], v[198:199]
	v_pk_mul_f32 v[170:171], v[170:171], v[198:199]
	v_exp_f32_e32 v164, v164
	v_exp_f32_e32 v165, v165
	v_exp_f32_e32 v166, v166
	v_exp_f32_e32 v167, v167
	v_exp_f32_e32 v168, v168
	v_exp_f32_e32 v169, v169
	v_exp_f32_e32 v170, v170
	v_exp_f32_e32 v171, v171
	v_pk_mul_f32 v[156:157], v[156:157], v[164:165]
	v_pk_mul_f32 v[158:159], v[158:159], v[166:167]
	v_pk_mul_f32 v[160:161], v[160:161], v[168:169]
	v_pk_mul_f32 v[162:163], v[162:163], v[170:171]
	v_pk_mul_f32 v[156:157], v[128:129], v[156:157]
	v_pk_mul_f32 v[158:159], v[130:131], v[158:159]
	v_pk_mul_f32 v[160:161], v[132:133], v[160:161]
	v_pk_mul_f32 v[162:163], v[134:135], v[162:163]
	v_max_f32_e32 v172, 0, v120
	v_max_f32_e32 v173, 0, v121
	v_max_f32_e32 v174, 0, v122
	v_max_f32_e32 v175, 0, v123
	v_max_f32_e32 v176, 0, v124
	v_max_f32_e32 v177, 0, v125
	v_max_f32_e32 v178, 0, v126
	v_max_f32_e32 v179, 0, v127
	v_pk_add_f32 v[172:173], v[172:173], v[156:157] neg_lo:[0,1] neg_hi:[0,1]
	v_pk_add_f32 v[174:175], v[174:175], v[158:159] neg_lo:[0,1] neg_hi:[0,1]
	v_pk_add_f32 v[176:177], v[176:177], v[160:161] neg_lo:[0,1] neg_hi:[0,1]
	v_pk_add_f32 v[178:179], v[178:179], v[162:163] neg_lo:[0,1] neg_hi:[0,1]
	v_pk_mul_f32 v[172:173], v[172:173], v[112:113]
	v_pk_mul_f32 v[174:175], v[174:175], v[114:115]
	v_pk_mul_f32 v[176:177], v[176:177], v[116:117]
	v_pk_mul_f32 v[178:179], v[178:179], v[118:119]
	v_cvt_pk_bf16_f32 v180, v172, v173
	v_cvt_pk_bf16_f32 v181, v174, v175
	v_cvt_pk_bf16_f32 v182, v176, v177
	v_cvt_pk_bf16_f32 v183, v178, v179
	global_store_dwordx2 v218, v[180:181], s[10:11]
	global_store_dwordx2 v219, v[182:183], s[10:11]
	v_add_u32_e32 v210, 0x2c00, v210
	v_add_u32_e32 v211, 0x2c00, v210
	v_min_u32_e32 v211, 0xad400, v211
	v_add_u32_e32 v212, v206, v211
	global_load_dwordx2 v[96:97], v212, s[6:7]
	v_add_u32_e32 v213, v207, v211
	global_load_dwordx2 v[98:99], v213, s[6:7]
	v_add_u32_e32 v214, v208, v211
	global_load_dwordx2 v[100:101], v214, s[6:7]
	v_add_u32_e32 v215, v209, v211
	global_load_dwordx2 v[102:103], v215, s[6:7]
	v_add_u32_e32 v218, v207, v210
	global_load_dwordx2 v[108:109], v218, s[8:9]
	v_add_u32_e32 v219, v208, v210
	global_load_dwordx2 v[110:111], v219, s[8:9]
	s_waitcnt vmcnt(8)
; __device__ __forceinline__ unsigned cvt_pk_bf16(float lo, float hi) { unsigned r; asm volatile("v_cvt_pk_bf16_f32 %0, %1, %2" : "=v"(r) : "v"(lo), "v"(hi)); return r; }
; __device__ __forceinline__ float gelu_as(float v) {
;   const float av = fabsf(v); const float t = __builtin_amdgcn_rcpf(av * 0.2316418882f + 1.0f);
;   float q = t * 0.5307027145f + (-0.7265760135f); q = q * t + 0.7107068705f; q = q * t + (-0.142248368f); q = q * t + 0.127414796f; q = q * t;
;   const float e = __builtin_amdgcn_exp2f((v * v) * (-0.72134752044f));
;   const float m = v * (q * e);
;   return v < 0.f ? m : v - m;
; }
; __device__ __forceinline__ void phase_conv(KP p, int l, int tid) {
;     ...
;     for (int jb = j0; jb < j0 + 16; jb += CB) {
;       u32x2 an[CB][RB + 2], ur[CB][RB];
; #pragma unroll
;       for (int q = 0; q < CB; ++q) { const int col = jb + q + 1; const int cl = col > 63 ? 63 : col;
; #pragma unroll
;         for (int di = 0; di < RB + 2; ++di) an[q][di] = *(const u32x2*)(rowp[di] + (size_t)cl * DFF);
; #pragma unroll
;         for (int rr = 0; rr < RB; ++rr) ur[q][rr] = *(const u32x2*)(U + (size_t)((r0 + rr) * 64 + jb + q) * DFF + c0); }
;       __builtin_amdgcn_sched_barrier(0);
; #pragma unroll
;       for (int q = 0; q < CB; ++q) {
;         const int col = jb + q + 1;
; #pragma unroll
;         for (int di = 0; di < RB + 2; ++di) { const bool ok = rv[di] && (col < 64); unpack4(an[q][di], win[2][di]);
; #pragma unroll
;           for (int k = 0; k < 4; ++k) win[2][di][k] = ok ? win[2][di][k] : 0.f; }
; #pragma unroll
;         for (int rr = 0; rr < RB; ++rr) {
;           float uv[4]; unpack4(ur[q][rr], uv);
;           float o[4];
; #pragma unroll
;           for (int k = 0; k < 4; ++k) {
;             float a = bsv[k];
; #pragma unroll
;             for (int di = 0; di < 3; ++di)
; #pragma unroll
;               for (int dj = 0; dj < 3; ++dj) a += win[dj][rr + di][k] * w[di * 3 + dj][k];
;             o[k] = gelu_as(a) * uv[k];
;           }
;           u32x2 ow; ow.x = cvt_pk_bf16(o[0], o[1]); ow.y = cvt_pk_bf16(o[2], o[3]);
;           *(u32x2*)(G + (size_t)((r0 + rr) * 64 + jb + q) * DFF + c0) = ow;
	v_lshlrev_b32_e32 v56, 16, v88
	v_and_b32_e32 v57, 0xffff0000, v88
	v_lshlrev_b32_e32 v58, 16, v89
	v_and_b32_e32 v59, 0xffff0000, v89
	v_lshlrev_b32_e32 v60, 16, v90
	v_and_b32_e32 v61, 0xffff0000, v90
	v_lshlrev_b32_e32 v62, 16, v91
	v_and_b32_e32 v63, 0xffff0000, v91
	v_lshlrev_b32_e32 v64, 16, v92
	v_and_b32_e32 v65, 0xffff0000, v92
	v_lshlrev_b32_e32 v66, 16, v93
	v_and_b32_e32 v67, 0xffff0000, v93
	v_lshlrev_b32_e32 v68, 16, v94
	v_and_b32_e32 v69, 0xffff0000, v94
	v_lshlrev_b32_e32 v70, 16, v95
	v_and_b32_e32 v71, 0xffff0000, v95
	v_pk_mul_f32 v[56:57], v[56:57], v[200:201]
	v_pk_mul_f32 v[58:59], v[58:59], v[200:201]
	v_pk_mul_f32 v[68:69], v[68:69], v[202:203]
	v_pk_mul_f32 v[70:71], v[70:71], v[202:203]
	v_lshlrev_b32_e32 v112, 16, v104
	v_and_b32_e32 v113, 0xffff0000, v104
	v_lshlrev_b32_e32 v114, 16, v105
	v_and_b32_e32 v115, 0xffff0000, v105
	v_lshlrev_b32_e32 v116, 16, v106
	v_and_b32_e32 v117, 0xffff0000, v106
	v_lshlrev_b32_e32 v118, 16, v107
	v_and_b32_e32 v119, 0xffff0000, v107
	v_pk_fma_f32 v[120:121], v[72:73], v[0:1], v[36:37]
	v_pk_fma_f32 v[122:123], v[74:75], v[2:3], v[38:39]
	v_pk_fma_f32 v[124:125], v[76:77], v[0:1], v[36:37]
	v_pk_fma_f32 v[126:127], v[78:79], v[2:3], v[38:39]
	v_pk_fma_f32 v[120:121], v[40:41], v[4:5], v[120:121]
	v_pk_fma_f32 v[122:123], v[42:43], v[6:7], v[122:123]
	v_pk_fma_f32 v[124:125], v[44:45], v[4:5], v[124:125]
	v_pk_fma_f32 v[126:127], v[46:47], v[6:7], v[126:127]
	v_pk_fma_f32 v[120:121], v[56:57], v[8:9], v[120:121]
	v_pk_fma_f32 v[122:123], v[58:59], v[10:11], v[122:123]
	v_pk_fma_f32 v[124:125], v[60:61], v[8:9], v[124:125]
	v_pk_fma_f32 v[126:127], v[62:63], v[10:11], v[126:127]
	v_pk_fma_f32 v[120:121], v[76:77], v[12:13], v[120:121]
	v_pk_fma_f32 v[122:123], v[78:79], v[14:15], v[122:123]
	v_pk_fma_f32 v[124:125], v[80:81], v[12:13], v[124:125]
	v_pk_fma_f32 v[126:127], v[82:83], v[14:15], v[126:127]
	v_pk_fma_f32 v[120:121], v[44:45], v[16:17], v[120:121]
	v_pk_fma_f32 v[122:123], v[46:47], v[18:19], v[122:123]
	v_pk_fma_f32 v[124:125], v[48:49], v[16:17], v[124:125]
	v_pk_fma_f32 v[126:127], v[50:51], v[18:19], v[126:127]
	v_pk_fma_f32 v[120:121], v[60:61], v[20:21], v[120:121]
	v_pk_fma_f32 v[122:123], v[62:63], v[22:23], v[122:123]
	v_pk_fma_f32 v[124:125], v[64:65], v[20:21], v[124:125]
	v_pk_fma_f32 v[126:127], v[66:67], v[22:23], v[126:127]
	v_pk_fma_f32 v[120:121], v[80:81], v[24:25], v[120:121]
	v_pk_fma_f32 v[122:123], v[82:83], v[26:27], v[122:123]
	v_pk_fma_f32 v[124:125], v[84:85], v[24:25], v[124:125]
	v_pk_fma_f32 v[126:127], v[86:87], v[26:27], v[126:127]
	v_pk_fma_f32 v[120:121], v[48:49], v[28:29], v[120:121]
	v_pk_fma_f32 v[122:123], v[50:51], v[30:31], v[122:123]
	v_pk_fma_f32 v[124:125], v[52:53], v[28:29], v[124:125]
	v_pk_fma_f32 v[126:127], v[54:55], v[30:31], v[126:127]
	v_pk_fma_f32 v[120:121], v[64:65], v[32:33], v[120:121]
	v_pk_fma_f32 v[122:123], v[66:67], v[34:35], v[122:123]
	v_pk_fma_f32 v[124:125], v[68:69], v[32:33], v[124:125]
	v_pk_fma_f32 v[126:127], v[70:71], v[34:35], v[126:127]
	v_and_b32_e32 v128, 0x7fffffff, v120
	v_and_b32_e32 v129, 0x7fffffff, v121
	v_and_b32_e32 v130, 0x7fffffff, v122
	v_and_b32_e32 v131, 0x7fffffff, v123
	v_and_b32_e32 v132, 0x7fffffff, v124
	v_and_b32_e32 v133, 0x7fffffff, v125
	v_and_b32_e32 v134, 0x7fffffff, v126
	v_and_b32_e32 v135, 0x7fffffff, v127
	v_pk_fma_f32 v[148:149], v[128:129], v[184:185], v[186:187]
	v_pk_fma_f32 v[150:151], v[130:131], v[184:185], v[186:187]
	v_pk_fma_f32 v[152:153], v[132:133], v[184:185], v[186:187]
	v_pk_fma_f32 v[154:155], v[134:135], v[184:185], v[186:187]
	v_rcp_f32_e32 v148, v148
	v_rcp_f32_e32 v149, v149
	v_rcp_f32_e32 v150, v150
	v_rcp_f32_e32 v151, v151
	v_rcp_f32_e32 v152, v152
	v_rcp_f32_e32 v153, v153
	v_rcp_f32_e32 v154, v154
	v_rcp_f32_e32 v155, v155
	v_pk_fma_f32 v[156:157], v[148:149], v[188:189], v[190:191]
	v_pk_fma_f32 v[158:159], v[150:151], v[188:189], v[190:191]
	v_pk_fma_f32 v[160:161], v[152:153], v[188:189], v[190:191]
	v_pk_fma_f32 v[162:163], v[154:155], v[188:189], v[190:191]
	v_pk_fma_f32 v[156:157], v[156:157], v[148:149], v[192:193]
	v_pk_fma_f32 v[158:159], v[158:159], v[150:151], v[192:193]
	v_pk_fma_f32 v[160:161], v[160:161], v[152:153], v[192:193]
	v_pk_fma_f32 v[162:163], v[162:163], v[154:155], v[192:193]
	v_pk_fma_f32 v[156:157], v[156:157], v[148:149], v[194:195]
	v_pk_fma_f32 v[158:159], v[158:159], v[150:151], v[194:195]
	v_pk_fma_f32 v[160:161], v[160:161], v[152:153], v[194:195]
	v_pk_fma_f32 v[162:163], v[162:163], v[154:155], v[194:195]
	v_pk_fma_f32 v[156:157], v[156:157], v[148:149], v[196:197]
	v_pk_fma_f32 v[158:159], v[158:159], v[150:151], v[196:197]
	v_pk_fma_f32 v[160:161], v[160:161], v[152:153], v[196:197]
	v_pk_fma_f32 v[162:163], v[162:163], v[154:155], v[196:197]
	v_pk_mul_f32 v[156:157], v[156:157], v[148:149]
	v_pk_mul_f32 v[158:159], v[158:159], v[150:151]
	v_pk_mul_f32 v[160:161], v[160:161], v[152:153]
	v_pk_mul_f32 v[162:163], v[162:163], v[154:155]
	v_pk_mul_f32 v[164:165], v[120:121], v[120:121]
	v_pk_mul_f32 v[166:167], v[122:123], v[122:123]
	v_pk_mul_f32 v[168:169], v[124:125], v[124:125]
	v_pk_mul_f32 v[170:171], v[126:127], v[126:127]
	v_pk_mul_f32 v[164:165], v[164:165], v[198:199]
	v_pk_mul_f32 v[166:167], v[166:167], v[198:199]
	v_pk_mul_f32 v[168:169], v[168:169], v[198:199]
	v_pk_mul_f32 v[170:171], v[170:171], v[198:199]
	v_exp_f32_e32 v164, v164
	v_exp_f32_e32 v165, v165
	v_exp_f32_e32 v166, v166
	v_exp_f32_e32 v167, v167
	v_exp_f32_e32 v168, v168
	v_exp_f32_e32 v169, v169
	v_exp_f32_e32 v170, v170
	v_exp_f32_e32 v171, v171
	v_pk_mul_f32 v[156:157], v[156:157], v[164:165]
	v_pk_mul_f32 v[158:159], v[158:159], v[166:167]
	v_pk_mul_f32 v[160:161], v[160:161], v[168:169]
	v_pk_mul_f32 v[162:163], v[162:163], v[170:171]
	v_pk_mul_f32 v[156:157], v[128:129], v[156:157]
	v_pk_mul_f32 v[158:159], v[130:131], v[158:159]
	v_pk_mul_f32 v[160:161], v[132:133], v[160:161]
	v_pk_mul_f32 v[162:163], v[134:135], v[162:163]
	v_max_f32_e32 v172, 0, v120
	v_max_f32_e32 v173, 0, v121
	v_max_f32_e32 v174, 0, v122
	v_max_f32_e32 v175, 0, v123
	v_max_f32_e32 v176, 0, v124
	v_max_f32_e32 v177, 0, v125
	v_max_f32_e32 v178, 0, v126
	v_max_f32_e32 v179, 0, v127
	v_pk_add_f32 v[172:173], v[172:173], v[156:157] neg_lo:[0,1] neg_hi:[0,1]
	v_pk_add_f32 v[174:175], v[174:175], v[158:159] neg_lo:[0,1] neg_hi:[0,1]
	v_pk_add_f32 v[176:177], v[176:177], v[160:161] neg_lo:[0,1] neg_hi:[0,1]
	v_pk_add_f32 v[178:179], v[178:179], v[162:163] neg_lo:[0,1] neg_hi:[0,1]
	v_pk_mul_f32 v[172:173], v[172:173], v[112:113]
	v_pk_mul_f32 v[174:175], v[174:175], v[114:115]
	v_pk_mul_f32 v[176:177], v[176:177], v[116:117]
	v_pk_mul_f32 v[178:179], v[178:179], v[118:119]
	v_cvt_pk_bf16_f32 v180, v172, v173
	v_cvt_pk_bf16_f32 v181, v174, v175
	v_cvt_pk_bf16_f32 v182, v176, v177
	v_cvt_pk_bf16_f32 v183, v178, v179
	global_store_dwordx2 v216, v[180:181], s[10:11]
	global_store_dwordx2 v217, v[182:183], s[10:11]
	s_waitcnt vmcnt(2)
; __device__ __forceinline__ void phase_conv(KP p, int l, int tid) {
;     ...
;     for (int jb = j0; jb < j0 + 16; jb += CB) {
;       u32x2 an[CB][RB + 2], ur[CB][RB];
; #pragma unroll
;       for (int q = 0; q < CB; ++q) { const int col = jb + q + 1; const int cl = col > 63 ? 63 : col;
; #pragma unroll
;         for (int di = 0; di < RB + 2; ++di) an[q][di] = *(const u32x2*)(rowp[di] + (size_t)cl * DFF);
; #pragma unroll
;         for (int rr = 0; rr < RB; ++rr) ur[q][rr] = *(const u32x2*)(U + (size_t)((r0 + rr) * 64 + jb + q) * DFF + c0); }
;       __builtin_amdgcn_sched_barrier(0);
; #pragma unroll
;       for (int q = 0; q < CB; ++q) {
;         const int col = jb + q + 1;
; #pragma unroll
;         for (int di = 0; di < RB + 2; ++di) { const bool ok = rv[di] && (col < 64); unpack4(an[q][di], win[2][di]);
; #pragma unroll
;           for (int k = 0; k < 4; ++k) win[2][di][k] = ok ? win[2][di][k] : 0.f; }
; #pragma unroll
;         for (int rr = 0; rr < RB; ++rr) {
;           float uv[4]; unpack4(ur[q][rr], uv);
;           float o[4];
; #pragma unroll
;           for (int k = 0; k < 4; ++k) {
;             float a = bsv[k];
; #pragma unroll
;             for (int di = 0; di < 3; ++di)
; #pragma unroll
;               for (int dj = 0; dj < 3; ++dj) a += win[dj][rr + di][k] * w[di * 3 + dj][k];
	v_lshlrev_b32_e32 v72, 16, v96
	v_and_b32_e32 v73, 0xffff0000, v96
	v_lshlrev_b32_e32 v74, 16, v97
	v_and_b32_e32 v75, 0xffff0000, v97
	v_lshlrev_b32_e32 v76, 16, v98
	v_and_b32_e32 v77, 0xffff0000, v98
	v_lshlrev_b32_e32 v78, 16, v99
	v_and_b32_e32 v79, 0xffff0000, v99
	v_lshlrev_b32_e32 v80, 16, v100
	v_and_b32_e32 v81, 0xffff0000, v100
	v_lshlrev_b32_e32 v82, 16, v101
	v_and_b32_e32 v83, 0xffff0000, v101
	v_lshlrev_b32_e32 v84, 16, v102
	v_and_b32_e32 v85, 0xffff0000, v102
	v_lshlrev_b32_e32 v86, 16, v103
	v_and_b32_e32 v87, 0xffff0000, v103
	v_pk_mul_f32 v[72:73], v[72:73], v[200:201]
	v_pk_mul_f32 v[74:75], v[74:75], v[200:201]
	v_pk_mul_f32 v[84:85], v[84:85], v[202:203]
	v_pk_mul_f32 v[86:87], v[86:87], v[202:203]
	v_pk_mul_f32 v[72:73], v[72:73], v[204:205]
	v_pk_mul_f32 v[74:75], v[74:75], v[204:205]
	v_pk_mul_f32 v[76:77], v[76:77], v[204:205]
	v_pk_mul_f32 v[78:79], v[78:79], v[204:205]
	v_pk_mul_f32 v[80:81], v[80:81], v[204:205]
	v_pk_mul_f32 v[82:83], v[82:83], v[204:205]
	v_pk_mul_f32 v[84:85], v[84:85], v[204:205]
	v_pk_mul_f32 v[86:87], v[86:87], v[204:205]
	v_lshlrev_b32_e32 v112, 16, v108
	v_and_b32_e32 v113, 0xffff0000, v108
	v_lshlrev_b32_e32 v114, 16, v109
	v_and_b32_e32 v115, 0xffff0000, v109
	v_lshlrev_b32_e32 v116, 16, v110
	v_and_b32_e32 v117, 0xffff0000, v110
	v_lshlrev_b32_e32 v118, 16, v111
	v_and_b32_e32 v119, 0xffff0000, v111
	v_pk_fma_f32 v[120:121], v[40:41], v[0:1], v[36:37]
	v_pk_fma_f32 v[122:123], v[42:43], v[2:3], v[38:39]
	v_pk_fma_f32 v[124:125], v[44:45], v[0:1], v[36:37]
	v_pk_fma_f32 v[126:127], v[46:47], v[2:3], v[38:39]
	v_pk_fma_f32 v[120:121], v[56:57], v[4:5], v[120:121]
	v_pk_fma_f32 v[122:123], v[58:59], v[6:7], v[122:123]
	v_pk_fma_f32 v[124:125], v[60:61], v[4:5], v[124:125]
	v_pk_fma_f32 v[126:127], v[62:63], v[6:7], v[126:127]
	v_pk_fma_f32 v[120:121], v[72:73], v[8:9], v[120:121]
	v_pk_fma_f32 v[122:123], v[74:75], v[10:11], v[122:123]
	v_pk_fma_f32 v[124:125], v[76:77], v[8:9], v[124:125]
	v_pk_fma_f32 v[126:127], v[78:79], v[10:11], v[126:127]
	v_pk_fma_f32 v[120:121], v[44:45], v[12:13], v[120:121]
	v_pk_fma_f32 v[122:123], v[46:47], v[14:15], v[122:123]
	v_pk_fma_f32 v[124:125], v[48:49], v[12:13], v[124:125]
	v_pk_fma_f32 v[126:127], v[50:51], v[14:15], v[126:127]
	v_pk_fma_f32 v[120:121], v[60:61], v[16:17], v[120:121]
	v_pk_fma_f32 v[122:123], v[62:63], v[18:19], v[122:123]
	v_pk_fma_f32 v[124:125], v[64:65], v[16:17], v[124:125]
	v_pk_fma_f32 v[126:127], v[66:67], v[18:19], v[126:127]
	v_pk_fma_f32 v[120:121], v[76:77], v[20:21], v[120:121]
	v_pk_fma_f32 v[122:123], v[78:79], v[22:23], v[122:123]
	v_pk_fma_f32 v[124:125], v[80:81], v[20:21], v[124:125]
	v_pk_fma_f32 v[126:127], v[82:83], v[22:23], v[126:127]
	v_pk_fma_f32 v[120:121], v[48:49], v[24:25], v[120:121]
	v_pk_fma_f32 v[122:123], v[50:51], v[26:27], v[122:123]
	v_pk_fma_f32 v[124:125], v[52:53], v[24:25], v[124:125]
	v_pk_fma_f32 v[126:127], v[54:55], v[26:27], v[126:127]
	v_pk_fma_f32 v[120:121], v[64:65], v[28:29], v[120:121]
	v_pk_fma_f32 v[122:123], v[66:67], v[30:31], v[122:123]
	v_pk_fma_f32 v[124:125], v[68:69], v[28:29], v[124:125]
	v_pk_fma_f32 v[126:127], v[70:71], v[30:31], v[126:127]
	v_pk_fma_f32 v[120:121], v[80:81], v[32:33], v[120:121]
	v_pk_fma_f32 v[122:123], v[82:83], v[34:35], v[122:123]
	v_pk_fma_f32 v[124:125], v[84:85], v[32:33], v[124:125]
	v_pk_fma_f32 v[126:127], v[86:87], v[34:35], v[126:127]
	v_and_b32_e32 v128, 0x7fffffff, v120
	v_and_b32_e32 v129, 0x7fffffff, v121
	v_and_b32_e32 v130, 0x7fffffff, v122
	v_and_b32_e32 v131, 0x7fffffff, v123
	v_and_b32_e32 v132, 0x7fffffff, v124
	v_and_b32_e32 v133, 0x7fffffff, v125
	v_and_b32_e32 v134, 0x7fffffff, v126
	v_and_b32_e32 v135, 0x7fffffff, v127
; __device__ __forceinline__ unsigned cvt_pk_bf16(float lo, float hi) { unsigned r; asm volatile("v_cvt_pk_bf16_f32 %0, %1, %2" : "=v"(r) : "v"(lo), "v"(hi)); return r; }
; __device__ __forceinline__ float gelu_as(float v) {
;   const float av = fabsf(v); const float t = __builtin_amdgcn_rcpf(av * 0.2316418882f + 1.0f);
;   float q = t * 0.5307027145f + (-0.7265760135f); q = q * t + 0.7107068705f; q = q * t + (-0.142248368f); q = q * t + 0.127414796f; q = q * t;
;   const float e = __builtin_amdgcn_exp2f((v * v) * (-0.72134752044f));
;   const float m = v * (q * e);
;   return v < 0.f ? m : v - m;
; }
; __device__ __forceinline__ void phase_conv(KP p, int l, int tid) {
;     ...
;           u32x2 ow; ow.x = cvt_pk_bf16(o[0], o[1]); ow.y = cvt_pk_bf16(o[2], o[3]);
;           *(u32x2*)(G + (size_t)((r0 + rr) * 64 + jb + q) * DFF + c0) = ow;
;         }
; #pragma unroll
;         for (int di = 0; di < RB + 2; ++di)
; #pragma unroll
;           for (int k = 0; k < 4; ++k) { win[0][di][k] = win[1][di][k]; win[1][di][k] = win[2][di][k]; }
;       }
;     }
;   }
; }
	v_pk_fma_f32 v[148:149], v[128:129], v[184:185], v[186:187]
	v_pk_fma_f32 v[150:151], v[130:131], v[184:185], v[186:187]
	v_pk_fma_f32 v[152:153], v[132:133], v[184:185], v[186:187]
	v_pk_fma_f32 v[154:155], v[134:135], v[184:185], v[186:187]
	v_rcp_f32_e32 v148, v148
	v_rcp_f32_e32 v149, v149
	v_rcp_f32_e32 v150, v150
	v_rcp_f32_e32 v151, v151
	v_rcp_f32_e32 v152, v152
	v_rcp_f32_e32 v153, v153
	v_rcp_f32_e32 v154, v154
	v_rcp_f32_e32 v155, v155
	v_pk_fma_f32 v[156:157], v[148:149], v[188:189], v[190:191]
	v_pk_fma_f32 v[158:159], v[150:151], v[188:189], v[190:191]
	v_pk_fma_f32 v[160:161], v[152:153], v[188:189], v[190:191]
	v_pk_fma_f32 v[162:163], v[154:155], v[188:189], v[190:191]
	v_pk_fma_f32 v[156:157], v[156:157], v[148:149], v[192:193]
	v_pk_fma_f32 v[158:159], v[158:159], v[150:151], v[192:193]
	v_pk_fma_f32 v[160:161], v[160:161], v[152:153], v[192:193]
	v_pk_fma_f32 v[162:163], v[162:163], v[154:155], v[192:193]
	v_pk_fma_f32 v[156:157], v[156:157], v[148:149], v[194:195]
	v_pk_fma_f32 v[158:159], v[158:159], v[150:151], v[194:195]
	v_pk_fma_f32 v[160:161], v[160:161], v[152:153], v[194:195]
	v_pk_fma_f32 v[162:163], v[162:163], v[154:155], v[194:195]
	v_pk_fma_f32 v[156:157], v[156:157], v[148:149], v[196:197]
	v_pk_fma_f32 v[158:159], v[158:159], v[150:151], v[196:197]
	v_pk_fma_f32 v[160:161], v[160:161], v[152:153], v[196:197]
	v_pk_fma_f32 v[162:163], v[162:163], v[154:155], v[196:197]
	v_pk_mul_f32 v[156:157], v[156:157], v[148:149]
	v_pk_mul_f32 v[158:159], v[158:159], v[150:151]
	v_pk_mul_f32 v[160:161], v[160:161], v[152:153]
	v_pk_mul_f32 v[162:163], v[162:163], v[154:155]
	v_pk_mul_f32 v[164:165], v[120:121], v[120:121]
	v_pk_mul_f32 v[166:167], v[122:123], v[122:123]
	v_pk_mul_f32 v[168:169], v[124:125], v[124:125]
	v_pk_mul_f32 v[170:171], v[126:127], v[126:127]
	v_pk_mul_f32 v[164:165], v[164:165], v[198:199]
	v_pk_mul_f32 v[166:167], v[166:167], v[198:199]
	v_pk_mul_f32 v[168:169], v[168:169], v[198:199]
	v_pk_mul_f32 v[170:171], v[170:171], v[198:199]
	v_exp_f32_e32 v164, v164
	v_exp_f32_e32 v165, v165
	v_exp_f32_e32 v166, v166
	v_exp_f32_e32 v167, v167
	v_exp_f32_e32 v168, v168
	v_exp_f32_e32 v169, v169
	v_exp_f32_e32 v170, v170
	v_exp_f32_e32 v171, v171
	v_pk_mul_f32 v[156:157], v[156:157], v[164:165]
	v_pk_mul_f32 v[158:159], v[158:159], v[166:167]
	v_pk_mul_f32 v[160:161], v[160:161], v[168:169]
	v_pk_mul_f32 v[162:163], v[162:163], v[170:171]
	v_pk_mul_f32 v[156:157], v[128:129], v[156:157]
	v_pk_mul_f32 v[158:159], v[130:131], v[158:159]
	v_pk_mul_f32 v[160:161], v[132:133], v[160:161]
	v_pk_mul_f32 v[162:163], v[134:135], v[162:163]
	v_max_f32_e32 v172, 0, v120
	v_max_f32_e32 v173, 0, v121
	v_max_f32_e32 v174, 0, v122
	v_max_f32_e32 v175, 0, v123
	v_max_f32_e32 v176, 0, v124
	v_max_f32_e32 v177, 0, v125
	v_max_f32_e32 v178, 0, v126
	v_max_f32_e32 v179, 0, v127
	v_pk_add_f32 v[172:173], v[172:173], v[156:157] neg_lo:[0,1] neg_hi:[0,1]
	v_pk_add_f32 v[174:175], v[174:175], v[158:159] neg_lo:[0,1] neg_hi:[0,1]
	v_pk_add_f32 v[176:177], v[176:177], v[160:161] neg_lo:[0,1] neg_hi:[0,1]
	v_pk_add_f32 v[178:179], v[178:179], v[162:163] neg_lo:[0,1] neg_hi:[0,1]
	v_pk_mul_f32 v[172:173], v[172:173], v[112:113]
	v_pk_mul_f32 v[174:175], v[174:175], v[114:115]
	v_pk_mul_f32 v[176:177], v[176:177], v[116:117]
	v_pk_mul_f32 v[178:179], v[178:179], v[118:119]
	v_cvt_pk_bf16_f32 v180, v172, v173
	v_cvt_pk_bf16_f32 v181, v174, v175
	v_cvt_pk_bf16_f32 v182, v176, v177
	v_cvt_pk_bf16_f32 v183, v178, v179
	global_store_dwordx2 v218, v[180:181], s[10:11]
	global_store_dwordx2 v219, v[182:183], s[10:11]
	v_add_u32_e32 v142, s73, v142
	s_mov_b32 s0, 0xaffff
	v_cmp_lt_i32_e32 vcc, s0, v142
	s_or_b64 s[28:29], vcc, s[28:29]
	s_andn2_b64 exec, exec, s[28:29]
	s_cbranch_execnz .Lcv_item
